# attn: padded bias table, Q loads hoisted; FB staging 16 loads in flight; ME epilogue gate loads batched; AD epilogue residual loads pipelined; MD cvt counted waits
# speedup vs baseline: 1.0093x; 1.0093x over previous
; __device__ __forceinline__ unsigned xb_ld(unsigned* p)              { return __hip_atomic_load(p, __ATOMIC_RELAXED, __HIP_MEMORY_SCOPE_AGENT); }
; __device__ __forceinline__ void xcd_barrier_complete(unsigned* bar, unsigned x, unsigned& nloc, unsigned& nx) {
;     const unsigned G = gridDim.x * gridDim.y * gridDim.z;
;     unsigned sum, cnt, mine, sp = 0u;
;     for (;;) {
;         sum = 0u; cnt = 0u; mine = 0u;
; #pragma unroll
;         for (unsigned j = 0; j < 16; ++j) { const unsigned c = xb_ld(&bar[XB_XCNT(j)]); sum += c; cnt += (c > 0u) ? 1u : 0u; mine = (j == x) ? c : mine; }
;         if (sum == G) break;
;         __builtin_amdgcn_s_sleep(1);
;         if ((++sp & 255u) == 0u) { if (xb_ld(&bar[XB_TMO])) break; if (sp > XB_SPIN_CAP) { atomicAdd(&bar[XB_TMO], 1u); break; } }
;     }
;     nloc = mine > 0u ? mine : 1u; nx = cnt > 0u ? cnt : 1u;
; }
; __device__ __forceinline__ void phase_ac(const Params& p, Frame& F, int l) {
;     ...
;     for (int U = F.vcu; U < NB * 64 * NKV; U += F.G) {
;         int b = U >> 8, n = (U >> 2) & 63, kvh = U & 3;
;         if (F.G == 256) { const int xg = F.vcu >> 5, lu = (F.vcu & 31) + ((U >= 256) ? 32 : 0); b = xg >> 2; n = 16 * (xg & 3) + (lu >> 2); kvh = lu & 3; }
.LBB0_173:
	s_waitcnt lgkmcnt(0)
	v_readlane_b32 s12, v251, 7
	s_cmpk_lt_i32 s12, 0x180
	s_cselect_b64 s[0:1], -1, 0
	v_writelane_b32 v251, s0, 16
	v_mov_b32_e32 v145, 0
	v_mov_b32_e32 v179, 1
	v_writelane_b32 v251, s1, 17
	s_ashr_i32 s0, s12, 31
	v_writelane_b32 v251, s0, 18
	s_lshr_b32 s0, s0, 29
	s_add_i32 s0, s12, s0
	s_ashr_i32 s6, s0, 3
	s_and_b32 s0, s0, -8
	v_readlane_b32 s17, v251, 6
	s_sub_i32 s8, s12, s0
	s_ashr_i32 s19, s17, 31
	s_cmpk_lg_i32 s17, 0x100
	s_cselect_b64 s[0:1], -1, 0
	v_writelane_b32 v251, s0, 19
	s_cmpk_gt_u32 s12, 0x7f
	v_mov_b32_e32 v241, 0xc1800000
	v_writelane_b32 v251, s1, 20
	s_cselect_b64 s[0:1], -1, 0
	s_lshl_b32 s4, s17, 2
	s_cmpk_eq_i32 s17, 0x100
	s_cselect_b64 s[14:15], -1, 0
	v_writelane_b32 v251, s4, 21
	s_and_b64 s[2:3], s[14:15], exec
	v_writelane_b32 v251, s14, 22
	s_cselect_b32 s20, s17, s4
	s_and_b64 s[0:1], s[0:1], s[14:15]
	v_writelane_b32 v251, s15, 23
	v_writelane_b32 v251, s0, 24
	s_mul_i32 s26, s20, 3
	v_mov_b32_e32 v240, 0x358637bd
	v_writelane_b32 v251, s1, 25
	v_mov_b64_e32 v[242:243], 0x180
	v_readlane_b32 s18, v251, 8
	s_lshl_b32 s1, s18, 3
	s_ashr_i32 s0, s18, 5
	s_and_b32 s2, s1, 0xf8
	s_mul_i32 s22, s0, 0xc00
	v_writelane_b32 v251, s1, 26
	s_add_i32 s1, s2, 0xffffff80
	v_writelane_b32 v251, s1, 27
	s_or_b32 s1, s22, 0x200
	s_cmpk_lt_i32 s18, 0x100
	v_writelane_b32 v251, s1, 28
	s_cselect_b64 s[4:5], -1, 0
	v_writelane_b32 v251, s4, 29
	s_cmp_lt_i32 s18, 64
	v_mov_b64_e32 v[244:245], 0x17f
	v_writelane_b32 v251, s5, 30
	s_cselect_b64 s[4:5], -1, 0
	v_writelane_b32 v251, s4, 31
	s_bfe_u32 s3, s18, 0x20002
	s_and_b32 s7, s18, 3
	v_writelane_b32 v251, s5, 32
	s_bfe_u32 s4, s18, 0x10004
	s_lshl_b32 s1, s4, 2
	s_lshl_b32 s5, s0, 3
	s_or_b32 s1, s1, s5
	s_or_b32 s1, s1, s3
	v_writelane_b32 v251, s1, 33
	s_ashr_i32 s1, s0, 31
	s_lshl_b64 s[14:15], s[0:1], 21
	v_writelane_b32 v251, s14, 34
	s_lshl_b32 s1, s3, 19
	v_mov_b32_e32 v238, 0xc00
	v_writelane_b32 v251, s15, 35
	v_writelane_b32 v251, s1, 36
	v_writelane_b32 v251, s7, 37
	s_lshl_b32 s1, s7, 9
	v_writelane_b32 v251, s1, 38
	s_lshl_b32 s1, s4, 17
	v_writelane_b32 v251, s1, 39
	s_ashr_i32 s1, s18, 31
	s_add_u32 s4, s46, 0x4200
	s_addc_u32 s5, s47, 0
	v_writelane_b32 v251, s4, 40
	v_mov_b64_e32 v[246:247], 0x100
	v_mov_b64_e32 v[248:249], 0xff
	v_writelane_b32 v251, s5, 41
	s_add_u32 s4, s46, 0x4400
	s_addc_u32 s5, s47, 0
	v_writelane_b32 v251, s4, 42
	v_mov_b32_e32 v250, 0x7f800000
	v_mov_b32_e32 v157, 0x10000
	v_writelane_b32 v251, s5, 43
	s_add_u32 s4, s46, 0x4500
	s_addc_u32 s5, s47, 0
	v_writelane_b32 v251, s4, 44
	v_mov_b64_e32 v[236:237], 0x7ff
	s_movk_i32 s59, 0x2000
	v_writelane_b32 v251, s5, 45
	s_add_u32 s4, s46, 0x4600
	s_addc_u32 s5, s47, 0
	v_writelane_b32 v251, s4, 46
	s_movk_i32 s61, 0x101
	s_mov_b32 s52, 0x3f803f80
	v_writelane_b32 v251, s5, 47
	s_add_u32 s4, s46, 0x4700
	s_addc_u32 s5, s47, 0
	v_writelane_b32 v251, s4, 48
	s_nop 1
	v_writelane_b32 v251, s5, 49
	s_add_u32 s4, s46, 0x4800
	s_addc_u32 s5, s47, 0
	v_writelane_b32 v251, s4, 50
	s_nop 1
	v_writelane_b32 v251, s5, 51
	s_add_u32 s4, s46, 0x4900
	s_addc_u32 s5, s47, 0
	v_writelane_b32 v251, s4, 52
	s_nop 1
	v_writelane_b32 v251, s5, 53
	s_add_u32 s4, s46, 0x4a00
	s_addc_u32 s5, s47, 0
	v_writelane_b32 v251, s4, 54
	s_nop 1
	v_writelane_b32 v251, s5, 55
	s_add_u32 s4, s46, 0x4b00
	s_addc_u32 s5, s47, 0
	v_writelane_b32 v251, s4, 56
	s_nop 1
	v_writelane_b32 v251, s5, 57
	s_add_u32 s4, s46, 0x4c00
	s_addc_u32 s5, s47, 0
	v_writelane_b32 v251, s4, 58
	s_nop 1
	v_writelane_b32 v251, s5, 59
	s_add_u32 s4, s46, 0x4d00
	s_addc_u32 s5, s47, 0
	v_writelane_b32 v251, s4, 60
	s_nop 1
	v_writelane_b32 v251, s5, 61
	s_add_u32 s4, s46, 0x4e00
	s_addc_u32 s5, s47, 0
	v_writelane_b32 v251, s4, 62
	s_nop 1
	v_writelane_b32 v251, s5, 63
	s_add_u32 s4, s46, 0x4f00
	s_addc_u32 s5, s47, 0
	v_writelane_b32 v252, s4, 0
	s_nop 1
	v_writelane_b32 v252, s5, 1
	s_add_u32 s4, s46, 0x5000
	s_addc_u32 s5, s47, 0
	v_writelane_b32 v252, s4, 2
	s_nop 1
	v_writelane_b32 v252, s5, 3
	s_add_u32 s4, s46, 0x5100
	s_addc_u32 s5, s47, 0
	v_writelane_b32 v252, s4, 4
	s_nop 1
	v_writelane_b32 v252, s5, 5
	s_add_u32 s4, s46, 0x5200
	s_addc_u32 s5, s47, 0
	v_writelane_b32 v252, s4, 6
	s_nop 1
	v_writelane_b32 v252, s5, 7
	s_add_u32 s4, s46, 0x5300
	s_addc_u32 s5, s47, 0
	v_writelane_b32 v252, s4, 8
	s_cmp_eq_u32 s33, 15
	s_nop 0
	v_writelane_b32 v252, s5, 9
	s_cselect_b64 s[4:5], -1, 0
	v_writelane_b32 v252, s4, 10
	s_cmp_eq_u32 s33, 14
	s_nop 0
	v_writelane_b32 v252, s5, 11
	s_cselect_b64 s[4:5], -1, 0
	v_writelane_b32 v252, s4, 12
	s_cmp_eq_u32 s33, 13
	s_nop 0
	v_writelane_b32 v252, s5, 13
	s_cselect_b64 s[4:5], -1, 0
	v_writelane_b32 v252, s4, 14
	s_cmp_eq_u32 s33, 12
	s_nop 0
	v_writelane_b32 v252, s5, 15
	s_cselect_b64 s[4:5], -1, 0
	v_writelane_b32 v252, s4, 16
	s_cmp_eq_u32 s33, 11
	s_nop 0
	v_writelane_b32 v252, s5, 17
	s_cselect_b64 s[4:5], -1, 0
	v_writelane_b32 v252, s4, 18
	s_cmp_eq_u32 s33, 10
	s_nop 0
	v_writelane_b32 v252, s5, 19
	s_cselect_b64 s[4:5], -1, 0
	v_writelane_b32 v252, s4, 20
	s_cmp_eq_u32 s33, 9
	s_nop 0
	v_writelane_b32 v252, s5, 21
	s_cselect_b64 s[4:5], -1, 0
	v_writelane_b32 v252, s4, 22
	s_cmp_eq_u32 s33, 8
	s_nop 0
	v_writelane_b32 v252, s5, 23
	s_cselect_b64 s[4:5], -1, 0
	v_writelane_b32 v252, s4, 24
	s_cmp_eq_u32 s33, 7
	s_nop 0
	v_writelane_b32 v252, s5, 25
	s_cselect_b64 s[4:5], -1, 0
	v_writelane_b32 v252, s4, 26
	s_cmp_eq_u32 s33, 6
	s_nop 0
	v_writelane_b32 v252, s5, 27
	s_cselect_b64 s[4:5], -1, 0
	v_writelane_b32 v252, s4, 28
	s_cmp_eq_u32 s33, 5
	s_nop 0
	v_writelane_b32 v252, s5, 29
	s_cselect_b64 s[4:5], -1, 0
	v_writelane_b32 v252, s4, 30
	s_cmp_eq_u32 s33, 4
; __device__ __forceinline__ unsigned xb_ld(unsigned* p)              { return __hip_atomic_load(p, __ATOMIC_RELAXED, __HIP_MEMORY_SCOPE_AGENT); }
; __device__ __forceinline__ unsigned xb_add(unsigned* p, unsigned v) { return __hip_atomic_fetch_add(p, v, __ATOMIC_RELAXED, __HIP_MEMORY_SCOPE_AGENT); }
; #define XB_SPIN(cond, bar) do { unsigned _sp = 0; while (cond) { __builtin_amdgcn_s_sleep(1); \
;     if ((++_sp & 255u) == 0u) { if (xb_ld(&(bar)[XB_TMO])) break; if (_sp > XB_SPIN_CAP) { atomicAdd(&(bar)[XB_TMO], 1u); break; } } } } while (0)
; __device__ __forceinline__ bool tile_of(int i, int G, int c, int nM, int nN, int wgm, int& tm, int& tn) {
;     const int nwg = nM * nN; const long L = (long)i * G + c; if (L >= nwg) return false;
;     int wgid = (int)L; { const int q = nwg / NXCD, r = nwg % NXCD, xcd = wgid % NXCD, off = wgid / NXCD; wgid = (xcd < r ? xcd * (q + 1) : r * (q + 1) + (xcd - r) * q) + off; }
;     const int nig = wgm * nN, gid = wgid / nig, fm = gid * wgm, gsz = (nM - fm) < wgm ? (nM - fm) : wgm;
;     tm = fm + ((wgid % nig) % gsz); tn = (wgid % nig) / gsz; return true;
; }
; __device__ __forceinline__ void xcd_barrier(const XcdBarrier& b, const bool local = false) {
;     ...
;         const unsigned old = xb_add(&bar[XB_XSUB(b.x)], 1u);
;         const unsigned gen = old / nloc;
;         if (old + 1u == (gen + 1u) * nloc) {
;             if (!local) {
;             __builtin_amdgcn_fence(__ATOMIC_RELEASE, "agent");
;             asm volatile("s_waitcnt vmcnt(0)" ::: "memory");
;             const unsigned og = xb_add(&bar[XB_TOP], 1u);
;             const unsigned tg = og / nx;
;             if (og + 1u == (tg + 1u) * nx) xb_add(&bar[XB_TOPGEN], 1u);
;             else XB_SPIN(xb_ld(&bar[XB_TOPGEN]) == tg, bar);
;             }
;             __builtin_amdgcn_fence(__ATOMIC_ACQUIRE, "agent");
;             xb_add(&bar[XB_XGEN(b.x)], 1u);
;             asm volatile("s_waitcnt vmcnt(0)" ::: "memory");
;         } else {
;             XB_SPIN(xb_ld(&bar[XB_XGEN(b.x)]) == gen, bar);
	s_nop 0
	v_writelane_b32 v252, s5, 31
	s_cselect_b64 s[4:5], -1, 0
	v_writelane_b32 v252, s4, 32
	s_cmp_eq_u32 s33, 3
	s_nop 0
	v_writelane_b32 v252, s5, 33
	s_cselect_b64 s[4:5], -1, 0
	v_writelane_b32 v252, s4, 34
	s_cmp_eq_u32 s33, 2
	s_nop 0
	v_writelane_b32 v252, s5, 35
	s_cselect_b64 s[4:5], -1, 0
	v_writelane_b32 v252, s4, 36
	s_cmp_eq_u32 s33, 1
	s_nop 0
	v_writelane_b32 v252, s5, 37
	s_cselect_b64 s[4:5], -1, 0
	v_writelane_b32 v252, s4, 38
	s_cmp_eq_u32 s33, 0
	s_nop 0
	v_writelane_b32 v252, s5, 39
	s_cselect_b64 s[4:5], -1, 0
	s_lshl_b32 s3, s33, 8
	v_writelane_b32 v252, s4, 40
	s_add_u32 s3, s10, s3
	s_nop 0
	v_writelane_b32 v252, s5, 41
	s_addc_u32 s4, s11, 0
	s_add_u32 s10, s3, 0x1400
	s_addc_u32 s11, s4, 0
	v_writelane_b32 v252, s10, 42
	s_nop 1
	v_writelane_b32 v252, s11, 43
	s_add_u32 s10, s3, 0x2400
	s_addc_u32 s11, s4, 0
	v_writelane_b32 v252, s10, 44
	s_add_u32 s4, s46, 0x7400
	s_addc_u32 s5, s47, 0
	v_writelane_b32 v252, s11, 45
	v_writelane_b32 v252, s4, 46
	s_nop 1
	v_writelane_b32 v252, s5, 47
	s_add_u32 s4, s46, 0x7500
	s_addc_u32 s5, s47, 0
	v_writelane_b32 v252, s4, 48
	s_cmpk_lt_i32 s18, 0x200
	s_mov_b32 s46, 0xbfb8aa3b
	v_writelane_b32 v252, s5, 49
	s_cselect_b64 s[4:5], -1, 0
	v_writelane_b32 v252, s4, 50
	s_lshr_b32 s3, s18, 1
	s_and_b32 s3, s3, 48
	v_writelane_b32 v252, s5, 51
	v_writelane_b32 v252, s3, 52
	s_and_b32 s3, s18, 28
	v_writelane_b32 v252, s3, 53
	s_ashr_i32 s3, s18, 7
	s_cmpk_lt_i32 s12, 0x100
	v_writelane_b32 v252, s3, 54
	s_cselect_b64 s[4:5], -1, 0
	s_lshl_b32 s24, s20, 1
	v_writelane_b32 v252, s4, 55
	s_ashr_i32 s21, s20, 31
	s_ashr_i32 s25, s24, 31
	s_ashr_i32 s27, s26, 31
	s_lshl_b32 s10, s8, 5
	s_lshl_b32 s3, s20, 3
	s_lshl_b32 s28, s17, 3
	s_lshl_b32 s30, s20, 2
	v_writelane_b32 v252, s5, 56
	s_cmpk_lt_i32 s17, 0x100
	v_writelane_b32 v252, s3, 57
	s_cselect_b64 s[4:5], -1, 0
	v_writelane_b32 v252, s4, 58
	s_nop 1
	v_writelane_b32 v252, s5, 59
	s_and_b64 s[4:5], s[4:5], exec
	s_cselect_b32 s3, 0, 3
	v_writelane_b32 v252, s3, 60
	s_movk_i32 s3, 0x400
	s_cselect_b32 s3, s3, 0x80
	s_cselect_b32 s23, 1, 8
	v_writelane_b32 v252, s3, 61
	s_cselect_b32 s3, 10, 7
	v_writelane_b32 v252, s3, 62
	s_lshl_b32 s3, s23, 5
	s_cmp_lt_i32 s18, s3
	s_cselect_b64 s[4:5], -1, 0
	v_writelane_b32 v252, s3, 63
	v_writelane_b32 v253, s4, 0
	s_add_i32 s3, s23, -1
	s_ashr_i32 s7, s17, 3
	v_writelane_b32 v253, s5, 1
	s_and_b32 s4, s3, 1
	v_writelane_b32 v253, s4, 2
	s_and_b32 s4, s3, 2
	v_writelane_b32 v253, s4, 3
	s_and_b32 s4, s3, 3
	v_writelane_b32 v253, s4, 4
	s_and_b32 s4, s3, 4
	v_writelane_b32 v253, s4, 5
	s_and_b32 s4, s3, 5
	v_writelane_b32 v253, s4, 6
	s_and_b32 s4, s3, 6
	v_writelane_b32 v253, s4, 7
	s_and_b32 s4, s3, 9
	v_writelane_b32 v253, s4, 8
	s_and_b32 s4, s3, 10
	v_writelane_b32 v253, s4, 9
	s_and_b32 s4, s3, 11
	v_writelane_b32 v253, s4, 10
	s_and_b32 s4, s3, 12
	v_writelane_b32 v253, s4, 11
	s_and_b32 s4, s3, 13
	v_writelane_b32 v253, s4, 12
	v_writelane_b32 v253, s3, 13
	s_and_b32 s3, s3, 14
	v_writelane_b32 v253, s3, 14
	s_and_b32 s3, s17, -8
	s_add_i32 s9, s17, 0x7ff
	v_writelane_b32 v253, s3, 15
	s_lshl_b32 s3, s3, 1
	s_cmpk_lt_i32 s12, 0x200
	v_writelane_b32 v253, s3, 16
	s_cselect_b64 s[4:5], -1, 0
	s_lshr_b32 s3, s8, 31
	s_or_b32 s3, s3, 64
	s_mul_i32 s3, s3, s8
	v_writelane_b32 v253, s4, 17
	s_add_i32 s3, s3, s6
	s_nop 0
	v_writelane_b32 v253, s5, 18
	s_ashr_i32 s4, s3, 31
	s_lshr_b32 s4, s4, 28
	s_add_i32 s5, s3, s4
	s_and_b32 s4, s5, -16
	s_sub_i32 s4, s3, s4
	s_ashr_i32 s3, s5, 4
	s_lshl_b32 s3, s3, 2
	s_sub_i32 s5, 0x80, s3
	s_min_i32 s5, s5, 4
	s_cmp_lt_i32 s8, 0
	s_cselect_b32 s11, 49, 48
	s_mul_i32 s11, s8, s11
	s_mul_i32 s8, s8, 33
	s_cselect_b32 s8, s8, s10
	s_add_i32 s11, s11, s6
	s_mul_hi_i32 s10, s11, 0x2aaaaaab
	s_lshr_b32 s12, s10, 31
	s_ashr_i32 s10, s10, 3
	s_add_i32 s10, s10, s12
	s_mul_i32 s12, s10, 48
	s_sub_i32 s11, s11, s12
	s_bfe_i32 s12, s11, 0x80000
	s_bfe_u32 s12, s12, 0x3000c
	s_add_i32 s12, s11, s12
	s_add_i32 s6, s8, s6
	s_and_b32 s13, s12, 0xf8
	s_ashr_i32 s8, s6, 31
	s_sub_i32 s11, s11, s13
	s_lshr_b32 s13, s8, 27
	s_add_i32 s13, s6, s13
	s_and_b32 s14, s13, 0xffe0
	s_sub_i32 s14, s6, s14
	s_bfe_i32 s15, s14, 0x80000
	s_bfe_u32 s15, s15, 0x3000c
	s_add_i32 s15, s14, s15
	s_lshr_b32 s8, s8, 26
	s_and_b32 s16, s15, 0xf8
	s_add_i32 s8, s6, s8
	s_sub_i32 s14, s14, s16
	s_and_b32 s16, s8, 0xffffffc0
	s_sub_i32 s16, s6, s16
	s_lshl_b32 s6, s10, 3
	s_bfe_i32 s10, s12, 0x80000
	s_sext_i32_i16 s10, s10
	s_sext_i32_i8 s11, s11
	s_add_i32 s36, s6, s11
	s_ashr_i32 s6, s10, 3
	v_writelane_b32 v253, s6, 19
	s_lshr_b32 s6, s10, 3
	s_bfe_i64 s[10:11], s[6:7], 0x100000
	s_lshl_b64 s[10:11], s[10:11], 19
	v_writelane_b32 v253, s10, 20
	s_ashr_i32 s6, s13, 5
	s_lshl_b32 s6, s6, 3
	v_writelane_b32 v253, s11, 21
	s_bfe_i32 s10, s15, 0x80000
	s_sext_i32_i16 s10, s10
	s_sext_i32_i8 s11, s14
	s_add_i32 s12, s6, s11
	s_ashr_i32 s6, s10, 3
	v_writelane_b32 v253, s6, 22
	s_lshr_b32 s6, s10, 3
	s_bfe_i64 s[10:11], s[6:7], 0x100000
	s_ashr_i32 s6, s8, 6
	s_bfe_i32 s8, s16, 0x80000
	s_lshl_b64 s[10:11], s[10:11], 19
	s_bfe_u32 s8, s8, 0x3000c
	v_writelane_b32 v253, s10, 23
	s_add_i32 s8, s16, s8
	s_lshl_b32 s6, s6, 3
	v_writelane_b32 v253, s11, 24
	s_bfe_i32 s10, s8, 0x80000
	s_and_b32 s8, s8, 0xf8
	s_sub_i32 s8, s16, s8
	s_sext_i32_i16 s10, s10
	s_sext_i32_i8 s8, s8
	s_add_i32 s14, s6, s8
	s_ashr_i32 s6, s10, 3
	v_writelane_b32 v253, s6, 25
	s_mov_b32 s8, s36
	s_ashr_i32 s37, s36, 31
	v_writelane_b32 v253, s8, 26
	s_lshr_b32 s6, s10, 3
	s_lshl_b64 s[10:11], s[36:37], 19
	v_writelane_b32 v253, s9, 27
	v_writelane_b32 v253, s10, 28
	s_mov_b32 s8, s12
	s_ashr_i32 s13, s12, 31
; #define RELAUNDER() do { int w_ = wave0; asm volatile("" : "+s"(w_)); F.wave = w_; F.lane = pg8::lane_id_asm(); F.tid = F.wave * 64 + F.lane; } while (0)
; __device__ __forceinline__ bool tile_of(int i, int G, int c, int nM, int nN, int wgm, int& tm, int& tn) {
;     const int nwg = nM * nN; const long L = (long)i * G + c; if (L >= nwg) return false;
;     int wgid = (int)L; { const int q = nwg / NXCD, r = nwg % NXCD, xcd = wgid % NXCD, off = wgid / NXCD; wgid = (xcd < r ? xcd * (q + 1) : r * (q + 1) + (xcd - r) * q) + off; }
;     const int nig = wgm * nN, gid = wgid / nig, fm = gid * wgm, gsz = (nM - fm) < wgm ? (nM - fm) : wgm;
;     tm = fm + ((wgid % nig) % gsz); tn = (wgid % nig) / gsz; return true;
; }
; __global__ void __launch_bounds__(NTHR, 2) mk_fwd(Params p) {
;     ...
;             const int nxg = F.G >> 3, xslot = F.vcu / nxg; const int nper = (2048 + F.G - 1) / F.G, rsplit = (l + 1 < DEPTH) ? (7 - xslot) * nper / 8 : nper;
;     ...
;             if (MD_SKEW_TICKS) { const unsigned long long t0 = __builtin_amdgcn_s_memrealtime(), dl = (unsigned long long)((F.vcu & 3) * MD_SKEW_TICKS);
;                 while (__builtin_amdgcn_s_memrealtime() - t0 < dl) __builtin_amdgcn_s_sleep(8); }
; #pragma unroll 1
;             for (int part = 0; part < 2; ++part) {
;                 pg8::SchedMoE Sc{(const char*)(q.ws + WS_XIN), (const char*)(q.ws + WS_W1 + (size_t)l * NE * 4096 * 1024 * 2), (size_t)256 * 1024 * 2, (size_t)256 * 1024 * 2, 16, F.G, (int)blockIdx.x, part ? rsplit : 0, part ? nper - rsplit : rsplit, (PROBE_SAMETILE && rep_ == 1) ? 1 : 0};
;                 pg8::EpiSwiGLU E{(bf16*)(q.ws + WS_ACT), 2048, (PROBE_NOEPI && rep_ == 1) ? 1 : 0};
;                 pg8::gemm_phase<pg8::EpiSwiGLU, pg8::SchedMoE, 1024, 1024, 1024>(F.lds, Sc, E, F.wave);
;                 if (part == 0 && l + 1 < DEPTH && rep_ == 0) { RELAUNDER();
;                     const unsigned long long* pt = (const unsigned long long*)(q.ws + WS_PAR + 512 * 1024);
;                     q.in[IN_WG] = (const float*)pt[0]; q.in[IN_WU] = (const float*)pt[1]; q.in[IN_WD] = (const float*)pt[2];
;                     const int nslotw = nxg * NWAVES, per = 3 * 8192 / 8;
;                     const int pre = (F.G == 256 && l + 1 >= 2) ? CVT_PRE : 0;
;                     cvt_moe_layer(q, F, l + 1, xslot * per + pre + (F.vcu - xslot * nxg) * NWAVES + F.wave, nslotw, (xslot + 1) * per); __syncthreads(); }
	v_writelane_b32 v253, s11, 29
	v_writelane_b32 v253, s8, 30
	s_lshl_b64 s[10:11], s[12:13], 19
	s_ashr_i32 s15, s14, 31
	v_writelane_b32 v253, s9, 31
	v_writelane_b32 v253, s10, 32
	s_mov_b32 s8, s14
	s_nop 0
	v_writelane_b32 v253, s11, 33
	v_writelane_b32 v253, s8, 34
	s_lshl_b64 s[10:11], s[14:15], 20
	s_cmp_gt_i32 s16, 31
	v_writelane_b32 v253, s9, 35
	v_writelane_b32 v253, s10, 36
	s_cselect_b32 s8, 0x800, 0
	s_nop 0
	v_writelane_b32 v253, s11, 37
	v_writelane_b32 v253, s8, 38
	s_abs_i32 s8, s28
	v_cvt_f32_u32_e32 v0, s8
	v_writelane_b32 v253, s8, 39
	s_sub_i32 s8, 0, s8
	v_rcp_iflag_f32_e32 v0, v0
	s_nop 0
	v_mul_f32_e32 v0, 0x4f7ffffe, v0
	v_cvt_u32_f32_e32 v0, v0
	s_nop 0
	v_readfirstlane_b32 s10, v0
	v_cvt_f32_ubyte0_e32 v0, s23
	v_rcp_iflag_f32_e32 v0, v0
	s_mul_i32 s8, s8, s10
	s_mul_hi_u32 s8, s10, s8
	s_add_i32 s8, s10, s8
	v_mul_f32_e32 v0, 0x4f7ffffe, v0
	v_cvt_u32_f32_e32 v0, v0
	v_writelane_b32 v253, s8, 40
	s_sub_i32 s8, 0, s23
	v_writelane_b32 v253, s23, 41
	v_readfirstlane_b32 s10, v0
	s_mul_i32 s8, s8, s10
	s_mul_hi_u32 s8, s10, s8
	s_add_i32 s8, s10, s8
	v_writelane_b32 v253, s8, 42
	s_abs_i32 s8, s7
	v_cvt_f32_u32_e32 v0, s8
	s_sub_i32 s10, 0, s8
	v_rcp_iflag_f32_e32 v0, v0
	s_nop 0
	v_mul_f32_e32 v0, 0x4f7ffffe, v0
	v_cvt_u32_f32_e32 v0, v0
	s_nop 0
	v_readfirstlane_b32 s11, v0
	s_mul_i32 s10, s10, s11
	s_mul_hi_u32 s10, s11, s10
	s_add_i32 s11, s11, s10
	s_abs_i32 s10, s18
	s_mul_hi_u32 s12, s10, s11
	s_mul_i32 s11, s12, s8
	s_sub_i32 s13, s10, s11
	s_bfe_i64 s[10:11], s[6:7], 0x100000
	s_lshl_b64 s[10:11], s[10:11], 19
	v_writelane_b32 v253, s10, 43
	s_xor_b32 s6, s18, s7
	s_ashr_i32 s6, s6, 31
	v_writelane_b32 v253, s11, 44
	s_bfe_i32 s10, s17, 0x1001c
	v_writelane_b32 v253, s10, 45
	s_add_i32 s10, s12, 1
	s_sub_i32 s11, s13, s8
	s_cmp_ge_u32 s13, s8
	s_cselect_b32 s10, s10, s12
	s_cselect_b32 s11, s11, s13
	s_add_i32 s12, s10, 1
	s_cmp_ge_u32 s11, s8
	s_cselect_b32 s8, s12, s10
	s_abs_i32 s10, s17
	v_cvt_f32_u32_e32 v0, s10
	s_sub_i32 s11, 0, s10
	s_xor_b32 s8, s8, s6
	v_rcp_iflag_f32_e32 v0, v0
	s_nop 0
	v_mul_f32_e32 v0, 0x4f7ffffe, v0
	v_cvt_u32_f32_e32 v0, v0
	s_nop 0
	v_readfirstlane_b32 s12, v0
	s_mul_i32 s11, s11, s12
	s_mul_hi_u32 s11, s12, s11
	s_add_i32 s12, s12, s11
	s_abs_i32 s11, s9
	s_mul_hi_u32 s12, s11, s12
	s_mul_i32 s13, s12, s10
	s_sub_i32 s11, s11, s13
	s_xor_b32 s9, s9, s17
	s_ashr_i32 s9, s9, 31
	s_sub_i32 s13, s8, s6
	s_add_i32 s14, s12, 1
	s_sub_i32 s15, s11, s10
	s_cmp_ge_u32 s11, s10
	s_cselect_b32 s12, s14, s12
	s_cselect_b32 s11, s15, s11
	s_add_i32 s14, s12, 1
	s_cmp_ge_u32 s11, s10
	s_cselect_b32 s10, s14, s12
	s_xor_b32 s10, s10, s9
	s_sub_i32 s10, s10, s9
	s_sub_i32 s9, 7, s13
	s_mul_i32 s9, s9, s10
	v_writelane_b32 v253, s10, 46
	s_ashr_i32 s10, s9, 31
	s_lshr_b32 s10, s10, 29
	s_add_i32 s9, s9, s10
	s_abs_i32 s10, s5
	v_cvt_f32_u32_e32 v0, s10
	s_sub_i32 s11, 0, s10
	s_ashr_i32 s9, s9, 3
	s_mul_i32 s7, s13, s7
	v_rcp_iflag_f32_e32 v0, v0
	v_writelane_b32 v253, s9, 47
	s_sub_i32 s9, s18, s7
	s_lshl_b32 s9, s9, 3
	v_mul_f32_e32 v0, 0x4f7ffffe, v0
	v_cvt_u32_f32_e32 v0, v0
	s_mulk_i32 s13, 0xc00
	v_writelane_b32 v253, s9, 48
	s_xor_b32 s9, s4, s5
	v_readfirstlane_b32 s12, v0
	s_mul_i32 s11, s11, s12
	s_mul_hi_u32 s11, s12, s11
	s_add_i32 s12, s12, s11
	s_abs_i32 s11, s4
	s_mul_hi_u32 s12, s11, s12
	s_mul_i32 s14, s12, s10
	s_sub_i32 s11, s11, s14
	s_ashr_i32 s9, s9, 31
	v_writelane_b32 v253, s13, 49
	s_add_i32 s33, s13, 0xc00
	s_add_i32 s13, s12, 1
	s_sub_i32 s14, s11, s10
	s_cmp_ge_u32 s11, s10
	s_cselect_b32 s12, s13, s12
	s_cselect_b32 s11, s14, s11
	s_add_i32 s13, s12, 1
	s_cmp_ge_u32 s11, s10
	s_cselect_b32 s10, s13, s12
	s_xor_b32 s10, s10, s9
	s_sub_i32 s11, s10, s9
	s_mul_i32 s5, s11, s5
	s_and_b32 s9, s18, 31
	s_sub_i32 s4, s4, s5
	s_mul_i32 s5, s0, 0x30000
	s_lshl_b32 s10, s9, 9
	s_or_b32 s5, s5, s10
; #define RELAUNDER() do { int w_ = wave0; asm volatile("" : "+s"(w_)); F.wave = w_; F.lane = pg8::lane_id_asm(); F.tid = F.wave * 64 + F.lane; } while (0)
; __global__ void __launch_bounds__(NTHR, 2) mk_fwd(Params p) {
;     ...
;                 pg8::SchedMoE Sc{(const char*)(q.ws + WS_XIN), (const char*)(q.ws + WS_W1 + (size_t)l * NE * 4096 * 1024 * 2), (size_t)256 * 1024 * 2, (size_t)256 * 1024 * 2, 16, F.G, (int)blockIdx.x, part ? rsplit : 0, part ? nper - rsplit : rsplit, (PROBE_SAMETILE && rep_ == 1) ? 1 : 0};
;                 pg8::EpiSwiGLU E{(bf16*)(q.ws + WS_ACT), 2048, (PROBE_NOEPI && rep_ == 1) ? 1 : 0};
;                 pg8::gemm_phase<pg8::EpiSwiGLU, pg8::SchedMoE, 1024, 1024, 1024>(F.lds, Sc, E, F.wave);
;                 if (part == 0 && l + 1 < DEPTH && rep_ == 0) { RELAUNDER();
;                     const unsigned long long* pt = (const unsigned long long*)(q.ws + WS_PAR + 512 * 1024);
;                     q.in[IN_WG] = (const float*)pt[0]; q.in[IN_WU] = (const float*)pt[1]; q.in[IN_WD] = (const float*)pt[2];
;                     const int nslotw = nxg * NWAVES, per = 3 * 8192 / 8;
;                     const int pre = (F.G == 256 && l + 1 >= 2) ? CVT_PRE : 0;
;                     cvt_moe_layer(q, F, l + 1, xslot * per + pre + (F.vcu - xslot * nxg) * NWAVES + F.wave, nslotw, (xslot + 1) * per); __syncthreads(); }
	v_writelane_b32 v253, s5, 50
	s_mul_i32 s5, s0, 0x1800
	s_lshl_b32 s10, s9, 4
	s_or_b32 s5, s5, s10
	v_writelane_b32 v253, s5, 51
	s_mulk_i32 s0, 0x3000
	s_lshl_b32 s5, s9, 5
	s_or_b32 s0, s0, s5
	v_writelane_b32 v253, s0, 52
	s_add_i32 s0, s4, s3
	s_and_b32 s3, s4, 3
	s_ashr_i32 s4, s0, 3
	s_lshl_b32 s0, s0, 2
	s_and_b32 s0, s0, 16
	s_add_i32 s0, s0, s4
	s_lshl_b32 s0, s0, 2
	s_or_b32 s12, s0, s3
	s_lshl_b32 s0, s4, 2
	s_add_i32 s4, s0, s11
	s_ashr_i32 s5, s4, 31
	v_writelane_b32 v253, s11, 53
	s_lshl_b64 s[4:5], s[4:5], 20
	v_writelane_b32 v253, s4, 54
	s_or_b32 s0, s22, s2
	s_addk_i32 s0, 0x80
	v_writelane_b32 v253, s5, 55
	v_writelane_b32 v253, s22, 56
	v_writelane_b32 v253, s0, 57
	s_mov_b32 s0, s12
	s_ashr_i32 s13, s12, 31
	v_writelane_b32 v253, s0, 58
	s_lshl_b64 s[2:3], s[12:13], 20
	s_nop 0
	v_writelane_b32 v253, s1, 59
	v_writelane_b32 v253, s2, 60
	s_add_u32 s0, s18, s17
	s_addc_u32 s1, s1, s19
	v_writelane_b32 v253, s3, 61
	v_writelane_b32 v253, s19, 62
	v_writelane_b32 v253, s0, 63
	s_ashr_i32 s29, s28, 31
	s_ashr_i32 s31, s30, 31
	v_writelane_b32 v254, s1, 0
	s_mul_i32 s0, s8, 0x1800
	s_lshl_b32 s1, s18, 4
	s_add_i32 s0, s0, s1
	s_lshl_b32 s1, s7, 4
	s_sub_i32 s0, s0, s1
	s_mul_i32 s1, s6, 0x1800
	s_sub_i32 s0, s0, s1
	v_writelane_b32 v254, s0, 1
	s_mul_i32 s0, s8, 0x3000
	s_lshl_b32 s1, s18, 5
	s_add_i32 s0, s0, s1
	s_lshl_b32 s1, s7, 5
	s_sub_i32 s0, s0, s1
	s_mul_i32 s1, s6, 0x3000
	s_sub_i32 s0, s0, s1
	s_lshr_b32 s1, s17, 3
	v_writelane_b32 v254, s0, 2
	s_mul_i32 s0, s8, 0x30000
	s_lshl_b32 s2, s1, 9
	s_lshl_b32 s3, s1, 10
	s_add_i32 s2, s0, s2
	v_writelane_b32 v254, s3, 3
	s_add_i32 s0, s0, s3
	s_lshl_b32 s3, s7, 9
	s_sub_i32 s0, s0, s3
	s_mul_i32 s6, s6, 0x30000
	s_sub_i32 s2, s2, s3
	s_sub_i32 s0, s0, s6
	v_writelane_b32 v254, s0, 4
	s_sub_i32 s0, s2, s6
	v_writelane_b32 v254, s0, 5
	s_lshl_b32 s0, s20, 7
	s_sub_i32 s0, 0, s0
	v_writelane_b32 v254, s0, 6
	s_lshl_b32 s0, s20, 8
	s_sub_i32 s0, 0, s0
	v_writelane_b32 v254, s0, 7
	s_lshl_b32 s0, s1, 5
	v_writelane_b32 v254, s0, 8
	s_lshl_b32 s0, s1, 6
	v_writelane_b32 v254, s0, 9
	s_lshl_b32 s0, s18, 13
	v_writelane_b32 v254, s0, 10
	s_lshl_b32 s0, s17, 13
	v_writelane_b32 v254, s0, 11
	s_lshl_b32 s0, s20, 9
	v_writelane_b32 v254, s0, 12
	s_sub_i32 s0, 0, s20
	v_writelane_b32 v254, s0, 13
	s_sub_i32 s0, 0, s24
	v_writelane_b32 v254, s0, 14
	s_lshl_b32 s0, s18, 9
	v_writelane_b32 v254, s0, 15
	s_add_i32 s0, 0, 0x20820
	v_writelane_b32 v254, s0, 16
	s_add_i32 s0, 0, 0x20824
	v_writelane_b32 v254, s0, 17
	s_add_i32 s0, 0, 0xf660
	v_writelane_b32 v254, s0, 18
	s_add_i32 s0, 0, 0x1c800
	v_writelane_b32 v254, s0, 19
	s_add_i32 s0, 0, 0x20828
	v_writelane_b32 v254, s0, 20
	s_add_i32 s0, 0, 0x2100
	v_writelane_b32 v254, s0, 21
	s_mov_b32 s1, 0
	s_mov_b32 s0, s28
	v_writelane_b32 v254, s0, 22
	s_lshl_b64 s[2:3], s[28:29], 2
	s_nop 0
	v_writelane_b32 v254, s1, 23
	v_writelane_b32 v254, s2, 24
	s_mov_b32 s0, s30
	s_nop 0
	v_writelane_b32 v254, s3, 25
	v_writelane_b32 v254, s0, 26
	s_lshl_b64 s[2:3], s[30:31], 2
	s_mov_b64 s[30:31], 0x80
	v_writelane_b32 v254, s1, 27
	v_writelane_b32 v254, s2, 28
	s_mov_b32 s0, s20
	s_nop 0
	v_writelane_b32 v254, s3, 29
	v_writelane_b32 v254, s0, 30
	s_lshl_b64 s[2:3], s[20:21], 2
	s_nop 0
	v_writelane_b32 v254, s1, 31
	v_writelane_b32 v254, s2, 32
	s_mov_b32 s0, s24
	s_nop 0
	v_writelane_b32 v254, s3, 33
	v_writelane_b32 v254, s0, 34
	s_lshl_b64 s[2:3], s[24:25], 2
	s_nop 0
	v_writelane_b32 v254, s1, 35
	v_writelane_b32 v254, s2, 36
	s_mov_b32 s0, s26
	s_nop 0
	v_writelane_b32 v254, s3, 37
	v_writelane_b32 v254, s0, 38
	s_lshl_b64 s[2:3], s[26:27], 2
	s_nop 0
	v_writelane_b32 v254, s1, 39
	v_writelane_b32 v254, s2, 40
	s_nop 1
	v_writelane_b32 v254, s3, 41
	s_mov_b64 s[2:3], 0x2410000
	v_writelane_b32 v254, s2, 42
	s_nop 1
	v_writelane_b32 v254, s3, 43
	s_branch .LBB0_177

; __device__ __forceinline__ void phase_ac(const Params& p, Frame& F, int l) {
;     ...
;     LAS unsigned char* Kimg = F.lds + AT_KOFF; LAS unsigned char* Vimg = F.lds + AT_VOFF; LAS float* btab = (LAS float*)(F.lds + AT_BOFF);
;     const int lane = F.lane, g4 = lane >> 4, ql = lane & 15;
;     const int hq = F.wave >> 1, th = F.wave & 1;
;     constexpr float LOG2E = 1.44269504f;
;     for (int U = F.vcu; U < NB * 64 * NKV; U += F.G) {
;         int b = U >> 8, n = (U >> 2) & 63, kvh = U & 3;
;         if (F.G == 256) { const int xg = F.vcu >> 5, lu = (F.vcu & 31) + ((U >= 256) ? 32 : 0); b = xg >> 2; n = 16 * (xg & 3) + (lu >> 2); kvh = lu & 3; }
;         const int h = kvh * 4 + hq;
;         __syncthreads();
;         { const int part = F.tid & 7; f32x4 kg0 = *(const f32x4*)(kg + part * 8), kg1 = *(const f32x4*)(kg + part * 8 + 4);
;           v4u kqa[6], vqa[6];
; #pragma unroll
;           for (int i = 0; i < 6; ++i) { const int row = (F.tid >> 3) + 64 * i; const int kpos = n * 128 - 128 + row; const bool ok = (kpos >= 0) && (kpos < S);
;               kqa[i] = (v4u){0u, 0u, 0u, 0u}; vqa[i] = (v4u){0u, 0u, 0u, 0u};
;               if (ok) { const bf16* base = QKV + ((size_t)b * S + kpos) * QKVN + NH * HD + kvh * HD + part * 8; kqa[i] = *(const GAS v4u*)base; vqa[i] = *(const GAS v4u*)(base + NKV * HD); } }
; #pragma unroll
;           for (int i = 0; i < 6; ++i) { const int row = (F.tid >> 3) + 64 * i; const v4u kq = kqa[i], vq = vqa[i];
;               float f[8] = {bf_lo(kq.x), bf_hi(kq.x), bf_lo(kq.y), bf_hi(kq.y), bf_lo(kq.z), bf_hi(kq.z), bf_lo(kq.w), bf_hi(kq.w)};
;               float ss = 0.f;
; #pragma unroll
;               for (int e = 0; e < 8; ++e) ss += f[e] * f[e];
;               ss += shx(ss, 1, F.lane); ss += shx(ss, 2, F.lane); ss += shx(ss, 4, F.lane);
;               const float r = rsqrtf(ss * (1.0f / HD) + EPS);
;               v4u ko; ko.x = pk2(f[0] * r * kg0.x, f[1] * r * kg0.y); ko.y = pk2(f[2] * r * kg0.z, f[3] * r * kg0.w); ko.z = pk2(f[4] * r * kg1.x, f[5] * r * kg1.y); ko.w = pk2(f[6] * r * kg1.z, f[7] * r * kg1.w);
;               *(LAS v4u*)(Kimg + row * AT_KP + part * 16) = ko; *(LAS v4u*)(Vimg + row * AT_VP + part * 16) = vq; } }
;         for (int i = F.tid; i < 4 * 257; i += NTHR) { const int gg = i / 257, r = i - gg * 257; btab[gg * 260 + r] = biasrel[(kvh * 4 + gg) * 257 + r] - ATT_COFF; }
;         __syncthreads();
.LBB0_310:
	s_andn2_b64 vcc, exec, s[0:1]
	s_cbranch_vccnz .LBB0_481
	v_readlane_b32 s4, v251, 0
	v_readlane_b32 s0, v251, 14
	v_readlane_b32 s6, v251, 2
	v_readlane_b32 s7, v251, 3
	v_readlane_b32 s1, v251, 15
	s_mov_b64 s[2:3], s[6:7]
	v_readlane_b32 s16, v251, 13
	v_mbcnt_lo_u32_b32 v143, -1, 0
	v_mbcnt_hi_u32_b32 v143, -1, v143
	s_mov_b64 s[2:3], -1
	s_and_b64 vcc, exec, s[10:11]
	v_lshl_add_u32 v147, s16, 6, v143
	v_readlane_b32 s5, v251, 1
	s_cbranch_vccz .LBB0_411
	v_readlane_b32 s2, v252, 50
	v_readlane_b32 s3, v252, 51
	s_andn2_b64 vcc, exec, s[2:3]
	s_cbranch_vccnz .LBB0_410
	s_lshl_b32 s34, s26, 4
	s_add_u32 s4, s0, 0x16000000
	s_addc_u32 s5, s1, 0
	s_add_u32 s17, s0, 0x19000000
	s_addc_u32 s18, s1, 0
	s_add_u32 s6, s0, 0x200000
	s_addc_u32 s7, s1, 0
	s_lshl_b64 s[2:3], s[34:35], 2
	s_add_u32 s2, s0, s2
	s_addc_u32 s3, s1, s3
	s_add_u32 s19, s2, 0x2408400
	s_addc_u32 s20, s3, 0
	s_lshl_b32 s34, s26, 6
	s_ashr_i32 s21, s16, 1
	s_and_b32 s12, s16, 1
	s_lshl_b64 s[2:3], s[34:35], 2
	s_waitcnt vmcnt(0) lgkmcnt(0)
	v_ashrrev_i32_e32 v4, 4, v143
	v_lshlrev_b32_e32 v0, 3, v143
	s_add_u32 s2, s0, s2
	v_and_b32_e32 v6, 24, v0
	v_lshlrev_b32_e32 v0, 3, v4
	s_addc_u32 s3, s1, s3
	v_ashrrev_i32_e32 v1, 31, v0
	v_lshl_add_u64 v[2:3], v[0:1], 2, s[2:3]
	s_mov_b64 s[8:9], 0x2408000
	v_lshl_add_u64 v[136:137], v[2:3], 0, s[8:9]
	v_and_b32_e32 v3, 7, v143
	v_lshlrev_b32_e32 v144, 5, v3
	v_lshl_add_u64 v[138:139], v[0:1], 1, s[4:5]
	v_lshl_add_u64 v[0:1], s[2:3], 0, v[144:145]
	s_mov_b64 s[2:3], 0x2408200
	v_and_b32_e32 v156, 15, v143
	s_lshl_b32 s22, s12, 6
	v_lshlrev_b32_e32 v140, 2, v4
	v_lshl_add_u64 v[162:163], v[0:1], 0, s[2:3]
	v_lshlrev_b32_e32 v0, 2, v143
	v_bfe_u32 v5, v143, 2, 2
	v_and_b32_e32 v2, -16, v143
	v_ashrrev_i32_e32 v171, 3, v147
	v_xor_b32_e32 v173, 4, v0
	v_xor_b32_e32 v174, 8, v0
	v_xor_b32_e32 v175, 16, v0
	s_movk_i32 s2, 0x90
	s_movk_i32 s3, 0xa0
	v_xor_b32_e32 v177, 64, v0
	v_xor_b32_e32 v178, 0x80, v0
	s_mulk_i32 s12, 0x2400
	v_mul_u32_u24_e32 v0, 0x90, v156
	v_add_u32_e32 v182, s22, v140
	v_mul_lo_u32 v1, v171, s2
	v_mul_lo_u32 v176, v171, s3
	s_movk_i32 s2, 0x404
	v_add3_u32 v180, s12, v0, v2
	v_or_b32_e32 v0, v182, v5
	s_mul_i32 s13, s21, 0x800
	v_lshlrev_b32_e32 v142, 3, v3
	v_lshl_add_u32 v172, v3, 4, 0
	v_add_u32_e32 v3, 0x2800, v176
	v_add_u32_e32 v4, 0x5000, v176
	v_add_u32_e32 v7, 0x7800, v176
	v_add_u32_e32 v8, 0xa000, v176
	v_add_u32_e32 v9, 0xc800, v176
	v_cmp_gt_i32_e64 s[36:37], s2, v147
	v_mul_lo_u32 v0, v0, s3
	v_readlane_b32 s2, v254, 18
	v_ashrrev_i32_e32 v141, 31, v140
	v_or_b32_e32 v170, s22, v156
	v_add3_u32 v184, v0, s2, v6
	v_add_u32_e32 v186, s13, v2
	v_add_u32_e32 v186, 0x200, v186
	v_add_u32_e32 v188, v172, v1
	v_add_u32_e32 v189, v172, v3
	v_add_u32_e32 v190, v172, v4
	v_add_u32_e32 v191, v172, v7
	v_add_u32_e32 v192, v172, v8
	v_add_u32_e32 v193, v172, v9
	v_readlane_b32 s23, v251, 8
	s_branch .LBB0_315

; #define GAS __attribute__((address_space(1)))
; #define LAS __attribute__((address_space(3)))
; __device__ __forceinline__ unsigned pk2(float lo, float hi) { const f32x2_t v = {lo, hi}; return __builtin_bit_cast(unsigned, __builtin_convertvector(v, bf16x2_t)); }
; __device__ __forceinline__ float shx(float v, int o, int lane) { return __builtin_bit_cast(float, __builtin_amdgcn_ds_bpermute((lane ^ o) << 2, __builtin_bit_cast(int, v))); }
; __device__ __forceinline__ void phase_ac(const Params& p, Frame& F, int l) {
;     ...
;           for (int i = 0; i < 6; ++i) { const int row = (F.tid >> 3) + 64 * i; const int kpos = n * 128 - 128 + row; const bool ok = (kpos >= 0) && (kpos < S);
;               kqa[i] = (v4u){0u, 0u, 0u, 0u}; vqa[i] = (v4u){0u, 0u, 0u, 0u};
;               if (ok) { const bf16* base = QKV + ((size_t)b * S + kpos) * QKVN + NH * HD + kvh * HD + part * 8; kqa[i] = *(const GAS v4u*)base; vqa[i] = *(const GAS v4u*)(base + NKV * HD); } }
; #pragma unroll
;           for (int i = 0; i < 6; ++i) { const int row = (F.tid >> 3) + 64 * i; const v4u kq = kqa[i], vq = vqa[i];
;               float f[8] = {bf_lo(kq.x), bf_hi(kq.x), bf_lo(kq.y), bf_hi(kq.y), bf_lo(kq.z), bf_hi(kq.z), bf_lo(kq.w), bf_hi(kq.w)};
;               float ss = 0.f;
; #pragma unroll
;               for (int e = 0; e < 8; ++e) ss += f[e] * f[e];
;               ss += shx(ss, 1, F.lane); ss += shx(ss, 2, F.lane); ss += shx(ss, 4, F.lane);
;               const float r = rsqrtf(ss * (1.0f / HD) + EPS);
;               v4u ko; ko.x = pk2(f[0] * r * kg0.x, f[1] * r * kg0.y); ko.y = pk2(f[2] * r * kg0.z, f[3] * r * kg0.w); ko.z = pk2(f[4] * r * kg1.x, f[5] * r * kg1.y); ko.w = pk2(f[6] * r * kg1.z, f[7] * r * kg1.w);
;               *(LAS v4u*)(Kimg + row * AT_KP + part * 16) = ko; *(LAS v4u*)(Vimg + row * AT_VP + part * 16) = vq; } }
.LBB0_331:
	s_or_b64 exec, exec, s[12:13]
	s_waitcnt vmcnt(0)
	v_lshlrev_b32_e32 v66, 16, v44
	v_and_b32_e32 v67, 0xffff0000, v44
	v_lshlrev_b32_e32 v78, 16, v52
	v_and_b32_e32 v79, 0xffff0000, v52
	v_lshlrev_b32_e32 v62, 16, v45
	v_and_b32_e32 v63, 0xffff0000, v45
	v_pk_mul_f32 v[44:45], v[66:67], v[66:67]
	v_lshlrev_b32_e32 v74, 16, v53
	v_and_b32_e32 v75, 0xffff0000, v53
	v_pk_mul_f32 v[52:53], v[78:79], v[78:79]
	v_pk_mul_f32 v[64:65], v[62:63], v[62:63]
	v_pk_mul_f32 v[76:77], v[74:75], v[74:75]
	v_mov_b32_e32 v80, v52
	v_mov_b32_e32 v81, v44
	v_mov_b32_e32 v44, v53
	v_lshlrev_b32_e32 v60, 16, v46
	v_and_b32_e32 v61, 0xffff0000, v46
	v_lshlrev_b32_e32 v72, 16, v54
	v_and_b32_e32 v73, 0xffff0000, v54
	v_pk_add_f32 v[44:45], v[80:81], v[44:45]
	v_mov_b32_e32 v52, v76
	v_mov_b32_e32 v53, v64
	v_lshlrev_b32_e32 v56, 16, v47
	v_and_b32_e32 v57, 0xffff0000, v47
	v_pk_mul_f32 v[46:47], v[60:61], v[60:61]
	v_lshlrev_b32_e32 v68, 16, v55
	v_and_b32_e32 v69, 0xffff0000, v55
	v_pk_mul_f32 v[54:55], v[72:73], v[72:73]
	v_pk_add_f32 v[44:45], v[52:53], v[44:45]
	v_mov_b32_e32 v64, v77
	v_pk_add_f32 v[44:45], v[64:65], v[44:45]
	v_mov_b32_e32 v52, v54
	v_mov_b32_e32 v53, v46
	v_pk_mul_f32 v[58:59], v[56:57], v[56:57]
	v_pk_mul_f32 v[70:71], v[68:69], v[68:69]
	v_pk_add_f32 v[44:45], v[52:53], v[44:45]
	v_mov_b32_e32 v46, v55
	v_pk_add_f32 v[44:45], v[46:47], v[44:45]
	v_mov_b32_e32 v46, v70
	v_mov_b32_e32 v47, v58
	v_pk_add_f32 v[44:45], v[46:47], v[44:45]
	v_mov_b32_e32 v58, v71
	v_pk_add_f32 v[44:45], v[58:59], v[44:45]
	ds_bpermute_b32 v47, v173, v45
	ds_bpermute_b32 v46, v173, v44
	s_mov_b32 s12, 0x358637bd
	s_mov_b32 s14, 0x3c800000
	v_lshlrev_b32_e32 v70, 16, v48
	v_and_b32_e32 v71, 0xffff0000, v48
	s_waitcnt lgkmcnt(0)
	v_pk_add_f32 v[44:45], v[44:45], v[46:47]
	ds_bpermute_b32 v47, v174, v45
	ds_bpermute_b32 v46, v174, v44
	v_lshlrev_b32_e32 v64, 16, v49
	v_and_b32_e32 v65, 0xffff0000, v49
	v_pk_mul_f32 v[48:49], v[70:71], v[70:71]
	s_mov_b32 s42, 0x3c800000
	s_waitcnt lgkmcnt(0)
	v_pk_add_f32 v[44:45], v[44:45], v[46:47]
	ds_bpermute_b32 v47, v175, v45
	ds_bpermute_b32 v46, v175, v44
	v_mov_b32_e32 v76, v48
	s_waitcnt lgkmcnt(0)
	v_pk_add_f32 v[46:47], v[44:45], v[46:47]
	v_mov_b64_e32 v[44:45], s[12:13]
	v_pk_fma_f32 v[46:47], v[46:47], s[14:15], v[44:45] op_sel_hi:[1,0,0]
	s_mov_b32 s12, 0x800000
	v_mul_f32_e32 v52, 0x4b800000, v47
	v_cmp_gt_f32_e32 vcc, s12, v47
	s_nop 1
	v_cndmask_b32_e32 v47, v47, v52, vcc
	v_rsq_f32_e32 v47, v47
	s_nop 0
	v_mul_f32_e32 v52, 0x45800000, v47
	v_cndmask_b32_e32 v58, v47, v52, vcc
	v_pk_mul_f32 v[52:53], v[58:59], v[66:67] op_sel_hi:[0,1]
	v_pk_mul_f32 v[54:55], v[58:59], v[62:63] op_sel_hi:[0,1]
	v_pk_mul_f32 v[52:53], v[4:5], v[52:53]
	v_pk_mul_f32 v[54:55], v[6:7], v[54:55]
	v_cvt_pk_bf16_f32 v52, v52, v53
	v_cvt_pk_bf16_f32 v53, v54, v55
	v_pk_mul_f32 v[54:55], v[58:59], v[60:61] op_sel_hi:[0,1]
	v_pk_mul_f32 v[56:57], v[58:59], v[56:57] op_sel_hi:[0,1]
	v_mul_f32_e32 v47, 0x4b800000, v46
	v_cmp_gt_f32_e32 vcc, s12, v46
	v_pk_mul_f32 v[54:55], v[0:1], v[54:55]
	v_pk_mul_f32 v[56:57], v[2:3], v[56:57]
	v_cndmask_b32_e32 v46, v46, v47, vcc
	v_cvt_pk_bf16_f32 v54, v54, v55
	v_cvt_pk_bf16_f32 v55, v56, v57
	v_rsq_f32_e32 v80, v46
	v_add_u32_e32 v46, v172, v176
	v_lshlrev_b32_e32 v56, 16, v40
	v_and_b32_e32 v57, 0xffff0000, v40
	ds_write_b128 v188, v[52:55]
	ds_write_b128 v46, v[28:31] offset:55296
	v_lshlrev_b32_e32 v46, 16, v43
	v_and_b32_e32 v47, 0xffff0000, v43
	v_lshlrev_b32_e32 v52, 16, v42
	v_and_b32_e32 v53, 0xffff0000, v42
	v_lshlrev_b32_e32 v42, 16, v41
	v_and_b32_e32 v43, 0xffff0000, v41
	v_pk_mul_f32 v[40:41], v[56:57], v[56:57]
	v_pk_mul_f32 v[54:55], v[42:43], v[42:43]
	v_pk_mul_f32 v[66:67], v[64:65], v[64:65]
	v_mov_b32_e32 v77, v40
	v_mov_b32_e32 v40, v49
	v_lshlrev_b32_e32 v62, 16, v50
	v_and_b32_e32 v63, 0xffff0000, v50
	v_pk_add_f32 v[40:41], v[76:77], v[40:41]
	v_mov_b32_e32 v48, v66
	v_mov_b32_e32 v49, v54
	v_pk_mul_f32 v[30:31], v[52:53], v[52:53]
	v_lshlrev_b32_e32 v58, 16, v51
	v_and_b32_e32 v59, 0xffff0000, v51
	v_pk_mul_f32 v[50:51], v[62:63], v[62:63]
	v_pk_add_f32 v[40:41], v[48:49], v[40:41]
	v_mov_b32_e32 v54, v67
	v_pk_add_f32 v[40:41], v[54:55], v[40:41]
	v_mov_b32_e32 v48, v50
	v_mov_b32_e32 v49, v30
	v_pk_mul_f32 v[28:29], v[46:47], v[46:47]
	v_pk_mul_f32 v[60:61], v[58:59], v[58:59]
	v_pk_add_f32 v[40:41], v[48:49], v[40:41]
	v_mov_b32_e32 v30, v51
	v_pk_add_f32 v[30:31], v[30:31], v[40:41]
	v_mov_b32_e32 v40, v60
	v_mov_b32_e32 v41, v28
	v_pk_add_f32 v[30:31], v[40:41], v[30:31]
	v_mov_b32_e32 v28, v61
	v_pk_add_f32 v[30:31], v[28:29], v[30:31]
	ds_bpermute_b32 v41, v173, v31
	ds_bpermute_b32 v40, v173, v30
	v_mul_f32_e32 v81, 0x45800000, v80
	v_cndmask_b32_e32 v48, v80, v81, vcc
	v_pk_mul_f32 v[28:29], v[48:49], v[78:79] op_sel_hi:[0,1]
	v_pk_mul_f32 v[50:51], v[48:49], v[74:75] op_sel_hi:[0,1]
	s_waitcnt lgkmcnt(0)
	v_pk_add_f32 v[30:31], v[30:31], v[40:41]
	ds_bpermute_b32 v41, v174, v31
	ds_bpermute_b32 v40, v174, v30
	v_pk_mul_f32 v[28:29], v[4:5], v[28:29]
	v_pk_mul_f32 v[50:51], v[6:7], v[50:51]
	v_cvt_pk_bf16_f32 v28, v28, v29
	v_cvt_pk_bf16_f32 v29, v50, v51
	s_waitcnt lgkmcnt(0)
	v_pk_add_f32 v[40:41], v[30:31], v[40:41]
	ds_bpermute_b32 v55, v175, v41
	ds_bpermute_b32 v54, v175, v40
	v_pk_mul_f32 v[50:51], v[48:49], v[72:73] op_sel_hi:[0,1]
	v_pk_mul_f32 v[30:31], v[0:1], v[50:51]
	v_pk_mul_f32 v[48:49], v[48:49], v[68:69] op_sel_hi:[0,1]
	v_cvt_pk_bf16_f32 v30, v30, v31
	s_waitcnt lgkmcnt(0)
; #define LAS __attribute__((address_space(3)))
; __device__ __forceinline__ unsigned pk2(float lo, float hi) { const f32x2_t v = {lo, hi}; return __builtin_bit_cast(unsigned, __builtin_convertvector(v, bf16x2_t)); }
; __device__ __forceinline__ float shx(float v, int o, int lane) { return __builtin_bit_cast(float, __builtin_amdgcn_ds_bpermute((lane ^ o) << 2, __builtin_bit_cast(int, v))); }
; __device__ __forceinline__ void phase_ac(const Params& p, Frame& F, int l) {
;     ...
;           for (int i = 0; i < 6; ++i) { const int row = (F.tid >> 3) + 64 * i; const v4u kq = kqa[i], vq = vqa[i];
;               float f[8] = {bf_lo(kq.x), bf_hi(kq.x), bf_lo(kq.y), bf_hi(kq.y), bf_lo(kq.z), bf_hi(kq.z), bf_lo(kq.w), bf_hi(kq.w)};
;               float ss = 0.f;
; #pragma unroll
;               for (int e = 0; e < 8; ++e) ss += f[e] * f[e];
;               ss += shx(ss, 1, F.lane); ss += shx(ss, 2, F.lane); ss += shx(ss, 4, F.lane);
;               const float r = rsqrtf(ss * (1.0f / HD) + EPS);
;               v4u ko; ko.x = pk2(f[0] * r * kg0.x, f[1] * r * kg0.y); ko.y = pk2(f[2] * r * kg0.z, f[3] * r * kg0.w); ko.z = pk2(f[4] * r * kg1.x, f[5] * r * kg1.y); ko.w = pk2(f[6] * r * kg1.z, f[7] * r * kg1.w);
;               *(LAS v4u*)(Kimg + row * AT_KP + part * 16) = ko; *(LAS v4u*)(Vimg + row * AT_VP + part * 16) = vq; } }
;         for (int i = F.tid; i < 4 * 257; i += NTHR) { const int gg = i / 257, r = i - gg * 257; btab[gg * 260 + r] = biasrel[(kvh * 4 + gg) * 257 + r] - ATT_COFF; }
	v_pk_add_f32 v[40:41], v[40:41], v[54:55]
	v_pk_mul_f32 v[48:49], v[2:3], v[48:49]
	v_pk_fma_f32 v[40:41], v[40:41], s[14:15], v[44:45] op_sel_hi:[1,0,0]
	s_nop 0
	v_mul_f32_e32 v31, 0x4b800000, v41
	v_cmp_gt_f32_e32 vcc, s12, v41
	s_nop 1
	v_cndmask_b32_e32 v31, v41, v31, vcc
	v_rsq_f32_e32 v41, v31
	v_cvt_pk_bf16_f32 v31, v48, v49
	ds_write_b128 v188, v[28:31] offset:9216
	ds_write_b128 v189, v[12:15] offset:55296
	v_lshlrev_b32_e32 v48, 16, v37
	v_mul_f32_e32 v12, 0x45800000, v41
	v_cndmask_b32_e32 v28, v41, v12, vcc
	v_pk_mul_f32 v[12:13], v[28:29], v[56:57] op_sel_hi:[0,1]
	v_pk_mul_f32 v[14:15], v[28:29], v[42:43] op_sel_hi:[0,1]
	v_pk_mul_f32 v[12:13], v[4:5], v[12:13]
	v_pk_mul_f32 v[14:15], v[6:7], v[14:15]
	v_cvt_pk_bf16_f32 v12, v12, v13
	v_cvt_pk_bf16_f32 v13, v14, v15
	v_pk_mul_f32 v[14:15], v[28:29], v[52:53] op_sel_hi:[0,1]
	v_pk_mul_f32 v[14:15], v[0:1], v[14:15]
	v_pk_mul_f32 v[28:29], v[28:29], v[46:47] op_sel_hi:[0,1]
	v_cvt_pk_bf16_f32 v14, v14, v15
	v_mul_f32_e32 v15, 0x4b800000, v40
	v_cmp_gt_f32_e32 vcc, s12, v40
	v_pk_mul_f32 v[28:29], v[2:3], v[28:29]
	v_lshlrev_b32_e32 v52, 16, v36
	v_cndmask_b32_e32 v15, v40, v15, vcc
	v_rsq_f32_e32 v56, v15
	v_cvt_pk_bf16_f32 v15, v28, v29
	ds_write_b128 v188, v[12:15] offset:18432
	ds_write_b128 v190, v[24:27] offset:55296
	v_lshlrev_b32_e32 v24, 16, v35
	v_and_b32_e32 v25, 0xffff0000, v35
	v_lshlrev_b32_e32 v26, 16, v34
	v_and_b32_e32 v27, 0xffff0000, v34
	v_lshlrev_b32_e32 v34, 16, v32
	v_and_b32_e32 v35, 0xffff0000, v32
	v_and_b32_e32 v53, 0xffff0000, v36
	v_lshlrev_b32_e32 v28, 16, v33
	v_and_b32_e32 v29, 0xffff0000, v33
	v_pk_mul_f32 v[32:33], v[34:35], v[34:35]
	v_and_b32_e32 v49, 0xffff0000, v37
	v_pk_mul_f32 v[36:37], v[52:53], v[52:53]
	v_pk_mul_f32 v[30:31], v[28:29], v[28:29]
	v_pk_mul_f32 v[50:51], v[48:49], v[48:49]
	v_mov_b32_e32 v54, v36
	v_mov_b32_e32 v55, v32
	v_mov_b32_e32 v32, v37
	v_lshlrev_b32_e32 v46, 16, v38
	v_and_b32_e32 v47, 0xffff0000, v38
	v_pk_add_f32 v[32:33], v[54:55], v[32:33]
	v_mov_b32_e32 v36, v50
	v_mov_b32_e32 v37, v30
	v_pk_mul_f32 v[14:15], v[26:27], v[26:27]
	v_lshlrev_b32_e32 v40, 16, v39
	v_and_b32_e32 v41, 0xffff0000, v39
	v_pk_mul_f32 v[38:39], v[46:47], v[46:47]
	v_pk_add_f32 v[32:33], v[36:37], v[32:33]
	v_mov_b32_e32 v30, v51
	v_pk_add_f32 v[30:31], v[30:31], v[32:33]
	v_mov_b32_e32 v32, v38
	v_mov_b32_e32 v33, v14
	v_pk_mul_f32 v[12:13], v[24:25], v[24:25]
	v_pk_mul_f32 v[42:43], v[40:41], v[40:41]
	v_pk_add_f32 v[30:31], v[32:33], v[30:31]
	v_mov_b32_e32 v14, v39
	v_pk_add_f32 v[14:15], v[14:15], v[30:31]
	v_mov_b32_e32 v30, v42
	v_mov_b32_e32 v31, v12
	v_pk_add_f32 v[14:15], v[30:31], v[14:15]
	v_mov_b32_e32 v12, v43
	v_pk_add_f32 v[14:15], v[12:13], v[14:15]
	ds_bpermute_b32 v31, v173, v15
	ds_bpermute_b32 v30, v173, v14
	v_mul_f32_e32 v57, 0x45800000, v56
	v_cndmask_b32_e32 v32, v56, v57, vcc
	v_pk_mul_f32 v[12:13], v[32:33], v[70:71] op_sel_hi:[0,1]
	v_pk_mul_f32 v[36:37], v[32:33], v[64:65] op_sel_hi:[0,1]
	s_waitcnt lgkmcnt(0)
	v_pk_add_f32 v[14:15], v[14:15], v[30:31]
	ds_bpermute_b32 v31, v174, v15
	ds_bpermute_b32 v30, v174, v14
	v_pk_mul_f32 v[12:13], v[4:5], v[12:13]
	v_pk_mul_f32 v[36:37], v[6:7], v[36:37]
	v_cvt_pk_bf16_f32 v12, v12, v13
	v_cvt_pk_bf16_f32 v13, v36, v37
	s_waitcnt lgkmcnt(0)
	v_pk_add_f32 v[30:31], v[14:15], v[30:31]
	ds_bpermute_b32 v39, v175, v31
	ds_bpermute_b32 v38, v175, v30
	v_pk_mul_f32 v[36:37], v[32:33], v[62:63] op_sel_hi:[0,1]
	v_pk_mul_f32 v[14:15], v[0:1], v[36:37]
	v_pk_mul_f32 v[32:33], v[32:33], v[58:59] op_sel_hi:[0,1]
	v_cvt_pk_bf16_f32 v14, v14, v15
	s_waitcnt lgkmcnt(0)
	v_pk_add_f32 v[30:31], v[30:31], v[38:39]
	v_pk_mul_f32 v[32:33], v[2:3], v[32:33]
	v_pk_fma_f32 v[30:31], v[30:31], s[14:15], v[44:45] op_sel_hi:[1,0,0]
	s_nop 0
	v_mul_f32_e32 v15, 0x4b800000, v31
	v_cmp_gt_f32_e32 vcc, s12, v31
	s_nop 1
	v_cndmask_b32_e32 v15, v31, v15, vcc
	v_rsq_f32_e32 v31, v15
	v_cvt_pk_bf16_f32 v15, v32, v33
	ds_write_b128 v188, v[12:15] offset:27648
	ds_write_b128 v191, v[8:11] offset:55296
	v_mul_f32_e32 v8, 0x45800000, v31
	v_cndmask_b32_e32 v12, v31, v8, vcc
	v_pk_mul_f32 v[8:9], v[12:13], v[34:35] op_sel_hi:[0,1]
	v_pk_mul_f32 v[10:11], v[12:13], v[28:29] op_sel_hi:[0,1]
	v_pk_mul_f32 v[8:9], v[4:5], v[8:9]
	v_pk_mul_f32 v[10:11], v[6:7], v[10:11]
	v_cvt_pk_bf16_f32 v8, v8, v9
	v_cvt_pk_bf16_f32 v9, v10, v11
	v_pk_mul_f32 v[10:11], v[12:13], v[26:27] op_sel_hi:[0,1]
	v_pk_mul_f32 v[10:11], v[0:1], v[10:11]
	v_cmp_gt_f32_e32 vcc, s12, v30
	v_cvt_pk_bf16_f32 v10, v10, v11
	v_mul_f32_e32 v11, 0x4b800000, v30
	v_cndmask_b32_e32 v11, v30, v11, vcc
	v_rsq_f32_e32 v14, v11
	v_pk_mul_f32 v[12:13], v[12:13], v[24:25] op_sel_hi:[0,1]
	v_pk_mul_f32 v[12:13], v[2:3], v[12:13]
	s_nop 0
	v_cvt_pk_bf16_f32 v11, v12, v13
	ds_write_b128 v188, v[8:11] offset:36864
	ds_write_b128 v192, v[20:23] offset:55296
	v_mul_f32_e32 v8, 0x45800000, v14
	v_cndmask_b32_e32 v8, v14, v8, vcc
	v_pk_mul_f32 v[10:11], v[8:9], v[52:53] op_sel_hi:[0,1]
	v_pk_mul_f32 v[4:5], v[4:5], v[10:11]
	v_pk_mul_f32 v[10:11], v[8:9], v[48:49] op_sel_hi:[0,1]
	v_pk_mul_f32 v[6:7], v[6:7], v[10:11]
	v_cvt_pk_bf16_f32 v4, v4, v5
	v_cvt_pk_bf16_f32 v5, v6, v7
	v_pk_mul_f32 v[6:7], v[8:9], v[46:47] op_sel_hi:[0,1]
	v_pk_mul_f32 v[0:1], v[0:1], v[6:7]
	s_nop 0
	v_cvt_pk_bf16_f32 v6, v0, v1
	v_pk_mul_f32 v[0:1], v[8:9], v[40:41] op_sel_hi:[0,1]
	v_pk_mul_f32 v[0:1], v[2:3], v[0:1]
	s_nop 0
	v_cvt_pk_bf16_f32 v7, v0, v1
	ds_write_b128 v188, v[4:7] offset:46080
	ds_write_b128 v193, v[16:19] offset:55296
	v_readlane_b32 s28, v254, 19
	v_add_u32_e32 v0, 0xffffff80, v147
	v_cmp_gt_u32_e32 vcc, 0x101, v0
	v_min_u32_e32 v0, 0x100, v0
	s_mul_i32 s27, s24, 0x404
	v_add_u32_e32 v0, s27, v0
	v_mov_b32_e32 v1, 0
	v_lshl_add_u64 v[0:1], v[0:1], 2, s[6:7]
	global_load_dword v4, v[0:1], off
	global_load_dword v5, v[0:1], off offset:1028
	global_load_dword v6, v[0:1], off offset:2056
	global_load_dword v7, v[0:1], off offset:3084
	v_lshl_add_u32 v2, v147, 2, s28
	v_mov_b32_e32 v3, 0xf149f2ca
	s_waitcnt vmcnt(0)
	v_add_f32_e32 v4, 0xc1800000, v4
	v_add_f32_e32 v5, 0xc1800000, v5
	v_add_f32_e32 v6, 0xc1800000, v6
	v_add_f32_e32 v7, 0xc1800000, v7
	v_cndmask_b32_e32 v4, v3, v4, vcc
	v_cndmask_b32_e32 v5, v3, v5, vcc
	v_cndmask_b32_e32 v6, v3, v6, vcc
	v_cndmask_b32_e32 v7, v3, v7, vcc
	ds_write_b32 v2, v4
	ds_write_b32 v2, v5 offset:2048
	ds_write_b32 v2, v6 offset:4096
	ds_write_b32 v2, v7 offset:6144
; #define LAS __attribute__((address_space(3)))
; __device__ __forceinline__ unsigned lds_addr(LAS void* p) { return (unsigned)(size_t)p; }
; __device__ __forceinline__ void phase_ac(const Params& p, Frame& F, int l) {
;     ...
;         for (int i = F.tid; i < 4 * 257; i += NTHR) { const int gg = i / 257, r = i - gg * 257; btab[gg * 260 + r] = biasrel[(kvh * 4 + gg) * 257 + r] - ATT_COFF; }
;         __syncthreads();
;         const float sk = sink[h] * LOG2E - ATT_COFF;
;         const LAS float* bt = btab + hq * 260;
;         const unsigned vbase = lds_addr(Vimg) + (unsigned)(((lane & 15) >> 2) * AT_VP + (lane & 3) * 8);
;         f32x4 qa[2][2];
;         const bf16x8 ones8 = __builtin_bit_cast(bf16x8, (v4u){0x3f803f80u, 0x3f803f80u, 0x3f803f80u, 0x3f803f80u});
; #pragma unroll
;         for (int ds = 0; ds < 2; ++ds) { qa[ds][0] = *(const f32x4*)(qg + 32 * ds + 8 * g4); qa[ds][1] = *(const f32x4*)(qg + 32 * ds + 8 * g4 + 4); }
;     ...
;             for (int q2 = 0; q2 < 2; ++q2) { const float lt = osum[q2].x + __builtin_amdgcn_exp2f(sk);
.LBB0_334:
	s_lshl_b32 s12, s24, 2
	s_add_i32 s12, s12, s21
	s_ashr_i32 s13, s12, 31
	s_lshl_b64 s[14:15], s[12:13], 2
	s_add_u32 s14, s19, s14
	s_addc_u32 s15, s20, s15
	v_mov_b64_e32 v[0:1], s[14:15]
	s_waitcnt lgkmcnt(0)
	s_barrier
	flat_load_dword v16, v[0:1]
	s_nop 0
	flat_load_dwordx4 v[0:3], v[136:137]
	flat_load_dwordx4 v[4:7], v[136:137] offset:16
	flat_load_dwordx4 v[8:11], v[136:137] offset:128
	flat_load_dwordx4 v[12:15], v[136:137] offset:144
	s_lshl_b32 s12, s12, 6
	s_ashr_i32 s13, s12, 31
	s_lshl_b64 s[2:3], s[2:3], 24
	s_lshl_b64 s[12:13], s[12:13], 1
	s_add_u32 s2, s17, s2
	s_addc_u32 s3, s18, s3
	s_add_u32 s2, s2, s12
	s_addc_u32 s3, s3, s13
	v_or_b32_e32 v194, s25, v170
	v_lshl_add_u64 v[164:165], v[138:139], 0, s[12:13]
	v_lshl_add_u64 v[166:167], v[140:141], 1, s[2:3]
	s_add_i32 s24, s22, s25
	v_add_u32_e32 v196, s25, v182
	s_mov_b32 s14, 0
	s_mov_b64 s[2:3], -1
	s_waitcnt vmcnt(0) lgkmcnt(0)
	v_fmamk_f32 v16, v16, 0x3fb8aa3b, v241
	v_exp_f32_e32 v195, v16
	s_branch .LBB0_336

; #define GAS __attribute__((address_space(1)))
; __device__ __forceinline__ float shx(float v, int o, int lane) { return __builtin_bit_cast(float, __builtin_amdgcn_ds_bpermute((lane ^ o) << 2, __builtin_bit_cast(int, v))); }
; __device__ __forceinline__ void phase_ac(const Params& p, Frame& F, int l) {
;     ...
;             for (int q2 = 0; q2 < 2; ++q2) { const int tok = n * 128 + th * 64 + 32 * qh + 16 * q2 + ql; const bf16* qp = QKV + ((size_t)b * S + tok) * QKVN + h * HD + 8 * g4;
;                 const v4u w0 = *(const GAS v4u*)qp, w1 = *(const GAS v4u*)(qp + 32);
;                 float f[16] = {bf_lo(w0.x), bf_hi(w0.x), bf_lo(w0.y), bf_hi(w0.y), bf_lo(w0.z), bf_hi(w0.z), bf_lo(w0.w), bf_hi(w0.w), bf_lo(w1.x), bf_hi(w1.x), bf_lo(w1.y), bf_hi(w1.y), bf_lo(w1.z), bf_hi(w1.z), bf_lo(w1.w), bf_hi(w1.w)};
;                 float ss = 0.f;
; #pragma unroll
;                 for (int e = 0; e < 16; ++e) ss += f[e] * f[e];
;                 ss += shx(ss, 16, F.lane); ss += shx(ss, 32, F.lane);
;                 const float r = rsqrtf(ss * (1.0f / HD) + EPS) * (0.125f * LOG2E);
.LBB0_336:
	v_or_b32_e32 v144, s14, v194
	v_lshl_add_u64 v[16:17], s[8:9], 0, v[144:145]
	s_movk_i32 s15, 0xc00
	s_xor_b64 s[12:13], s[2:3], -1
	v_mad_u64_u32 v[18:19], s[2:3], v16, s15, v[164:165]
	v_mad_i32_i24 v19, v17, s15, v19
	global_load_dwordx4 v[34:37], v[18:19], off
	s_nop 0
	global_load_dwordx4 v[16:19], v[18:19], off offset:64
	v_or_b32_e32 v168, 16, v144
	v_mov_b32_e32 v169, v145
	v_lshl_add_u64 v[42:43], s[8:9], 0, v[168:169]
	v_mad_u64_u32 v[58:59], s[2:3], v42, s15, v[164:165]
	v_mad_i32_i24 v59, v43, s15, v59
	global_load_dwordx4 v[42:45], v[58:59], off offset:64
	s_nop 0
	global_load_dwordx4 v[58:61], v[58:59], off
	v_mov_b32_e32 v199, v184
	v_mov_b32_e32 v200, v180
	s_mov_b32 s34, 0
	s_waitcnt vmcnt(3)
	v_lshlrev_b32_e32 v30, 16, v35
	s_waitcnt vmcnt(2)
	v_lshlrev_b32_e32 v26, 16, v17
	v_and_b32_e32 v27, 0xffff0000, v17
	v_lshlrev_b32_e32 v20, 16, v16
	v_and_b32_e32 v21, 0xffff0000, v16
	v_and_b32_e32 v31, 0xffff0000, v35
	v_lshlrev_b32_e32 v16, 16, v34
	v_and_b32_e32 v17, 0xffff0000, v34
	v_lshlrev_b32_e32 v24, 16, v19
	v_and_b32_e32 v25, 0xffff0000, v19
	v_lshlrev_b32_e32 v22, 16, v18
	v_and_b32_e32 v23, 0xffff0000, v18
	v_lshlrev_b32_e32 v28, 16, v37
	v_and_b32_e32 v29, 0xffff0000, v37
	v_lshlrev_b32_e32 v18, 16, v36
	v_and_b32_e32 v19, 0xffff0000, v36
	v_mov_b32_e32 v79, v17
	v_mov_b32_e32 v77, v16
	v_mov_b32_e32 v73, v30
	v_mov_b32_e32 v75, v31
	v_mov_b32_e32 v69, v18
	v_mov_b32_e32 v71, v19
	v_pk_mul_f32 v[54:55], v[20:21], v[20:21]
	v_pk_mul_f32 v[52:53], v[26:27], v[26:27]
	v_pk_mul_f32 v[50:51], v[22:23], v[22:23]
	v_pk_mul_f32 v[32:33], v[24:25], v[24:25]
	s_mov_b32 s2, 0x800000
	s_waitcnt vmcnt(0)
	v_and_b32_e32 v49, 0xffff0000, v58
	v_lshlrev_b32_e32 v48, 16, v58
	v_mov_b32_e32 v78, v49
	v_lshlrev_b32_e32 v46, 16, v59
	v_mov_b32_e32 v76, v48
	v_pk_mul_f32 v[78:79], v[78:79], v[78:79]
	v_and_b32_e32 v47, 0xffff0000, v59
	v_mov_b32_e32 v72, v46
	v_pk_fma_f32 v[76:77], v[76:77], v[76:77], v[78:79]
	s_waitcnt vmcnt(0)
	v_lshlrev_b32_e32 v36, 16, v44
	v_and_b32_e32 v37, 0xffff0000, v44
	v_lshlrev_b32_e32 v44, 16, v60
	v_mov_b32_e32 v74, v47
	v_pk_fma_f32 v[72:73], v[72:73], v[72:73], v[76:77]
	v_lshlrev_b32_e32 v34, 16, v45
	v_and_b32_e32 v35, 0xffff0000, v45
	v_and_b32_e32 v45, 0xffff0000, v60
	v_mov_b32_e32 v68, v44
	v_pk_fma_f32 v[72:73], v[74:75], v[74:75], v[72:73]
	v_lshlrev_b32_e32 v40, 16, v42
	v_and_b32_e32 v41, 0xffff0000, v42
	v_lshlrev_b32_e32 v42, 16, v61
	v_mov_b32_e32 v70, v45
	v_pk_fma_f32 v[68:69], v[68:69], v[68:69], v[72:73]
	v_lshlrev_b32_e32 v38, 16, v43
	v_and_b32_e32 v39, 0xffff0000, v43
	v_and_b32_e32 v43, 0xffff0000, v61
	v_mov_b32_e32 v58, v42
	v_mov_b32_e32 v59, v28
	v_pk_fma_f32 v[68:69], v[70:71], v[70:71], v[68:69]
	v_pk_mul_f32 v[66:67], v[40:41], v[40:41]
	v_mov_b32_e32 v60, v43
	v_mov_b32_e32 v61, v29
	v_pk_fma_f32 v[58:59], v[58:59], v[58:59], v[68:69]
	v_pk_mul_f32 v[64:65], v[38:39], v[38:39]
	v_pk_fma_f32 v[58:59], v[60:61], v[60:61], v[58:59]
	v_mov_b32_e32 v60, v66
	v_mov_b32_e32 v61, v54
	v_pk_add_f32 v[58:59], v[60:61], v[58:59]
	v_mov_b32_e32 v54, v67
	v_pk_add_f32 v[54:55], v[54:55], v[58:59]
	v_mov_b32_e32 v58, v64
	v_mov_b32_e32 v59, v52
	v_pk_mul_f32 v[62:63], v[36:37], v[36:37]
	v_pk_add_f32 v[54:55], v[58:59], v[54:55]
	v_mov_b32_e32 v52, v65
	v_pk_add_f32 v[52:53], v[52:53], v[54:55]
	v_mov_b32_e32 v54, v62
	v_mov_b32_e32 v55, v50
	v_pk_mul_f32 v[56:57], v[34:35], v[34:35]
	v_pk_add_f32 v[52:53], v[54:55], v[52:53]
	v_mov_b32_e32 v50, v63
	v_pk_add_f32 v[50:51], v[50:51], v[52:53]
	v_mov_b32_e32 v52, v56
	v_mov_b32_e32 v53, v32
	v_pk_add_f32 v[50:51], v[52:53], v[50:51]
	v_mov_b32_e32 v32, v57
	v_pk_add_f32 v[32:33], v[32:33], v[50:51]
	ds_bpermute_b32 v51, v177, v33
	ds_bpermute_b32 v50, v177, v32
	v_mov_b32_e32 v52, 0
	v_mov_b32_e32 v53, v52
	v_mov_b32_e32 v54, v52
	v_mov_b32_e32 v55, v52
	s_waitcnt lgkmcnt(0)
; #define LAS __attribute__((address_space(3)))
; __device__ __forceinline__ unsigned pk2(float lo, float hi) { const f32x2_t v = {lo, hi}; return __builtin_bit_cast(unsigned, __builtin_convertvector(v, bf16x2_t)); }
; __device__ __forceinline__ float shx(float v, int o, int lane) { return __builtin_bit_cast(float, __builtin_amdgcn_ds_bpermute((lane ^ o) << 2, __builtin_bit_cast(int, v))); }
; __device__ __forceinline__ void phase_ac(const Params& p, Frame& F, int l) {
;     ...
;                 ss += shx(ss, 16, F.lane); ss += shx(ss, 32, F.lane);
;                 const float r = rsqrtf(ss * (1.0f / HD) + EPS) * (0.125f * LOG2E);
; #pragma unroll
;                 for (int ds = 0; ds < 2; ++ds) { v4u o; o.x = pk2(f[8 * ds + 0] * r * qa[ds][0].x, f[8 * ds + 1] * r * qa[ds][0].y); o.y = pk2(f[8 * ds + 2] * r * qa[ds][0].z, f[8 * ds + 3] * r * qa[ds][0].w);
;                     o.z = pk2(f[8 * ds + 4] * r * qa[ds][1].x, f[8 * ds + 5] * r * qa[ds][1].y); o.w = pk2(f[8 * ds + 6] * r * qa[ds][1].z, f[8 * ds + 7] * r * qa[ds][1].w);
;                     qf[q2][ds] = __builtin_bit_cast(bf16x8, o); } }
;             f32x4 osum[2]; f32x4 oacc[4][2];
; #pragma unroll
;             for (int q2 = 0; q2 < 2; ++q2) { osum[q2] = (f32x4){0.f, 0.f, 0.f, 0.f};
; #pragma unroll
;                 for (int db = 0; db < 4; ++db) oacc[db][q2] = (f32x4){0.f, 0.f, 0.f, 0.f}; }
; #pragma unroll 1
;             for (int c = th; c < th + 5; ++c) {
;                 bf16x8 kf[4][2];
; #pragma unroll
;                 for (int kb = 0; kb < 4; ++kb)
; #pragma unroll
;                     for (int ds = 0; ds < 2; ++ds) kf[kb][ds] = *(const LAS bf16x8*)(Kimg + (64 * c + 16 * kb + ql) * AT_KP + (32 * ds + 8 * g4) * 2);
;                 bf16x8 pf[2][2];
; #pragma unroll
;                 for (int q2 = 0; q2 < 2; ++q2) { const int q0 = th * 64 + 32 * qh + 16 * q2, qoff = q0 + ql;
;                     f32x4 sacc[4];
;                     const bool full = (64 * c - 143 - q0 >= -128) && (64 * c - 65 - q0 <= 128) && (n * 128 + 64 * c - 128 >= 0) && (n * 128 + 64 * c - 65 < S);
;                     if (full) { const LAS float* bp = bt + (64 * c + 4 * g4 - qoff);
	v_pk_add_f32 v[32:33], v[32:33], v[50:51]
	ds_bpermute_b32 v51, v178, v33
	ds_bpermute_b32 v50, v178, v32
	v_mov_b32_e32 v64, v52
	v_mov_b32_e32 v65, v52
	v_mov_b32_e32 v66, v52
	v_mov_b32_e32 v67, v52
	s_waitcnt lgkmcnt(0)
	v_pk_add_f32 v[32:33], v[32:33], v[50:51]
	v_mov_b32_e32 v56, v52
	v_pk_fma_f32 v[32:33], v[32:33], s[42:43], v[240:241] op_sel_hi:[1,0,0]
	v_mov_b32_e32 v57, v52
	v_mul_f32_e32 v50, 0x4b800000, v33
	v_cmp_gt_f32_e32 vcc, s2, v32
	v_cmp_gt_f32_e64 s[2:3], s2, v33
	v_mov_b32_e32 v58, v52
	v_mov_b32_e32 v59, v52
	v_cndmask_b32_e64 v33, v33, v50, s[2:3]
	v_rsq_f32_e32 v33, v33
	v_mov_b32_e32 v68, v52
	v_mov_b32_e32 v69, v52
	v_mov_b32_e32 v70, v52
	v_mul_f32_e32 v50, 0x45800000, v33
	v_cndmask_b32_e64 v33, v33, v50, s[2:3]
	v_mul_f32_e32 v50, 0x3e38aa3b, v33
	v_pk_mul_f32 v[22:23], v[50:51], v[22:23] op_sel_hi:[0,1]
	v_pk_mul_f32 v[24:25], v[50:51], v[24:25] op_sel_hi:[0,1]
	v_pk_mul_f32 v[22:23], v[12:13], v[22:23]
	v_pk_mul_f32 v[24:25], v[14:15], v[24:25]
	v_cvt_pk_bf16_f32 v22, v22, v23
	v_cvt_pk_bf16_f32 v23, v24, v25
	v_mul_f32_e32 v24, 0x4b800000, v32
	v_cndmask_b32_e32 v24, v32, v24, vcc
	v_rsq_f32_e32 v24, v24
	v_pk_mul_f32 v[20:21], v[50:51], v[20:21] op_sel_hi:[0,1]
	v_pk_mul_f32 v[26:27], v[50:51], v[26:27] op_sel_hi:[0,1]
	v_pk_mul_f32 v[20:21], v[8:9], v[20:21]
	v_mul_f32_e32 v25, 0x45800000, v24
	v_cndmask_b32_e32 v24, v24, v25, vcc
	v_pk_mul_f32 v[26:27], v[10:11], v[26:27]
	v_mul_f32_e32 v32, 0x3e38aa3b, v24
	v_pk_mul_f32 v[18:19], v[50:51], v[18:19] op_sel_hi:[0,1]
	v_pk_mul_f32 v[28:29], v[50:51], v[28:29] op_sel_hi:[0,1]
	v_cvt_pk_bf16_f32 v20, v20, v21
	v_cvt_pk_bf16_f32 v21, v26, v27
	v_pk_mul_f32 v[24:25], v[32:33], v[48:49] op_sel_hi:[0,1]
	v_pk_mul_f32 v[26:27], v[32:33], v[46:47] op_sel_hi:[0,1]
	v_pk_mul_f32 v[18:19], v[4:5], v[18:19]
	v_pk_mul_f32 v[28:29], v[6:7], v[28:29]
	v_pk_mul_f32 v[24:25], v[0:1], v[24:25]
	v_pk_mul_f32 v[26:27], v[2:3], v[26:27]
	v_pk_mul_f32 v[16:17], v[50:51], v[16:17] op_sel_hi:[0,1]
	v_pk_mul_f32 v[30:31], v[50:51], v[30:31] op_sel_hi:[0,1]
	v_cvt_pk_bf16_f32 v18, v18, v19
	v_cvt_pk_bf16_f32 v19, v28, v29
	v_cvt_pk_bf16_f32 v24, v24, v25
	v_cvt_pk_bf16_f32 v25, v26, v27
	v_pk_mul_f32 v[26:27], v[32:33], v[44:45] op_sel_hi:[0,1]
	v_pk_mul_f32 v[28:29], v[32:33], v[42:43] op_sel_hi:[0,1]
	v_pk_mul_f32 v[16:17], v[0:1], v[16:17]
	v_pk_mul_f32 v[30:31], v[2:3], v[30:31]
	v_pk_mul_f32 v[26:27], v[4:5], v[26:27]
	v_pk_mul_f32 v[28:29], v[6:7], v[28:29]
	v_cvt_pk_bf16_f32 v16, v16, v17
	v_cvt_pk_bf16_f32 v17, v30, v31
	v_cvt_pk_bf16_f32 v26, v26, v27
	v_cvt_pk_bf16_f32 v27, v28, v29
	v_pk_mul_f32 v[28:29], v[32:33], v[40:41] op_sel_hi:[0,1]
	v_pk_mul_f32 v[30:31], v[32:33], v[38:39] op_sel_hi:[0,1]
	v_pk_mul_f32 v[28:29], v[8:9], v[28:29]
	v_pk_mul_f32 v[30:31], v[10:11], v[30:31]
	v_cvt_pk_bf16_f32 v28, v28, v29
	v_cvt_pk_bf16_f32 v29, v30, v31
	v_pk_mul_f32 v[30:31], v[32:33], v[36:37] op_sel_hi:[0,1]
	v_pk_mul_f32 v[32:33], v[32:33], v[34:35] op_sel_hi:[0,1]
	v_pk_mul_f32 v[30:31], v[12:13], v[30:31]
	v_pk_mul_f32 v[32:33], v[14:15], v[32:33]
	v_cvt_pk_bf16_f32 v30, v30, v31
	v_cvt_pk_bf16_f32 v31, v32, v33
	v_add_u32_e32 v32, s14, v156
	s_or_b32 s2, s14, s22
	v_lshlrev_b32_e32 v33, 2, v32
	s_or_b32 s25, s2, 0x80
	s_or_b32 s27, s2, 0x90
	s_or_b32 s28, s2, 15
	s_or_b32 s29, s2, 31
	v_sub_u32_e32 v197, v186, v33
	v_sub_u32_e32 v198, v140, v32
	v_mov_b32_e32 v44, v52
	v_mov_b32_e32 v45, v52
	v_mov_b32_e32 v46, v52
	v_mov_b32_e32 v47, v52
	v_mov_b32_e32 v36, v52
	v_mov_b32_e32 v37, v52
	v_mov_b32_e32 v38, v52
	v_mov_b32_e32 v39, v52
	v_mov_b32_e32 v48, v52
	v_mov_b32_e32 v49, v52
	v_mov_b32_e32 v50, v52
	v_mov_b32_e32 v51, v52
	v_mov_b32_e32 v32, v52
	v_mov_b32_e32 v33, v52
	v_mov_b32_e32 v34, v52
	v_mov_b32_e32 v35, v52
	v_mov_b32_e32 v40, v52
	v_mov_b32_e32 v41, v52
	v_mov_b32_e32 v42, v52
	v_mov_b32_e32 v43, v52
	v_mov_b32_e32 v71, v52
	v_mov_b32_e32 v60, v52
	v_mov_b32_e32 v61, v52
	v_mov_b32_e32 v62, v52
	v_mov_b32_e32 v63, v52
	s_branch .LBB0_339

; #define LAS __attribute__((address_space(3)))
; __device__ __forceinline__ void phase_ac(const Params& p, Frame& F, int l) {
;     ...
;             for (int c = th; c < th + 5; ++c) {
;                 bf16x8 kf[4][2];
; #pragma unroll
;                 for (int kb = 0; kb < 4; ++kb)
; #pragma unroll
;                     for (int ds = 0; ds < 2; ++ds) kf[kb][ds] = *(const LAS bf16x8*)(Kimg + (64 * c + 16 * kb + ql) * AT_KP + (32 * ds + 8 * g4) * 2);
;                 bf16x8 pf[2][2];
; #pragma unroll
;                 for (int q2 = 0; q2 < 2; ++q2) { const int q0 = th * 64 + 32 * qh + 16 * q2, qoff = q0 + ql;
;                     f32x4 sacc[4];
;                     const bool full = (64 * c - 143 - q0 >= -128) && (64 * c - 65 - q0 <= 128) && (n * 128 + 64 * c - 128 >= 0) && (n * 128 + 64 * c - 65 < S);
;                     if (full) { const LAS float* bp = bt + (64 * c + 4 * g4 - qoff);
; #pragma unroll
;                         for (int kb = 0; kb < 4; ++kb) sacc[kb] = (f32x4){bp[16 * kb], bp[16 * kb + 1], bp[16 * kb + 2], bp[16 * kb + 3]};
.LBB0_339:
	v_add_u32_e32 v72, 0, v200
	ds_read_b128 v[100:103], v72
	ds_read_b128 v[96:99], v72 offset:64
	ds_read_b128 v[92:95], v72 offset:2304
	ds_read_b128 v[88:91], v72 offset:2368
	ds_read_b128 v[84:87], v72 offset:4608
	ds_read_b128 v[80:83], v72 offset:4672
	ds_read_b128 v[76:79], v72 offset:6912
	ds_read_b128 v[72:75], v72 offset:6976
	s_add_i32 s38, s22, s34
	s_add_i32 s2, s24, s34
	s_add_i32 s39, s38, 0xffffffbf
	s_addk_i32 s2, 0xff80
	s_cmpk_gt_u32 s2, 0x1fc0
	s_cselect_b64 s[14:15], -1, 0
	s_cmp_lt_u32 s38, s28
	s_cselect_b64 s[2:3], -1, 0
	s_cmp_gt_i32 s39, s25
	s_cselect_b64 s[40:41], -1, 0
	s_or_b64 s[2:3], s[2:3], s[40:41]
	s_mov_b64 s[2:3], s[14:15]
	s_andn2_b64 vcc, exec, s[2:3]
	s_mov_b64 s[2:3], -1
	s_cbranch_vccz .LBB0_341
	v_add_u32_e32 v112, 0, v197
	v_add_u32_e32 v104, 0x1c800, v112
	v_add_u32_e32 v106, 0x1c808, v112
	v_add_u32_e32 v108, 0x1c840, v112
	v_add_u32_e32 v110, 0x1c848, v112
	v_add_u32_e32 v113, 0x1c880, v112
	v_add_u32_e32 v114, 0x1c888, v112
	v_add_u32_e32 v116, 0x1c8c0, v112
	v_add_u32_e32 v118, 0x1c8c8, v112
	ds_read2_b32 v[104:105], v104 offset1:1
	ds_read2_b32 v[106:107], v106 offset1:1
	ds_read2_b32 v[108:109], v108 offset1:1
	ds_read2_b32 v[110:111], v110 offset1:1
	ds_read2_b32 v[112:113], v113 offset1:1
	ds_read2_b32 v[114:115], v114 offset1:1
	ds_read2_b32 v[116:117], v116 offset1:1
	ds_read2_b32 v[118:119], v118 offset1:1
	s_mov_b64 s[2:3], 0

; #define LAS __attribute__((address_space(3)))
; #define MFMA16(a, b, c) __builtin_amdgcn_mfma_f32_16x16x32_bf16((a), (b), (c), 0, 0, 0)
; __device__ __forceinline__ void phase_ac(const Params& p, Frame& F, int l) {
;     ...
;                 for (int q2 = 0; q2 < 2; ++q2) { const int q0 = th * 64 + 32 * qh + 16 * q2, qoff = q0 + ql;
;                     f32x4 sacc[4];
;                     const bool full = (64 * c - 143 - q0 >= -128) && (64 * c - 65 - q0 <= 128) && (n * 128 + 64 * c - 128 >= 0) && (n * 128 + 64 * c - 65 < S);
;                     if (full) { const LAS float* bp = bt + (64 * c + 4 * g4 - qoff);
; #pragma unroll
;                         for (int kb = 0; kb < 4; ++kb) sacc[kb] = (f32x4){bp[16 * kb], bp[16 * kb + 1], bp[16 * kb + 2], bp[16 * kb + 3]};
;                     } else {
; #pragma unroll
;                         for (int kb = 0; kb < 4; ++kb)
; #pragma unroll
;                             for (int j = 0; j < 4; ++j) { const int koff = 64 * c + 16 * kb + 4 * g4 + j - 128; const int rel = koff - qoff; const int kpos = n * 128 + koff;
;                                 const bool ok = ((unsigned)(rel + 128) <= 256u) && (kpos >= 0) && (kpos < S);
;                                 sacc[kb][j] = ok ? bt[ok ? rel + 128 : 0] : -1e30f; } }
;                     float pv[4][4];
; #pragma unroll
;                     for (int kb = 0; kb < 4; ++kb) { f32x4 a = MFMA16(kf[kb][0], qf[q2][0], sacc[kb]); a = MFMA16(kf[kb][1], qf[q2][1], a);
.LBB0_375:
	s_waitcnt lgkmcnt(6)
	v_mfma_f32_16x16x32_bf16 v[104:107], v[100:103], v[16:19], v[104:107]
	s_cmp_lt_u32 s38, s29
	s_cselect_b64 s[2:3], -1, 0
	s_cmp_gt_i32 s39, s27
	v_mfma_f32_16x16x32_bf16 v[128:131], v[96:99], v[20:23], v[104:107]
	s_cselect_b64 s[38:39], -1, 0
	s_or_b64 s[2:3], s[2:3], s[38:39]
	s_nop 0
	s_waitcnt lgkmcnt(4)
	v_mfma_f32_16x16x32_bf16 v[104:107], v[92:95], v[16:19], v[108:111]
	s_mov_b64 s[2:3], -1
	s_and_b64 vcc, exec, s[14:15]
	v_mfma_f32_16x16x32_bf16 v[124:127], v[88:91], v[20:23], v[104:107]
	s_waitcnt lgkmcnt(2)
	v_mfma_f32_16x16x32_bf16 v[104:107], v[84:87], v[16:19], v[112:115]
	v_mfma_f32_16x16x32_bf16 v[120:123], v[80:83], v[20:23], v[104:107]
	s_waitcnt lgkmcnt(0)
	v_mfma_f32_16x16x32_bf16 v[104:107], v[76:79], v[16:19], v[116:119]
	v_mfma_f32_16x16x32_bf16 v[108:111], v[72:75], v[20:23], v[104:107]
	s_cbranch_vccnz .LBB0_377
	s_nop 0
	v_add_u32_e32 v116, 0, v197
	s_nop 3
	v_add_u32_e32 v104, 0x1c7c0, v116
	v_add_u32_e32 v106, 0x1c7c8, v116
	v_add_u32_e32 v112, 0x1c800, v116
	v_add_u32_e32 v114, 0x1c808, v116
	v_add_u32_e32 v117, 0x1c840, v116
	v_add_u32_e32 v118, 0x1c848, v116
	v_add_u32_e32 v132, 0x1c880, v116
	v_add_u32_e32 v134, 0x1c888, v116
	ds_read2_b32 v[104:105], v104 offset1:1
	ds_read2_b32 v[106:107], v106 offset1:1
	ds_read2_b32 v[112:113], v112 offset1:1
	ds_read2_b32 v[114:115], v114 offset1:1
	ds_read2_b32 v[116:117], v117 offset1:1
	ds_read2_b32 v[118:119], v118 offset1:1
	ds_read2_b32 v[132:133], v132 offset1:1
	ds_read2_b32 v[134:135], v134 offset1:1
	s_mov_b64 s[2:3], 0

; #define GAS __attribute__((address_space(1)))
; #define LAS __attribute__((address_space(3)))
; __device__ __forceinline__ void phase_fb(const Params& p, Frame& F) {
;     ...
;         const bf16* src = TA + ((size_t)(b * 32 + u) * 256) * 1024 + cq * 256;
; #pragma unroll 4
;         for (int i = 0; i < 16; ++i) { const int q = F.tid + 512 * i, row = q >> 5, c32 = q & 31;
;             const v4u v = *(const GAS v4u*)(src + (size_t)row * 1024 + c32 * 8);
;             *(LAS v4u*)(F.lds + (c32 >> 4) * 65536 + off_b(row, c32 & 15)) = v; }
.LBB0_416:
	v_mov_b32_e32 v8, v147
	v_ashrrev_i32_e32 v6, 5, v8
	v_ashrrev_i32_e32 v7, 31, v6
	v_lshlrev_b64 v[2:3], 11, v[6:7]
	v_lshl_add_u64 v[2:3], v[0:1], 0, v[2:3]
	global_load_dwordx4 v[10:13], v[2:3], off
	v_lshlrev_b32_e32 v9, 2, v6
	v_lshlrev_b32_e32 v7, 8, v6
	v_and_b32_e32 v9, 12, v9
	v_bfe_u32 v6, v6, 2, 2
	v_bitop3_b32 v6, v9, v156, v6 bitop3:0x36
	v_lshlrev_b32_e32 v6, 4, v6
	v_add3_u32 v74, v171, v6, v7
	v_add_u32_e32 v8, 0x200, v147
	v_ashrrev_i32_e32 v6, 5, v8
	v_ashrrev_i32_e32 v7, 31, v6
	v_lshlrev_b64 v[2:3], 11, v[6:7]
	v_lshl_add_u64 v[2:3], v[0:1], 0, v[2:3]
	global_load_dwordx4 v[14:17], v[2:3], off
	v_lshlrev_b32_e32 v9, 2, v6
	v_lshlrev_b32_e32 v7, 8, v6
	v_and_b32_e32 v9, 12, v9
	v_bfe_u32 v6, v6, 2, 2
	v_bitop3_b32 v6, v9, v156, v6 bitop3:0x36
	v_lshlrev_b32_e32 v6, 4, v6
	v_add3_u32 v75, v171, v6, v7
	v_add_u32_e32 v8, 0x400, v147
	v_ashrrev_i32_e32 v6, 5, v8
	v_ashrrev_i32_e32 v7, 31, v6
	v_lshlrev_b64 v[2:3], 11, v[6:7]
	v_lshl_add_u64 v[2:3], v[0:1], 0, v[2:3]
	global_load_dwordx4 v[18:21], v[2:3], off
	v_lshlrev_b32_e32 v9, 2, v6
	v_lshlrev_b32_e32 v7, 8, v6
	v_and_b32_e32 v9, 12, v9
	v_bfe_u32 v6, v6, 2, 2
	v_bitop3_b32 v6, v9, v156, v6 bitop3:0x36
	v_lshlrev_b32_e32 v6, 4, v6
	v_add3_u32 v76, v171, v6, v7
	v_add_u32_e32 v8, 0x600, v147
	v_ashrrev_i32_e32 v6, 5, v8
	v_ashrrev_i32_e32 v7, 31, v6
	v_lshlrev_b64 v[2:3], 11, v[6:7]
	v_lshl_add_u64 v[2:3], v[0:1], 0, v[2:3]
	global_load_dwordx4 v[22:25], v[2:3], off
	v_lshlrev_b32_e32 v9, 2, v6
	v_lshlrev_b32_e32 v7, 8, v6
	v_and_b32_e32 v9, 12, v9
	v_bfe_u32 v6, v6, 2, 2
	v_bitop3_b32 v6, v9, v156, v6 bitop3:0x36
	v_lshlrev_b32_e32 v6, 4, v6
	v_add3_u32 v77, v171, v6, v7
	v_add_u32_e32 v8, 0x800, v147
	v_ashrrev_i32_e32 v6, 5, v8
	v_ashrrev_i32_e32 v7, 31, v6
	v_lshlrev_b64 v[2:3], 11, v[6:7]
	v_lshl_add_u64 v[2:3], v[0:1], 0, v[2:3]
	global_load_dwordx4 v[26:29], v[2:3], off
	v_lshlrev_b32_e32 v9, 2, v6
	v_lshlrev_b32_e32 v7, 8, v6
	v_and_b32_e32 v9, 12, v9
	v_bfe_u32 v6, v6, 2, 2
	v_bitop3_b32 v6, v9, v156, v6 bitop3:0x36
	v_lshlrev_b32_e32 v6, 4, v6
	v_add3_u32 v78, v171, v6, v7
	v_add_u32_e32 v8, 0xa00, v147
	v_ashrrev_i32_e32 v6, 5, v8
	v_ashrrev_i32_e32 v7, 31, v6
	v_lshlrev_b64 v[2:3], 11, v[6:7]
	v_lshl_add_u64 v[2:3], v[0:1], 0, v[2:3]
	global_load_dwordx4 v[30:33], v[2:3], off
	v_lshlrev_b32_e32 v9, 2, v6
	v_lshlrev_b32_e32 v7, 8, v6
	v_and_b32_e32 v9, 12, v9
	v_bfe_u32 v6, v6, 2, 2
	v_bitop3_b32 v6, v9, v156, v6 bitop3:0x36
	v_lshlrev_b32_e32 v6, 4, v6
	v_add3_u32 v79, v171, v6, v7
	v_add_u32_e32 v8, 0xc00, v147
	v_ashrrev_i32_e32 v6, 5, v8
	v_ashrrev_i32_e32 v7, 31, v6
	v_lshlrev_b64 v[2:3], 11, v[6:7]
	v_lshl_add_u64 v[2:3], v[0:1], 0, v[2:3]
	global_load_dwordx4 v[34:37], v[2:3], off
	v_lshlrev_b32_e32 v9, 2, v6
	v_lshlrev_b32_e32 v7, 8, v6
	v_and_b32_e32 v9, 12, v9
	v_bfe_u32 v6, v6, 2, 2
	v_bitop3_b32 v6, v9, v156, v6 bitop3:0x36
	v_lshlrev_b32_e32 v6, 4, v6
	v_add3_u32 v80, v171, v6, v7
	v_add_u32_e32 v8, 0xe00, v147
	v_ashrrev_i32_e32 v6, 5, v8
	v_ashrrev_i32_e32 v7, 31, v6
	v_lshlrev_b64 v[2:3], 11, v[6:7]
	v_lshl_add_u64 v[2:3], v[0:1], 0, v[2:3]
	global_load_dwordx4 v[38:41], v[2:3], off
	v_lshlrev_b32_e32 v9, 2, v6
	v_lshlrev_b32_e32 v7, 8, v6
	v_and_b32_e32 v9, 12, v9
	v_bfe_u32 v6, v6, 2, 2
	v_bitop3_b32 v6, v9, v156, v6 bitop3:0x36
	v_lshlrev_b32_e32 v6, 4, v6
	v_add3_u32 v81, v171, v6, v7
	v_add_u32_e32 v8, 0x1000, v147
	v_ashrrev_i32_e32 v6, 5, v8
	v_ashrrev_i32_e32 v7, 31, v6
	v_lshlrev_b64 v[2:3], 11, v[6:7]
	v_lshl_add_u64 v[2:3], v[0:1], 0, v[2:3]
	global_load_dwordx4 v[42:45], v[2:3], off
	v_lshlrev_b32_e32 v9, 2, v6
	v_lshlrev_b32_e32 v7, 8, v6
	v_and_b32_e32 v9, 12, v9
	v_bfe_u32 v6, v6, 2, 2
	v_bitop3_b32 v6, v9, v156, v6 bitop3:0x36
	v_lshlrev_b32_e32 v6, 4, v6
	v_add3_u32 v82, v171, v6, v7
	v_add_u32_e32 v8, 0x1200, v147
	v_ashrrev_i32_e32 v6, 5, v8
	v_ashrrev_i32_e32 v7, 31, v6
	v_lshlrev_b64 v[2:3], 11, v[6:7]
	v_lshl_add_u64 v[2:3], v[0:1], 0, v[2:3]
	global_load_dwordx4 v[46:49], v[2:3], off
	v_lshlrev_b32_e32 v9, 2, v6
	v_lshlrev_b32_e32 v7, 8, v6
	v_and_b32_e32 v9, 12, v9
	v_bfe_u32 v6, v6, 2, 2
	v_bitop3_b32 v6, v9, v156, v6 bitop3:0x36
	v_lshlrev_b32_e32 v6, 4, v6
	v_add3_u32 v83, v171, v6, v7
	v_add_u32_e32 v8, 0x1400, v147
	v_ashrrev_i32_e32 v6, 5, v8
	v_ashrrev_i32_e32 v7, 31, v6
	v_lshlrev_b64 v[2:3], 11, v[6:7]
	v_lshl_add_u64 v[2:3], v[0:1], 0, v[2:3]
	global_load_dwordx4 v[50:53], v[2:3], off
	v_lshlrev_b32_e32 v9, 2, v6
	v_lshlrev_b32_e32 v7, 8, v6
	v_and_b32_e32 v9, 12, v9
	v_bfe_u32 v6, v6, 2, 2
	v_bitop3_b32 v6, v9, v156, v6 bitop3:0x36
	v_lshlrev_b32_e32 v6, 4, v6
	v_add3_u32 v84, v171, v6, v7
	v_add_u32_e32 v8, 0x1600, v147
	v_ashrrev_i32_e32 v6, 5, v8
	v_ashrrev_i32_e32 v7, 31, v6
	v_lshlrev_b64 v[2:3], 11, v[6:7]
	v_lshl_add_u64 v[2:3], v[0:1], 0, v[2:3]
	global_load_dwordx4 v[54:57], v[2:3], off
	v_lshlrev_b32_e32 v9, 2, v6
	v_lshlrev_b32_e32 v7, 8, v6
	v_and_b32_e32 v9, 12, v9
	v_bfe_u32 v6, v6, 2, 2
	v_bitop3_b32 v6, v9, v156, v6 bitop3:0x36
	v_lshlrev_b32_e32 v6, 4, v6
	v_add3_u32 v85, v171, v6, v7
	v_add_u32_e32 v8, 0x1800, v147
	v_ashrrev_i32_e32 v6, 5, v8
	v_ashrrev_i32_e32 v7, 31, v6
	v_lshlrev_b64 v[2:3], 11, v[6:7]
	v_lshl_add_u64 v[2:3], v[0:1], 0, v[2:3]
	global_load_dwordx4 v[58:61], v[2:3], off
	v_lshlrev_b32_e32 v9, 2, v6
	v_lshlrev_b32_e32 v7, 8, v6
	v_and_b32_e32 v9, 12, v9
	v_bfe_u32 v6, v6, 2, 2
	v_bitop3_b32 v6, v9, v156, v6 bitop3:0x36
	v_lshlrev_b32_e32 v6, 4, v6
	v_add3_u32 v86, v171, v6, v7
	v_add_u32_e32 v8, 0x1a00, v147
	v_ashrrev_i32_e32 v6, 5, v8
	v_ashrrev_i32_e32 v7, 31, v6
	v_lshlrev_b64 v[2:3], 11, v[6:7]
	v_lshl_add_u64 v[2:3], v[0:1], 0, v[2:3]
	global_load_dwordx4 v[62:65], v[2:3], off
	v_lshlrev_b32_e32 v9, 2, v6
	v_lshlrev_b32_e32 v7, 8, v6
	v_and_b32_e32 v9, 12, v9
	v_bfe_u32 v6, v6, 2, 2
	v_bitop3_b32 v6, v9, v156, v6 bitop3:0x36
	v_lshlrev_b32_e32 v6, 4, v6
	v_add3_u32 v87, v171, v6, v7
	v_add_u32_e32 v8, 0x1c00, v147
	v_ashrrev_i32_e32 v6, 5, v8
	v_ashrrev_i32_e32 v7, 31, v6
	v_lshlrev_b64 v[2:3], 11, v[6:7]
	v_lshl_add_u64 v[2:3], v[0:1], 0, v[2:3]
	global_load_dwordx4 v[66:69], v[2:3], off
	v_lshlrev_b32_e32 v9, 2, v6
	v_lshlrev_b32_e32 v7, 8, v6
	v_and_b32_e32 v9, 12, v9
	v_bfe_u32 v6, v6, 2, 2
	v_bitop3_b32 v6, v9, v156, v6 bitop3:0x36
	v_lshlrev_b32_e32 v6, 4, v6
	v_add3_u32 v88, v171, v6, v7
	v_add_u32_e32 v8, 0x1e00, v147
	v_ashrrev_i32_e32 v6, 5, v8
	v_ashrrev_i32_e32 v7, 31, v6
	v_lshlrev_b64 v[2:3], 11, v[6:7]
	v_lshl_add_u64 v[2:3], v[0:1], 0, v[2:3]
	global_load_dwordx4 v[70:73], v[2:3], off
	v_lshlrev_b32_e32 v9, 2, v6
	v_lshlrev_b32_e32 v7, 8, v6
	v_and_b32_e32 v9, 12, v9
	v_bfe_u32 v6, v6, 2, 2
	v_bitop3_b32 v6, v9, v156, v6 bitop3:0x36
	v_lshlrev_b32_e32 v6, 4, v6
	v_add3_u32 v89, v171, v6, v7
	s_waitcnt vmcnt(15)
; #define GAS __attribute__((address_space(1)))
; #define LAS __attribute__((address_space(3)))
; __device__ __forceinline__ unsigned lds_addr(LAS void* p) { return (unsigned)(size_t)p; }
; __device__ __forceinline__ void phase_fb(const Params& p, Frame& F) {
;     ...
;         const bf16* src = TA + ((size_t)(b * 32 + u) * 256) * 1024 + cq * 256;
; #pragma unroll 4
;         for (int i = 0; i < 16; ++i) { const int q = F.tid + 512 * i, row = q >> 5, c32 = q & 31;
;             const v4u v = *(const GAS v4u*)(src + (size_t)row * 1024 + c32 * 8);
;             *(LAS v4u*)(F.lds + (c32 >> 4) * 65536 + off_b(row, c32 & 15)) = v; }
;         __syncthreads();
;         f32x4 acc[16][2];
; #pragma unroll
;         for (int cb = 0; cb < 16; ++cb) { acc[cb][0] = (f32x4){0.f, 0.f, 0.f, 0.f}; acc[cb][1] = (f32x4){0.f, 0.f, 0.f, 0.f}; }
;         const bf16* mrow = MBT + ((size_t)u * 256 + 32 * F.wave + ql) * 256 + 8 * g4;
;         const unsigned lbase = lds_addr(F.lds);
	ds_write_b128 v74, v[10:13]
	s_waitcnt vmcnt(14)
	ds_write_b128 v75, v[14:17]
	s_waitcnt vmcnt(13)
	ds_write_b128 v76, v[18:21]
	s_waitcnt vmcnt(12)
	ds_write_b128 v77, v[22:25]
	s_waitcnt vmcnt(11)
	ds_write_b128 v78, v[26:29]
	s_waitcnt vmcnt(10)
	ds_write_b128 v79, v[30:33]
	s_waitcnt vmcnt(9)
	ds_write_b128 v80, v[34:37]
	s_waitcnt vmcnt(8)
	ds_write_b128 v81, v[38:41]
	s_waitcnt vmcnt(7)
	ds_write_b128 v82, v[42:45]
	s_waitcnt vmcnt(6)
	ds_write_b128 v83, v[46:49]
	s_waitcnt vmcnt(5)
	ds_write_b128 v84, v[50:53]
	s_waitcnt vmcnt(4)
	ds_write_b128 v85, v[54:57]
	s_waitcnt vmcnt(3)
	ds_write_b128 v86, v[58:61]
	s_waitcnt vmcnt(2)
	ds_write_b128 v87, v[62:65]
	s_waitcnt vmcnt(1)
	ds_write_b128 v88, v[66:69]
	s_waitcnt vmcnt(0)
	ds_write_b128 v89, v[70:73]
	s_movk_i32 s2, 0x2000
	s_and_b32 s1, s1, 31
	s_lshl_b32 s34, s1, 8
	v_lshl_add_u64 v[0:1], v[138:139], 0, s[34:35]
	v_lshlrev_b64 v[0:1], 9, v[0:1]
	v_lshl_add_u64 v[142:143], v[136:137], 0, v[0:1]
	v_mov_b32_e32 v0, 0
	s_mov_b32 s1, 0
	v_mov_b32_e32 v190, v188
	v_mov_b32_e32 v1, v0
	v_mov_b32_e32 v2, v0
	v_mov_b32_e32 v3, v0
	v_mov_b32_e32 v32, v0
	v_mov_b32_e32 v33, v0
	v_mov_b32_e32 v34, v0
	v_mov_b32_e32 v35, v0
	v_mov_b32_e32 v4, v0
	v_mov_b32_e32 v5, v0
	v_mov_b32_e32 v6, v0
	v_mov_b32_e32 v7, v0
	v_mov_b32_e32 v40, v0
	v_mov_b32_e32 v41, v0
	v_mov_b32_e32 v42, v0
	v_mov_b32_e32 v43, v0
	v_mov_b32_e32 v8, v0
	v_mov_b32_e32 v9, v0
	v_mov_b32_e32 v10, v0
	v_mov_b32_e32 v11, v0
	v_mov_b32_e32 v48, v0
	v_mov_b32_e32 v49, v0
	v_mov_b32_e32 v50, v0
	v_mov_b32_e32 v51, v0
	v_mov_b32_e32 v12, v0
	v_mov_b32_e32 v13, v0
	v_mov_b32_e32 v14, v0
	v_mov_b32_e32 v15, v0
	v_mov_b32_e32 v56, v0
	v_mov_b32_e32 v57, v0
	v_mov_b32_e32 v58, v0
	v_mov_b32_e32 v59, v0
	v_mov_b32_e32 v16, v0
	v_mov_b32_e32 v17, v0
	v_mov_b32_e32 v18, v0
	v_mov_b32_e32 v19, v0
	v_mov_b32_e32 v64, v0
	v_mov_b32_e32 v65, v0
	v_mov_b32_e32 v66, v0
	v_mov_b32_e32 v67, v0
	v_mov_b32_e32 v20, v0
	v_mov_b32_e32 v21, v0
	v_mov_b32_e32 v22, v0
	v_mov_b32_e32 v23, v0
	v_mov_b32_e32 v72, v0
	v_mov_b32_e32 v73, v0
	v_mov_b32_e32 v74, v0
	v_mov_b32_e32 v75, v0
	v_mov_b32_e32 v24, v0
	v_mov_b32_e32 v25, v0
	v_mov_b32_e32 v26, v0
	v_mov_b32_e32 v27, v0
	v_mov_b32_e32 v80, v0
	v_mov_b32_e32 v81, v0
	v_mov_b32_e32 v82, v0
	v_mov_b32_e32 v83, v0
	v_mov_b32_e32 v28, v0
	v_mov_b32_e32 v29, v0
	v_mov_b32_e32 v30, v0
	v_mov_b32_e32 v31, v0
	v_mov_b32_e32 v88, v0
	v_mov_b32_e32 v89, v0
	v_mov_b32_e32 v90, v0
	v_mov_b32_e32 v91, v0
	v_mov_b32_e32 v36, v0
	v_mov_b32_e32 v37, v0
	v_mov_b32_e32 v38, v0
	v_mov_b32_e32 v39, v0
	v_mov_b32_e32 v96, v0
	v_mov_b32_e32 v97, v0
	v_mov_b32_e32 v98, v0
	v_mov_b32_e32 v99, v0
	v_mov_b32_e32 v44, v0
	v_mov_b32_e32 v45, v0
	v_mov_b32_e32 v46, v0
	v_mov_b32_e32 v47, v0
	v_mov_b32_e32 v100, v0
	v_mov_b32_e32 v101, v0
	v_mov_b32_e32 v102, v0
	v_mov_b32_e32 v103, v0
	v_mov_b32_e32 v52, v0
	v_mov_b32_e32 v53, v0
	v_mov_b32_e32 v54, v0
	v_mov_b32_e32 v55, v0
	v_mov_b32_e32 v104, v0
	v_mov_b32_e32 v105, v0
	v_mov_b32_e32 v106, v0
	v_mov_b32_e32 v107, v0
	v_mov_b32_e32 v60, v0
	v_mov_b32_e32 v61, v0
	v_mov_b32_e32 v62, v0
	v_mov_b32_e32 v63, v0
	v_mov_b32_e32 v108, v0
	v_mov_b32_e32 v109, v0
	v_mov_b32_e32 v110, v0
	v_mov_b32_e32 v111, v0
	v_mov_b32_e32 v68, v0
	v_mov_b32_e32 v69, v0
	v_mov_b32_e32 v70, v0
	v_mov_b32_e32 v71, v0
	v_mov_b32_e32 v112, v0
	v_mov_b32_e32 v113, v0
	v_mov_b32_e32 v114, v0
	v_mov_b32_e32 v115, v0
	v_mov_b32_e32 v76, v0
	v_mov_b32_e32 v77, v0
	v_mov_b32_e32 v78, v0
	v_mov_b32_e32 v79, v0
	v_mov_b32_e32 v116, v0
	v_mov_b32_e32 v117, v0
	v_mov_b32_e32 v118, v0
	v_mov_b32_e32 v119, v0
	v_mov_b32_e32 v84, v0
	v_mov_b32_e32 v85, v0
	v_mov_b32_e32 v86, v0
	v_mov_b32_e32 v87, v0
	v_mov_b32_e32 v120, v0
	v_mov_b32_e32 v121, v0
	v_mov_b32_e32 v122, v0
	v_mov_b32_e32 v123, v0
	v_mov_b32_e32 v92, v0
	v_mov_b32_e32 v93, v0
	v_mov_b32_e32 v94, v0
	v_mov_b32_e32 v95, v0
	v_mov_b32_e32 v124, v0
	v_mov_b32_e32 v125, v0
	v_mov_b32_e32 v126, v0
	v_mov_b32_e32 v127, v0
	s_waitcnt lgkmcnt(0)
	s_barrier

; __device__ __forceinline__ unsigned cvt_pk_bf16(float lo, float hi) { unsigned r; asm volatile("v_cvt_pk_bf16_f32 %0, %1, %2" : "=v"(r) : "v"(lo), "v"(hi)); return r; }
; #define PG8_GAS __attribute__((address_space(1)))
;     __device__ __forceinline__ void operator()(const f32x4 (&acc)[2][2][4][2], const Unit& u, int wr, int wc, int fr, int fq) const {
;         const int row0 = u.pm * BM + wr * 64 + fr, col0 = u.pn * BM + wc * 32 + 8 * fq;
;         const float* gp = g + (size_t)((u.pm * BM) >> 13) * 6144 + col0;
;         f32x4 gv[2][2];
; #pragma unroll
;         for (int bj = 0; bj < 2; ++bj)
; #pragma unroll
;             for (int n = 0; n < 2; ++n) gv[bj][n] = *(const PG8_GAS f32x4*)(gp + bj * HALF + n * 4);
; #pragma unroll
;         for (int ai = 0; ai < 2; ++ai)
; #pragma unroll
;             for (int m = 0; m < 4; ++m) { bf16_t* rowp = X + (size_t)(row0 + ai * HALF + m * 16) * 1024 + col0;
; #pragma unroll
;                 for (int bj = 0; bj < 2; ++bj) { PG8_GAS u32x4* p = (PG8_GAS u32x4*)(rowp + bj * HALF); const u32x4 xo = *p;
;                     const f32x4 a0 = acc[ai][bj][m][0] * gv[bj][0], a1 = acc[ai][bj][m][1] * gv[bj][1];
;                     u32x4 w; w.x = cvt_pk_bf16(__builtin_bit_cast(float, xo.x << 16) + a0[0], __builtin_bit_cast(float, xo.x & 0xffff0000u) + a0[1]);
;                     w.y = cvt_pk_bf16(__builtin_bit_cast(float, xo.y << 16) + a0[2], __builtin_bit_cast(float, xo.y & 0xffff0000u) + a0[3]);
;                     w.z = cvt_pk_bf16(__builtin_bit_cast(float, xo.z << 16) + a1[0], __builtin_bit_cast(float, xo.z & 0xffff0000u) + a1[1]);
;                     w.w = cvt_pk_bf16(__builtin_bit_cast(float, xo.w << 16) + a1[2], __builtin_bit_cast(float, xo.w & 0xffff0000u) + a1[3]);
;                     *p = w; } }
.LBB0_501:
	v_mbcnt_lo_u32_b32 v146, -1, 0
	v_mbcnt_hi_u32_b32 v146, -1, v146
	s_lshl_b32 s9, s47, 8
	s_lshl_b32 s13, s51, 8
	v_ashrrev_i32_e32 v40, 1, v146
	s_add_i32 s9, s9, s44
	s_or_b32 s13, s13, s45
	v_and_b32_e32 v40, -8, v40
	v_add_u32_e32 v148, s13, v40
	s_ashr_i32 s13, s47, 5
	v_and_or_b32 v174, v146, 15, s9
	s_mul_hi_i32 s19, s13, 0x6000
	s_mulk_i32 s13, 0x6000
	v_ashrrev_i32_e32 v175, 31, v174
	s_add_u32 s18, s34, s13
	v_ashrrev_i32_e32 v149, 31, v148
	v_lshlrev_b64 v[150:151], 11, v[174:175]
	s_addc_u32 s19, s43, s19
	v_lshl_add_u64 v[150:151], s[4:5], 0, v[150:151]
	v_lshlrev_b64 v[176:177], 1, v[148:149]
	v_lshl_add_u64 v[44:45], v[148:149], 2, s[18:19]
	v_lshl_add_u64 v[172:173], v[150:151], 0, v[176:177]
	global_load_dwordx4 v[56:59], v[44:45], off offset:16
	global_load_dwordx4 v[60:63], v[44:45], off
	global_load_dwordx4 v[40:43], v[44:45], off offset:528
	s_nop 0
	global_load_dwordx4 v[44:47], v[44:45], off offset:512
	s_mov_b32 s9, 0x40000
	v_add_co_u32_e32 v154, vcc, 0x8000, v172
	s_nop 1
	v_addc_co_u32_e32 v155, vcc, 0, v173, vcc
	v_add_co_u32_e32 v158, vcc, 0x10000, v172
	s_nop 1
	v_addc_co_u32_e32 v159, vcc, 0, v173, vcc
	v_add_co_u32_e32 v160, vcc, 0x18000, v172
	s_nop 1
	v_addc_co_u32_e32 v161, vcc, 0, v173, vcc
	v_add_co_u32_e32 v162, vcc, 0x40000, v172
	s_nop 1
	v_addc_co_u32_e32 v163, vcc, 0, v173, vcc
	v_add_co_u32_e32 v164, vcc, 0x48000, v172
	s_nop 1
	v_addc_co_u32_e32 v165, vcc, 0, v173, vcc
	v_add_co_u32_e32 v166, vcc, 0x50000, v172
	s_nop 1
	v_addc_co_u32_e32 v167, vcc, 0, v173, vcc
	v_add_co_u32_e32 v168, vcc, 0x58000, v172
	s_nop 1
	v_addc_co_u32_e32 v169, vcc, 0, v173, vcc
	global_load_dwordx4 v[180:183], v[172:173], off
	global_load_dwordx4 v[184:187], v[172:173], off offset:256
	global_load_dwordx4 v[188:191], v[154:155], off
	global_load_dwordx4 v[192:195], v[154:155], off offset:256
	global_load_dwordx4 v[196:199], v[158:159], off
	global_load_dwordx4 v[200:203], v[158:159], off offset:256
	global_load_dwordx4 v[204:207], v[160:161], off
	global_load_dwordx4 v[208:211], v[160:161], off offset:256
	s_mov_b64 s[18:19], 0x40000
	s_waitcnt vmcnt(7)
	v_pk_mul_f32 v[152:153], v[138:139], v[58:59]
	v_pk_mul_f32 v[140:141], v[140:141], v[60:61]
	v_pk_mul_f32 v[138:139], v[136:137], v[56:57]
	v_pk_mul_f32 v[142:143], v[142:143], v[62:63]
	v_pk_mul_f32 v[132:133], v[132:133], v[44:45]
	v_lshlrev_b32_e32 v136, 16, v180
	v_and_b32_e32 v137, 0xffff0000, v180
	v_add_f32_e32 v136, v140, v136
	v_add_f32_e32 v137, v141, v137
	v_cvt_pk_bf16_f32 v136, v136, v137
	v_lshlrev_b32_e32 v137, 16, v181
	v_and_b32_e32 v140, 0xffff0000, v181
	v_add_f32_e32 v137, v142, v137
	v_add_f32_e32 v140, v143, v140
	v_cvt_pk_bf16_f32 v137, v137, v140
	v_lshlrev_b32_e32 v140, 16, v182
	v_add_f32_e32 v138, v138, v140
	v_and_b32_e32 v140, 0xffff0000, v182
	v_add_f32_e32 v139, v139, v140
	v_cvt_pk_bf16_f32 v138, v138, v139
	v_lshlrev_b32_e32 v139, 16, v183
	v_add_f32_e32 v139, v152, v139
	v_and_b32_e32 v140, 0xffff0000, v183
	global_load_dwordx4 v[180:183], v[162:163], off
	v_add_f32_e32 v140, v153, v140
	v_cvt_pk_bf16_f32 v139, v139, v140
	global_store_dwordx4 v[172:173], v[136:139], off
	v_pk_mul_f32 v[140:141], v[130:131], v[42:43]
	v_pk_mul_f32 v[130:131], v[128:129], v[40:41]
	v_pk_mul_f32 v[134:135], v[134:135], v[46:47]
	v_pk_mul_f32 v[124:125], v[124:125], v[60:61]
	v_pk_mul_f32 v[126:127], v[126:127], v[62:63]
	v_pk_mul_f32 v[116:117], v[116:117], v[44:45]
	v_pk_mul_f32 v[118:119], v[118:119], v[46:47]
	v_pk_mul_f32 v[108:109], v[108:109], v[60:61]
	v_pk_mul_f32 v[110:111], v[110:111], v[62:63]
	v_pk_mul_f32 v[100:101], v[100:101], v[44:45]
	v_pk_mul_f32 v[102:103], v[102:103], v[46:47]
	v_pk_mul_f32 v[92:93], v[92:93], v[60:61]
	v_pk_mul_f32 v[94:95], v[94:95], v[62:63]
	v_pk_mul_f32 v[84:85], v[84:85], v[44:45]
	v_pk_mul_f32 v[86:87], v[86:87], v[46:47]
	v_pk_mul_f32 v[76:77], v[76:77], v[60:61]
	v_pk_mul_f32 v[78:79], v[78:79], v[62:63]
	v_pk_mul_f32 v[68:69], v[68:69], v[44:45]
	v_pk_mul_f32 v[70:71], v[70:71], v[46:47]
	v_pk_mul_f32 v[52:53], v[52:53], v[60:61]
	v_pk_mul_f32 v[54:55], v[54:55], v[62:63]
	v_pk_mul_f32 v[36:37], v[36:37], v[44:45]
	v_pk_mul_f32 v[38:39], v[38:39], v[46:47]
	v_pk_mul_f32 v[28:29], v[28:29], v[60:61]
	v_pk_mul_f32 v[30:31], v[30:31], v[62:63]
	v_pk_mul_f32 v[20:21], v[20:21], v[44:45]
	v_pk_mul_f32 v[22:23], v[22:23], v[46:47]
	v_pk_mul_f32 v[12:13], v[12:13], v[60:61]
	v_pk_mul_f32 v[14:15], v[14:15], v[62:63]
	v_pk_mul_f32 v[4:5], v[4:5], v[44:45]
	v_pk_mul_f32 v[6:7], v[6:7], v[46:47]
	s_waitcnt vmcnt(8)
	v_lshlrev_b32_e32 v128, 16, v184
	v_and_b32_e32 v129, 0xffff0000, v184
	v_add_f32_e32 v128, v132, v128
	v_add_f32_e32 v129, v133, v129
	v_cvt_pk_bf16_f32 v128, v128, v129
	v_lshlrev_b32_e32 v129, 16, v185
	v_and_b32_e32 v132, 0xffff0000, v185
	v_add_f32_e32 v129, v134, v129
	v_add_f32_e32 v132, v135, v132
	v_cvt_pk_bf16_f32 v129, v129, v132
	v_lshlrev_b32_e32 v132, 16, v186
	v_add_f32_e32 v130, v130, v132
	v_and_b32_e32 v132, 0xffff0000, v186
	v_add_f32_e32 v131, v131, v132
	v_cvt_pk_bf16_f32 v130, v130, v131
	v_lshlrev_b32_e32 v131, 16, v187
	v_add_f32_e32 v131, v140, v131
	v_and_b32_e32 v132, 0xffff0000, v187
	global_load_dwordx4 v[184:187], v[162:163], off offset:256
	v_add_f32_e32 v132, v141, v132
	v_cvt_pk_bf16_f32 v131, v131, v132
	global_store_dwordx4 v[172:173], v[128:131], off offset:256
	v_pk_mul_f32 v[134:135], v[122:123], v[58:59]
	v_pk_mul_f32 v[122:123], v[120:121], v[56:57]
	v_or_b32_e32 v128, 16, v174
	v_ashrrev_i32_e32 v129, 31, v128
	v_lshlrev_b64 v[128:129], 11, v[128:129]
	v_lshl_add_u64 v[128:129], s[4:5], 0, v[128:129]
	v_lshl_add_u64 v[132:133], v[128:129], 0, v[176:177]
	s_waitcnt vmcnt(9)
; __device__ __forceinline__ unsigned cvt_pk_bf16(float lo, float hi) { unsigned r; asm volatile("v_cvt_pk_bf16_f32 %0, %1, %2" : "=v"(r) : "v"(lo), "v"(hi)); return r; }
; #define PG8_GAS __attribute__((address_space(1)))
;     __device__ __forceinline__ void operator()(const f32x4 (&acc)[2][2][4][2], const Unit& u, int wr, int wc, int fr, int fq) const {
;     ...
;         for (int ai = 0; ai < 2; ++ai)
; #pragma unroll
;             for (int m = 0; m < 4; ++m) { bf16_t* rowp = X + (size_t)(row0 + ai * HALF + m * 16) * 1024 + col0;
; #pragma unroll
;                 for (int bj = 0; bj < 2; ++bj) { PG8_GAS u32x4* p = (PG8_GAS u32x4*)(rowp + bj * HALF); const u32x4 xo = *p;
;                     const f32x4 a0 = acc[ai][bj][m][0] * gv[bj][0], a1 = acc[ai][bj][m][1] * gv[bj][1];
;                     u32x4 w; w.x = cvt_pk_bf16(__builtin_bit_cast(float, xo.x << 16) + a0[0], __builtin_bit_cast(float, xo.x & 0xffff0000u) + a0[1]);
;                     w.y = cvt_pk_bf16(__builtin_bit_cast(float, xo.y << 16) + a0[2], __builtin_bit_cast(float, xo.y & 0xffff0000u) + a0[3]);
;                     w.z = cvt_pk_bf16(__builtin_bit_cast(float, xo.z << 16) + a1[0], __builtin_bit_cast(float, xo.z & 0xffff0000u) + a1[1]);
;                     w.w = cvt_pk_bf16(__builtin_bit_cast(float, xo.w << 16) + a1[2], __builtin_bit_cast(float, xo.w & 0xffff0000u) + a1[3]);
;                     *p = w; } }
	v_lshlrev_b32_e32 v120, 16, v188
	v_and_b32_e32 v121, 0xffff0000, v188
	v_add_f32_e32 v120, v124, v120
	v_add_f32_e32 v121, v125, v121
	v_cvt_pk_bf16_f32 v120, v120, v121
	v_lshlrev_b32_e32 v121, 16, v189
	v_and_b32_e32 v124, 0xffff0000, v189
	v_add_f32_e32 v121, v126, v121
	v_add_f32_e32 v124, v127, v124
	v_cvt_pk_bf16_f32 v121, v121, v124
	v_lshlrev_b32_e32 v124, 16, v190
	v_add_f32_e32 v122, v122, v124
	v_and_b32_e32 v124, 0xffff0000, v190
	v_add_f32_e32 v123, v123, v124
	v_cvt_pk_bf16_f32 v122, v122, v123
	v_lshlrev_b32_e32 v123, 16, v191
	v_add_f32_e32 v123, v134, v123
	v_and_b32_e32 v124, 0xffff0000, v191
	global_load_dwordx4 v[188:191], v[164:165], off
	v_add_f32_e32 v124, v135, v124
	v_cvt_pk_bf16_f32 v123, v123, v124
	global_store_dwordx4 v[132:133], v[120:123], off
	v_pk_mul_f32 v[124:125], v[114:115], v[42:43]
	v_pk_mul_f32 v[114:115], v[112:113], v[40:41]
	s_waitcnt vmcnt(10)
	v_lshlrev_b32_e32 v112, 16, v192
	v_and_b32_e32 v113, 0xffff0000, v192
	v_add_f32_e32 v112, v116, v112
	v_add_f32_e32 v113, v117, v113
	v_cvt_pk_bf16_f32 v112, v112, v113
	v_lshlrev_b32_e32 v113, 16, v193
	v_and_b32_e32 v116, 0xffff0000, v193
	v_add_f32_e32 v113, v118, v113
	v_add_f32_e32 v116, v119, v116
	v_cvt_pk_bf16_f32 v113, v113, v116
	v_lshlrev_b32_e32 v116, 16, v194
	v_add_f32_e32 v114, v114, v116
	v_and_b32_e32 v116, 0xffff0000, v194
	v_add_f32_e32 v115, v115, v116
	v_cvt_pk_bf16_f32 v114, v114, v115
	v_lshlrev_b32_e32 v115, 16, v195
	v_add_f32_e32 v115, v124, v115
	v_and_b32_e32 v116, 0xffff0000, v195
	global_load_dwordx4 v[192:195], v[164:165], off offset:256
	v_add_f32_e32 v116, v125, v116
	v_cvt_pk_bf16_f32 v115, v115, v116
	global_store_dwordx4 v[132:133], v[112:115], off offset:256
	v_pk_mul_f32 v[118:119], v[106:107], v[58:59]
	v_pk_mul_f32 v[106:107], v[104:105], v[56:57]
	v_or_b32_e32 v112, 32, v174
	v_ashrrev_i32_e32 v113, 31, v112
	v_lshlrev_b64 v[112:113], 11, v[112:113]
	v_lshl_add_u64 v[112:113], s[4:5], 0, v[112:113]
	v_lshl_add_u64 v[116:117], v[112:113], 0, v[176:177]
	s_waitcnt vmcnt(11)
	v_lshlrev_b32_e32 v104, 16, v196
	v_and_b32_e32 v105, 0xffff0000, v196
	v_add_f32_e32 v104, v108, v104
	v_add_f32_e32 v105, v109, v105
	v_cvt_pk_bf16_f32 v104, v104, v105
	v_lshlrev_b32_e32 v105, 16, v197
	v_and_b32_e32 v108, 0xffff0000, v197
	v_add_f32_e32 v105, v110, v105
	v_add_f32_e32 v108, v111, v108
	v_cvt_pk_bf16_f32 v105, v105, v108
	v_lshlrev_b32_e32 v108, 16, v198
	v_add_f32_e32 v106, v106, v108
	v_and_b32_e32 v108, 0xffff0000, v198
	v_add_f32_e32 v107, v107, v108
	v_cvt_pk_bf16_f32 v106, v106, v107
	v_lshlrev_b32_e32 v107, 16, v199
	v_add_f32_e32 v107, v118, v107
	v_and_b32_e32 v108, 0xffff0000, v199
	global_load_dwordx4 v[196:199], v[166:167], off
	v_add_f32_e32 v108, v119, v108
	v_cvt_pk_bf16_f32 v107, v107, v108
	global_store_dwordx4 v[116:117], v[104:107], off
	v_pk_mul_f32 v[108:109], v[98:99], v[42:43]
	v_pk_mul_f32 v[98:99], v[96:97], v[40:41]
	s_waitcnt vmcnt(12)
	v_lshlrev_b32_e32 v96, 16, v200
	v_and_b32_e32 v97, 0xffff0000, v200
	v_add_f32_e32 v96, v100, v96
	v_add_f32_e32 v97, v101, v97
	v_cvt_pk_bf16_f32 v96, v96, v97
	v_lshlrev_b32_e32 v97, 16, v201
	v_and_b32_e32 v100, 0xffff0000, v201
	v_add_f32_e32 v97, v102, v97
	v_add_f32_e32 v100, v103, v100
	v_cvt_pk_bf16_f32 v97, v97, v100
	v_lshlrev_b32_e32 v100, 16, v202
	v_add_f32_e32 v98, v98, v100
	v_and_b32_e32 v100, 0xffff0000, v202
	v_add_f32_e32 v99, v99, v100
	v_cvt_pk_bf16_f32 v98, v98, v99
	v_lshlrev_b32_e32 v99, 16, v203
	v_add_f32_e32 v99, v108, v99
	v_and_b32_e32 v100, 0xffff0000, v203
	global_load_dwordx4 v[200:203], v[166:167], off offset:256
	v_add_f32_e32 v100, v109, v100
	v_cvt_pk_bf16_f32 v99, v99, v100
	global_store_dwordx4 v[116:117], v[96:99], off offset:256
	v_pk_mul_f32 v[102:103], v[90:91], v[58:59]
	v_pk_mul_f32 v[90:91], v[88:89], v[56:57]
	v_or_b32_e32 v96, 48, v174
	v_ashrrev_i32_e32 v97, 31, v96
	v_lshlrev_b64 v[96:97], 11, v[96:97]
	v_lshl_add_u64 v[96:97], s[4:5], 0, v[96:97]
	v_lshl_add_u64 v[100:101], v[96:97], 0, v[176:177]
	s_waitcnt vmcnt(13)
	v_lshlrev_b32_e32 v88, 16, v204
	v_and_b32_e32 v89, 0xffff0000, v204
	v_add_f32_e32 v88, v92, v88
	v_add_f32_e32 v89, v93, v89
	v_cvt_pk_bf16_f32 v88, v88, v89
	v_lshlrev_b32_e32 v89, 16, v205
	v_and_b32_e32 v92, 0xffff0000, v205
	v_add_f32_e32 v89, v94, v89
	v_add_f32_e32 v92, v95, v92
	v_cvt_pk_bf16_f32 v89, v89, v92
	v_lshlrev_b32_e32 v92, 16, v206
	v_add_f32_e32 v90, v90, v92
	v_and_b32_e32 v92, 0xffff0000, v206
	v_add_f32_e32 v91, v91, v92
	v_cvt_pk_bf16_f32 v90, v90, v91
	v_lshlrev_b32_e32 v91, 16, v207
	v_add_f32_e32 v91, v102, v91
	v_and_b32_e32 v92, 0xffff0000, v207
	global_load_dwordx4 v[204:207], v[168:169], off
	v_add_f32_e32 v92, v103, v92
	v_cvt_pk_bf16_f32 v91, v91, v92
	global_store_dwordx4 v[100:101], v[88:91], off
	v_pk_mul_f32 v[92:93], v[82:83], v[42:43]
	v_pk_mul_f32 v[82:83], v[80:81], v[40:41]
	s_waitcnt vmcnt(14)
	v_lshlrev_b32_e32 v80, 16, v208
	v_and_b32_e32 v81, 0xffff0000, v208
	v_add_f32_e32 v80, v84, v80
	v_add_f32_e32 v81, v85, v81
	v_cvt_pk_bf16_f32 v80, v80, v81
	v_lshlrev_b32_e32 v81, 16, v209
	v_and_b32_e32 v84, 0xffff0000, v209
	v_add_f32_e32 v81, v86, v81
	v_add_f32_e32 v84, v87, v84
	v_cvt_pk_bf16_f32 v81, v81, v84
	v_lshlrev_b32_e32 v84, 16, v210
	v_add_f32_e32 v82, v82, v84
	v_and_b32_e32 v84, 0xffff0000, v210
	v_add_f32_e32 v83, v83, v84
	v_cvt_pk_bf16_f32 v82, v82, v83
	v_lshlrev_b32_e32 v83, 16, v211
	v_add_f32_e32 v83, v92, v83
	v_and_b32_e32 v84, 0xffff0000, v211
	global_load_dwordx4 v[208:211], v[168:169], off offset:256
	v_add_co_u32_e32 v86, vcc, s9, v172
	v_add_f32_e32 v84, v93, v84
	v_cvt_pk_bf16_f32 v83, v83, v84
	s_nop 0
	v_addc_co_u32_e32 v87, vcc, 0, v173, vcc
	global_store_dwordx4 v[100:101], v[80:83], off offset:256
	v_pk_mul_f32 v[88:89], v[74:75], v[58:59]
	v_pk_mul_f32 v[74:75], v[72:73], v[56:57]
	v_lshl_add_u64 v[80:81], v[172:173], 0, s[18:19]
	s_mov_b32 s9, 0x48000
	s_mov_b64 s[18:19], 0x48000
	s_waitcnt vmcnt(14)
; __device__ __forceinline__ unsigned cvt_pk_bf16(float lo, float hi) { unsigned r; asm volatile("v_cvt_pk_bf16_f32 %0, %1, %2" : "=v"(r) : "v"(lo), "v"(hi)); return r; }
; #define PG8_GAS __attribute__((address_space(1)))
;     __device__ __forceinline__ void operator()(const f32x4 (&acc)[2][2][4][2], const Unit& u, int wr, int wc, int fr, int fq) const {
;     ...
;         for (int ai = 0; ai < 2; ++ai)
; #pragma unroll
;             for (int m = 0; m < 4; ++m) { bf16_t* rowp = X + (size_t)(row0 + ai * HALF + m * 16) * 1024 + col0;
; #pragma unroll
;                 for (int bj = 0; bj < 2; ++bj) { PG8_GAS u32x4* p = (PG8_GAS u32x4*)(rowp + bj * HALF); const u32x4 xo = *p;
;                     const f32x4 a0 = acc[ai][bj][m][0] * gv[bj][0], a1 = acc[ai][bj][m][1] * gv[bj][1];
;                     u32x4 w; w.x = cvt_pk_bf16(__builtin_bit_cast(float, xo.x << 16) + a0[0], __builtin_bit_cast(float, xo.x & 0xffff0000u) + a0[1]);
;                     w.y = cvt_pk_bf16(__builtin_bit_cast(float, xo.y << 16) + a0[2], __builtin_bit_cast(float, xo.y & 0xffff0000u) + a0[3]);
;                     w.z = cvt_pk_bf16(__builtin_bit_cast(float, xo.z << 16) + a1[0], __builtin_bit_cast(float, xo.z & 0xffff0000u) + a1[1]);
;                     w.w = cvt_pk_bf16(__builtin_bit_cast(float, xo.w << 16) + a1[2], __builtin_bit_cast(float, xo.w & 0xffff0000u) + a1[3]);
;                     *p = w; } }
	v_lshlrev_b32_e32 v72, 16, v180
	v_and_b32_e32 v73, 0xffff0000, v180
	v_add_f32_e32 v72, v76, v72
	v_add_f32_e32 v73, v77, v73
	v_cvt_pk_bf16_f32 v72, v72, v73
	v_lshlrev_b32_e32 v73, 16, v181
	v_and_b32_e32 v76, 0xffff0000, v181
	v_add_f32_e32 v73, v78, v73
	v_add_f32_e32 v76, v79, v76
	v_cvt_pk_bf16_f32 v73, v73, v76
	v_lshlrev_b32_e32 v76, 16, v182
	v_add_f32_e32 v74, v74, v76
	v_and_b32_e32 v76, 0xffff0000, v182
	v_add_f32_e32 v75, v75, v76
	v_cvt_pk_bf16_f32 v74, v74, v75
	v_lshlrev_b32_e32 v75, 16, v183
	v_add_f32_e32 v75, v88, v75
	v_and_b32_e32 v76, 0xffff0000, v183
	v_add_f32_e32 v76, v89, v76
	v_cvt_pk_bf16_f32 v75, v75, v76
	global_store_dwordx4 v[86:87], v[72:75], off
	v_pk_mul_f32 v[76:77], v[66:67], v[42:43]
	v_pk_mul_f32 v[66:67], v[64:65], v[40:41]
	s_waitcnt vmcnt(13)
	v_lshlrev_b32_e32 v64, 16, v184
	v_and_b32_e32 v65, 0xffff0000, v184
	v_add_f32_e32 v64, v68, v64
	v_add_f32_e32 v65, v69, v65
	v_cvt_pk_bf16_f32 v64, v64, v65
	v_lshlrev_b32_e32 v65, 16, v185
	v_and_b32_e32 v68, 0xffff0000, v185
	v_add_f32_e32 v65, v70, v65
	v_add_f32_e32 v68, v71, v68
	v_cvt_pk_bf16_f32 v65, v65, v68
	v_lshlrev_b32_e32 v68, 16, v186
	v_add_f32_e32 v66, v66, v68
	v_and_b32_e32 v68, 0xffff0000, v186
	v_add_f32_e32 v67, v67, v68
	v_cvt_pk_bf16_f32 v66, v66, v67
	v_lshlrev_b32_e32 v67, 16, v187
	v_add_f32_e32 v67, v76, v67
	v_and_b32_e32 v68, 0xffff0000, v187
	v_add_co_u32_e32 v70, vcc, s9, v172
	v_add_f32_e32 v68, v77, v68
	v_cvt_pk_bf16_f32 v67, v67, v68
	s_nop 0
	v_addc_co_u32_e32 v71, vcc, 0, v173, vcc
	global_store_dwordx4 v[80:81], v[64:67], off offset:256
	v_pk_mul_f32 v[72:73], v[50:51], v[58:59]
	v_pk_mul_f32 v[50:51], v[48:49], v[56:57]
	v_lshl_add_u64 v[64:65], v[172:173], 0, s[18:19]
	s_mov_b32 s9, 0x50000
	s_mov_b64 s[18:19], 0x50000
	s_waitcnt vmcnt(12)
	v_lshlrev_b32_e32 v48, 16, v188
	v_and_b32_e32 v49, 0xffff0000, v188
	v_add_f32_e32 v48, v52, v48
	v_add_f32_e32 v49, v53, v49
	v_cvt_pk_bf16_f32 v48, v48, v49
	v_lshlrev_b32_e32 v49, 16, v189
	v_and_b32_e32 v52, 0xffff0000, v189
	v_add_f32_e32 v49, v54, v49
	v_add_f32_e32 v52, v55, v52
	v_cvt_pk_bf16_f32 v49, v49, v52
	v_lshlrev_b32_e32 v52, 16, v190
	v_add_f32_e32 v50, v50, v52
	v_and_b32_e32 v52, 0xffff0000, v190
	v_add_f32_e32 v51, v51, v52
	v_cvt_pk_bf16_f32 v50, v50, v51
	v_lshlrev_b32_e32 v51, 16, v191
	v_add_f32_e32 v51, v72, v51
	v_and_b32_e32 v52, 0xffff0000, v191
	v_add_f32_e32 v52, v73, v52
	v_cvt_pk_bf16_f32 v51, v51, v52
	global_store_dwordx4 v[70:71], v[48:51], off
	v_pk_mul_f32 v[52:53], v[34:35], v[42:43]
	v_pk_mul_f32 v[34:35], v[32:33], v[40:41]
	s_waitcnt vmcnt(11)
	v_lshlrev_b32_e32 v32, 16, v192
	v_and_b32_e32 v33, 0xffff0000, v192
	v_add_f32_e32 v32, v36, v32
	v_add_f32_e32 v33, v37, v33
	v_cvt_pk_bf16_f32 v32, v32, v33
	v_lshlrev_b32_e32 v33, 16, v193
	v_and_b32_e32 v36, 0xffff0000, v193
	v_add_f32_e32 v33, v38, v33
	v_add_f32_e32 v36, v39, v36
	v_cvt_pk_bf16_f32 v33, v33, v36
	v_lshlrev_b32_e32 v36, 16, v194
	v_add_f32_e32 v34, v34, v36
	v_and_b32_e32 v36, 0xffff0000, v194
	v_add_f32_e32 v35, v35, v36
	v_cvt_pk_bf16_f32 v34, v34, v35
	v_lshlrev_b32_e32 v35, 16, v195
	v_add_f32_e32 v35, v52, v35
	v_and_b32_e32 v36, 0xffff0000, v195
	v_add_co_u32_e32 v38, vcc, s9, v172
	v_add_f32_e32 v36, v53, v36
	v_cvt_pk_bf16_f32 v35, v35, v36
	s_nop 0
	v_addc_co_u32_e32 v39, vcc, 0, v173, vcc
	global_store_dwordx4 v[64:65], v[32:35], off offset:256
	v_pk_mul_f32 v[48:49], v[26:27], v[58:59]
	v_pk_mul_f32 v[26:27], v[24:25], v[56:57]
	v_lshl_add_u64 v[32:33], v[172:173], 0, s[18:19]
	s_mov_b32 s9, 0x58000
	s_mov_b64 s[18:19], 0x58000
	s_waitcnt vmcnt(10)
	v_lshlrev_b32_e32 v24, 16, v196
	v_and_b32_e32 v25, 0xffff0000, v196
	v_add_f32_e32 v24, v28, v24
	v_add_f32_e32 v25, v29, v25
	v_cvt_pk_bf16_f32 v24, v24, v25
	v_lshlrev_b32_e32 v25, 16, v197
	v_and_b32_e32 v28, 0xffff0000, v197
	v_add_f32_e32 v25, v30, v25
	v_add_f32_e32 v28, v31, v28
	v_cvt_pk_bf16_f32 v25, v25, v28
	v_lshlrev_b32_e32 v28, 16, v198
	v_add_f32_e32 v26, v26, v28
	v_and_b32_e32 v28, 0xffff0000, v198
	v_add_f32_e32 v27, v27, v28
	v_cvt_pk_bf16_f32 v26, v26, v27
	v_lshlrev_b32_e32 v27, 16, v199
	v_add_f32_e32 v27, v48, v27
	v_and_b32_e32 v28, 0xffff0000, v199
	v_add_f32_e32 v28, v49, v28
	v_cvt_pk_bf16_f32 v27, v27, v28
	global_store_dwordx4 v[38:39], v[24:27], off
	v_pk_mul_f32 v[28:29], v[18:19], v[42:43]
	v_pk_mul_f32 v[18:19], v[16:17], v[40:41]
	s_waitcnt vmcnt(9)
	v_lshlrev_b32_e32 v16, 16, v200
	v_and_b32_e32 v17, 0xffff0000, v200
	v_add_f32_e32 v16, v20, v16
	v_add_f32_e32 v17, v21, v17
	v_cvt_pk_bf16_f32 v16, v16, v17
	v_lshlrev_b32_e32 v17, 16, v201
	v_and_b32_e32 v20, 0xffff0000, v201
	v_add_f32_e32 v17, v22, v17
	v_add_f32_e32 v20, v23, v20
	v_cvt_pk_bf16_f32 v17, v17, v20
	v_lshlrev_b32_e32 v20, 16, v202
	v_add_f32_e32 v18, v18, v20
	v_and_b32_e32 v20, 0xffff0000, v202
	v_add_f32_e32 v19, v19, v20
	v_cvt_pk_bf16_f32 v18, v18, v19
	v_lshlrev_b32_e32 v19, 16, v203
	v_add_f32_e32 v19, v28, v19
	v_and_b32_e32 v20, 0xffff0000, v203
	v_add_co_u32_e32 v22, vcc, s9, v172
	v_add_f32_e32 v20, v29, v20
	v_cvt_pk_bf16_f32 v19, v19, v20
	s_nop 0
	v_addc_co_u32_e32 v23, vcc, 0, v173, vcc
	global_store_dwordx4 v[32:33], v[16:19], off offset:256
	v_pk_mul_f32 v[24:25], v[10:11], v[58:59]
	v_pk_mul_f32 v[10:11], v[8:9], v[56:57]
	v_lshl_add_u64 v[16:17], v[172:173], 0, s[18:19]
	s_mov_b64 s[18:19], -1
	s_andn2_b64 vcc, exec, s[36:37]
	s_waitcnt vmcnt(8)
	v_lshlrev_b32_e32 v8, 16, v204
	v_and_b32_e32 v9, 0xffff0000, v204
	v_add_f32_e32 v8, v12, v8
	v_add_f32_e32 v9, v13, v9
	v_cvt_pk_bf16_f32 v8, v8, v9
	v_lshlrev_b32_e32 v9, 16, v205
	v_and_b32_e32 v12, 0xffff0000, v205
	v_add_f32_e32 v9, v14, v9
	v_add_f32_e32 v12, v15, v12
	v_cvt_pk_bf16_f32 v9, v9, v12
	v_lshlrev_b32_e32 v12, 16, v206
	v_add_f32_e32 v10, v10, v12
	v_and_b32_e32 v12, 0xffff0000, v206
	v_add_f32_e32 v11, v11, v12
	v_cvt_pk_bf16_f32 v10, v10, v11
	v_lshlrev_b32_e32 v11, 16, v207
	v_add_f32_e32 v11, v24, v11
	v_and_b32_e32 v12, 0xffff0000, v207
	v_add_f32_e32 v12, v25, v12
	v_cvt_pk_bf16_f32 v11, v11, v12
	global_store_dwordx4 v[22:23], v[8:11], off
	v_pk_mul_f32 v[12:13], v[2:3], v[42:43]
	v_pk_mul_f32 v[2:3], v[0:1], v[40:41]
	s_waitcnt vmcnt(7)
	v_lshlrev_b32_e32 v0, 16, v208
	v_and_b32_e32 v1, 0xffff0000, v208
	v_add_f32_e32 v0, v4, v0
	v_add_f32_e32 v1, v5, v1
	v_cvt_pk_bf16_f32 v0, v0, v1
	v_lshlrev_b32_e32 v1, 16, v209
	v_and_b32_e32 v4, 0xffff0000, v209
	v_add_f32_e32 v1, v6, v1
	v_add_f32_e32 v4, v7, v4
	v_cvt_pk_bf16_f32 v1, v1, v4
	v_lshlrev_b32_e32 v4, 16, v210
	v_add_f32_e32 v2, v2, v4
	v_and_b32_e32 v4, 0xffff0000, v210
	v_add_f32_e32 v3, v3, v4
	v_cvt_pk_bf16_f32 v2, v2, v3
	v_lshlrev_b32_e32 v3, 16, v211
	v_add_f32_e32 v3, v12, v3
	v_and_b32_e32 v4, 0xffff0000, v211
	v_add_f32_e32 v4, v13, v4
	v_cvt_pk_bf16_f32 v3, v3, v4
	global_store_dwordx4 v[16:17], v[0:3], off offset:256
	s_cbranch_vccnz .LBB0_490
	s_andn2_b64 vcc, exec, s[2:3]
	s_cbranch_vccnz .LBB0_489
	s_barrier
	s_branch .LBB0_489

; #define GAS __attribute__((address_space(1)))
; #define LAS __attribute__((address_space(3)))
; __device__ __forceinline__ void cvt_load(const CvtItem& it, f32x4 (&v)[16], int lane) {
;     const int kr = lane >> 4, nc = (lane & 15) * 4;
; #pragma unroll
;     for (int i = 0; i < 16; ++i) v[i] = __builtin_nontemporal_load((const GAS f32x4*)(it.src + (size_t)(4 * i + kr) * it.N + nc));
; }
; __device__ __forceinline__ void cvt_moe_layer(const Params& p, Frame& F, int l, int w0, int nw, int iend) {
;     LAS float* scr = (LAS float*)(F.lds + F.wave * 16640);
;     if (w0 >= iend) return;
;     f32x4 va[16], vb[16];
;     CvtItem ca = moe_item(p, l, w0), cb = ca; cvt_load(ca, va, F.lane);
.LBB0_1279:
	v_ashrrev_i32_e32 v134, 4, v68
	v_add_u32_e32 v136, 60, v134
	v_lshlrev_b32_e32 v6, 2, v68
	v_add_u32_e32 v140, 56, v134
	v_add_u32_e32 v142, 52, v134
	v_add_u32_e32 v156, 48, v134
	v_add_u32_e32 v162, 44, v134
	v_add_u32_e32 v164, 40, v134
	v_add_u32_e32 v166, 36, v134
	v_add_u32_e32 v168, 32, v134
	v_add_u32_e32 v170, 28, v134
	v_add_u32_e32 v172, 24, v134
	v_add_u32_e32 v174, 20, v134
	v_add_u32_e32 v176, 16, v134
	v_add_u32_e32 v178, 12, v134
	v_add_u32_e32 v180, 8, v134
	v_add_u32_e32 v182, 4, v134
	v_mad_i64_i32 v[4:5], s[18:19], s16, v136, 0
	v_and_b32_e32 v138, 60, v6
	v_mad_i64_i32 v[6:7], s[18:19], s16, v140, 0
	v_mad_i64_i32 v[12:13], s[18:19], s16, v142, 0
	v_mad_i64_i32 v[14:15], s[18:19], s16, v156, 0
	v_mad_i64_i32 v[20:21], s[18:19], s16, v162, 0
	v_mad_i64_i32 v[22:23], s[18:19], s16, v164, 0
	v_mad_i64_i32 v[28:29], s[18:19], s16, v166, 0
	v_mad_i64_i32 v[30:31], s[18:19], s16, v168, 0
	v_mad_i64_i32 v[36:37], s[18:19], s16, v170, 0
	v_mad_i64_i32 v[38:39], s[18:19], s16, v172, 0
	v_mad_i64_i32 v[44:45], s[18:19], s16, v174, 0
	v_mad_i64_i32 v[46:47], s[18:19], s16, v176, 0
	v_mad_i64_i32 v[52:53], s[18:19], s16, v178, 0
	v_mad_i64_i32 v[54:55], s[18:19], s16, v180, 0
	v_mad_i64_i32 v[62:63], s[18:19], s16, v182, 0
	v_mad_i64_i32 v[64:65], s[16:17], s16, v134, 0
	v_lshl_add_u64 v[4:5], v[4:5], 2, v[60:61]
	v_lshlrev_b32_e32 v144, 2, v138
	v_lshl_add_u64 v[6:7], v[6:7], 2, v[60:61]
	v_lshl_add_u64 v[12:13], v[12:13], 2, v[60:61]
	v_lshl_add_u64 v[14:15], v[14:15], 2, v[60:61]
	v_lshl_add_u64 v[20:21], v[20:21], 2, v[60:61]
	v_lshl_add_u64 v[22:23], v[22:23], 2, v[60:61]
	v_lshl_add_u64 v[28:29], v[28:29], 2, v[60:61]
	v_lshl_add_u64 v[30:31], v[30:31], 2, v[60:61]
	v_lshl_add_u64 v[36:37], v[36:37], 2, v[60:61]
	v_lshl_add_u64 v[38:39], v[38:39], 2, v[60:61]
	v_lshl_add_u64 v[44:45], v[44:45], 2, v[60:61]
	v_lshl_add_u64 v[46:47], v[46:47], 2, v[60:61]
	v_lshl_add_u64 v[52:53], v[52:53], 2, v[60:61]
	v_lshl_add_u64 v[54:55], v[54:55], 2, v[60:61]
	v_lshl_add_u64 v[62:63], v[62:63], 2, v[60:61]
	v_lshl_add_u64 v[60:61], v[64:65], 2, v[60:61]
	v_lshl_add_u64 v[4:5], v[4:5], 0, v[144:145]
	v_lshl_add_u64 v[6:7], v[6:7], 0, v[144:145]
	v_lshl_add_u64 v[12:13], v[12:13], 0, v[144:145]
	v_lshl_add_u64 v[14:15], v[14:15], 0, v[144:145]
	v_lshl_add_u64 v[20:21], v[20:21], 0, v[144:145]
	v_lshl_add_u64 v[22:23], v[22:23], 0, v[144:145]
	v_lshl_add_u64 v[28:29], v[28:29], 0, v[144:145]
	v_lshl_add_u64 v[30:31], v[30:31], 0, v[144:145]
	v_lshl_add_u64 v[36:37], v[36:37], 0, v[144:145]
	v_lshl_add_u64 v[38:39], v[38:39], 0, v[144:145]
	v_lshl_add_u64 v[44:45], v[44:45], 0, v[144:145]
	v_lshl_add_u64 v[46:47], v[46:47], 0, v[144:145]
	v_lshl_add_u64 v[52:53], v[52:53], 0, v[144:145]
	v_lshl_add_u64 v[54:55], v[54:55], 0, v[144:145]
	v_lshl_add_u64 v[62:63], v[62:63], 0, v[144:145]
	v_lshl_add_u64 v[60:61], v[60:61], 0, v[144:145]
	global_load_dwordx4 v[8:11], v[4:5], off nt
	s_nop 0
	global_load_dwordx4 v[4:7], v[6:7], off nt
	s_nop 0
	global_load_dwordx4 v[16:19], v[12:13], off nt
	s_nop 0
	global_load_dwordx4 v[12:15], v[14:15], off nt
	s_nop 0
	global_load_dwordx4 v[24:27], v[20:21], off nt
	s_nop 0
	global_load_dwordx4 v[20:23], v[22:23], off nt
	s_nop 0
	global_load_dwordx4 v[32:35], v[28:29], off nt
	s_nop 0
	global_load_dwordx4 v[28:31], v[30:31], off nt
	s_nop 0
	global_load_dwordx4 v[40:43], v[36:37], off nt
	s_nop 0
	global_load_dwordx4 v[36:39], v[38:39], off nt
	s_nop 0
	global_load_dwordx4 v[48:51], v[44:45], off nt
	s_nop 0
	global_load_dwordx4 v[44:47], v[46:47], off nt
	s_nop 0
	global_load_dwordx4 v[56:59], v[52:53], off nt
	s_nop 0
	global_load_dwordx4 v[52:55], v[54:55], off nt
	s_nop 0
	global_load_dwordx4 v[64:67], v[62:63], off nt
	s_nop 0
	global_load_dwordx4 v[60:63], v[60:61], off nt
	v_ashrrev_i32_e32 v184, 3, v68
	v_lshlrev_b32_e32 v68, 3, v68
	s_mul_i32 s16, s42, 0x4100
	s_movk_i32 s17, 0x104
	v_and_b32_e32 v186, 56, v68
	s_add_i32 s16, s16, 0
	v_mul_lo_u32 v70, v134, s17
	v_mul_u32_u24_e32 v68, 0x104, v186
	v_lshlrev_b32_e32 v71, 2, v184
	s_lshl_b32 s17, s42, 1
	v_add_u32_e32 v69, s16, v144
	v_add3_u32 v167, s16, v68, v71
	v_add_u32_e32 v188, 8, v184
	v_add_u32_e32 v190, 16, v184
	v_add_u32_e32 v192, 24, v184
	v_add_u32_e32 v194, 32, v184
	v_add_u32_e32 v196, 40, v184
	v_add_u32_e32 v198, 48, v184
	v_add_u32_e32 v200, 56, v184
	s_lshl_b32 s16, s42, 6
	s_add_i32 s27, s62, s17
	s_lshl_b32 s17, s42, 2
	v_ashrrev_i32_e32 v135, 31, v184
	v_ashrrev_i32_e32 v137, 31, v188
	v_ashrrev_i32_e32 v139, 31, v190
	v_ashrrev_i32_e32 v141, 31, v192
	v_ashrrev_i32_e32 v143, 31, v194
	v_ashrrev_i32_e32 v147, 31, v196
	v_ashrrev_i32_e32 v163, 31, v198
	v_ashrrev_i32_e32 v165, 31, v200
	s_add_i32 s26, s57, s16
	s_add_i32 s28, s63, s17
	s_add_i32 s29, s64, s16
	v_add_u32_e32 v169, v69, v70
	s_mov_b64 s[16:17], s[14:15]
	s_mov_b32 s36, s25
	s_branch .LBB0_1281

; #define LAS __attribute__((address_space(3)))
; #define LDS_WAIT() asm volatile("s_waitcnt lgkmcnt(0)" ::: "memory")
; __device__ __forceinline__ void cvt_store(const CvtItem& it, const f32x4 (&v)[16], LAS float* scr, int lane) {
;     const int kr = lane >> 4, nc = (lane & 15) * 4;
; #pragma unroll
;     for (int i = 0; i < 16; ++i) { LAS float* p = scr + (4 * i + kr) * 65 + nc; p[0] = v[i].x; p[1] = v[i].y; p[2] = v[i].z; p[3] = v[i].w; }
;     LDS_WAIT(); asm volatile("" ::: "memory");
; __device__ __forceinline__ void cvt_moe_layer(const Params& p, Frame& F, int l, int w0, int nw, int iend) {
;     ...
;     for (int it = w0; it < iend; it += 2 * nw) {
;         const bool hb = it + nw < iend;
;         if (hb) { cb = moe_item(p, l, it + nw); cvt_load(cb, vb, F.lane); }
;         cvt_store(ca, va, scr, F.lane);
.LBB0_1287:
	v_mad_i64_i32 v[68:69], s[22:23], s20, v134, 0
	v_mad_i64_i32 v[70:71], s[22:23], s20, v182, 0
	v_mad_i64_i32 v[76:77], s[22:23], s20, v180, 0
	v_mad_i64_i32 v[78:79], s[22:23], s20, v178, 0
	v_mad_i64_i32 v[84:85], s[22:23], s20, v176, 0
	v_mad_i64_i32 v[86:87], s[22:23], s20, v174, 0
	v_mad_i64_i32 v[92:93], s[22:23], s20, v172, 0
	v_mad_i64_i32 v[94:95], s[22:23], s20, v170, 0
	v_mad_i64_i32 v[100:101], s[22:23], s20, v168, 0
	v_mad_i64_i32 v[102:103], s[22:23], s20, v166, 0
	v_mad_i64_i32 v[108:109], s[22:23], s20, v164, 0
	v_mad_i64_i32 v[110:111], s[22:23], s20, v162, 0
	v_mad_i64_i32 v[116:117], s[22:23], s20, v156, 0
	v_mad_i64_i32 v[118:119], s[22:23], s20, v142, 0
	v_mad_i64_i32 v[126:127], s[22:23], s20, v140, 0
	v_mad_i64_i32 v[128:129], s[20:21], s20, v136, 0
	v_lshl_add_u64 v[68:69], v[68:69], 2, v[124:125]
	v_lshlrev_b32_e32 v144, 2, v138
	v_lshl_add_u64 v[70:71], v[70:71], 2, v[124:125]
	v_lshl_add_u64 v[76:77], v[76:77], 2, v[124:125]
	v_lshl_add_u64 v[78:79], v[78:79], 2, v[124:125]
	v_lshl_add_u64 v[84:85], v[84:85], 2, v[124:125]
	v_lshl_add_u64 v[86:87], v[86:87], 2, v[124:125]
	v_lshl_add_u64 v[92:93], v[92:93], 2, v[124:125]
	v_lshl_add_u64 v[94:95], v[94:95], 2, v[124:125]
	v_lshl_add_u64 v[100:101], v[100:101], 2, v[124:125]
	v_lshl_add_u64 v[102:103], v[102:103], 2, v[124:125]
	v_lshl_add_u64 v[108:109], v[108:109], 2, v[124:125]
	v_lshl_add_u64 v[110:111], v[110:111], 2, v[124:125]
	v_lshl_add_u64 v[116:117], v[116:117], 2, v[124:125]
	v_lshl_add_u64 v[118:119], v[118:119], 2, v[124:125]
	v_lshl_add_u64 v[126:127], v[126:127], 2, v[124:125]
	v_lshl_add_u64 v[124:125], v[128:129], 2, v[124:125]
	v_lshl_add_u64 v[68:69], v[68:69], 0, v[144:145]
	v_lshl_add_u64 v[72:73], v[70:71], 0, v[144:145]
	v_lshl_add_u64 v[76:77], v[76:77], 0, v[144:145]
	v_lshl_add_u64 v[80:81], v[78:79], 0, v[144:145]
	v_lshl_add_u64 v[84:85], v[84:85], 0, v[144:145]
	v_lshl_add_u64 v[88:89], v[86:87], 0, v[144:145]
	v_lshl_add_u64 v[92:93], v[92:93], 0, v[144:145]
	v_lshl_add_u64 v[96:97], v[94:95], 0, v[144:145]
	v_lshl_add_u64 v[100:101], v[100:101], 0, v[144:145]
	v_lshl_add_u64 v[104:105], v[102:103], 0, v[144:145]
	v_lshl_add_u64 v[108:109], v[108:109], 0, v[144:145]
	v_lshl_add_u64 v[112:113], v[110:111], 0, v[144:145]
	v_lshl_add_u64 v[116:117], v[116:117], 0, v[144:145]
	v_lshl_add_u64 v[120:121], v[118:119], 0, v[144:145]
	v_lshl_add_u64 v[126:127], v[126:127], 0, v[144:145]
	v_lshl_add_u64 v[128:129], v[124:125], 0, v[144:145]
	global_load_dwordx4 v[68:71], v[68:69], off nt
	s_nop 0
	global_load_dwordx4 v[72:75], v[72:73], off nt
	s_nop 0
	global_load_dwordx4 v[76:79], v[76:77], off nt
	s_nop 0
	global_load_dwordx4 v[80:83], v[80:81], off nt
	s_nop 0
	global_load_dwordx4 v[84:87], v[84:85], off nt
	s_nop 0
	global_load_dwordx4 v[88:91], v[88:89], off nt
	s_nop 0
	global_load_dwordx4 v[92:95], v[92:93], off nt
	s_nop 0
	global_load_dwordx4 v[96:99], v[96:97], off nt
	s_nop 0
	global_load_dwordx4 v[100:103], v[100:101], off nt
	s_nop 0
	global_load_dwordx4 v[104:107], v[104:105], off nt
	s_nop 0
	global_load_dwordx4 v[108:111], v[108:109], off nt
	s_nop 0
	global_load_dwordx4 v[112:115], v[112:113], off nt
	s_nop 0
	global_load_dwordx4 v[116:119], v[116:117], off nt
	s_nop 0
	global_load_dwordx4 v[120:123], v[120:121], off nt
	s_nop 0
	global_load_dwordx4 v[124:127], v[126:127], off nt
	s_nop 0
	global_load_dwordx4 v[128:131], v[128:129], off nt
.LBB0_1288:
	v_add_u32_e32 v173, 0x410, v169
	v_add_u32_e32 v175, 0x418, v169
	v_add_u32_e32 v177, 0x820, v169
	v_add_u32_e32 v189, 0x828, v169
	v_add_u32_e32 v191, 0xc30, v169
	v_add_u32_e32 v193, 0xc38, v169
	v_add_u32_e32 v195, 0x1040, v169
	v_add_u32_e32 v197, 0x1048, v169
	v_add_u32_e32 v199, 0x1450, v169
	v_add_u32_e32 v201, 0x1458, v169
	v_add_u32_e32 v204, 0x1860, v169
	v_add_u32_e32 v205, 0x1868, v169
	v_add_u32_e32 v206, 0x1c70, v169
	v_add_u32_e32 v207, 0x1c78, v169
	v_add_u32_e32 v208, 0x2080, v169
	v_add_u32_e32 v209, 0x2088, v169
	v_add_u32_e32 v210, 0x2490, v169
	v_add_u32_e32 v211, 0x2498, v169
	v_add_u32_e32 v212, 0x28a0, v169
	v_add_u32_e32 v213, 0x28a8, v169
	v_add_u32_e32 v214, 0x2cb0, v169
	v_add_u32_e32 v215, 0x2cb8, v169
	v_add_u32_e32 v216, 0x30c0, v169
	v_add_u32_e32 v217, 0x30c8, v169
	v_add_u32_e32 v218, 0x34d0, v169
	v_add_u32_e32 v219, 0x34d8, v169
	v_add_u32_e32 v220, 0x38e0, v169
	v_add_u32_e32 v221, 0x38e8, v169
	v_add_u32_e32 v222, 0x3cf0, v169
	v_add_u32_e32 v223, 0x3cf8, v169
	s_waitcnt vmcnt(0)
	ds_write2_b32 v169, v60, v61 offset1:1
	ds_write2_b32 v169, v62, v63 offset0:2 offset1:3
	ds_write2_b32 v173, v64, v65 offset1:1
	ds_write2_b32 v175, v66, v67 offset1:1
	ds_write2_b32 v177, v52, v53 offset1:1
	ds_write2_b32 v189, v54, v55 offset1:1
	ds_write2_b32 v191, v56, v57 offset1:1
	ds_write2_b32 v193, v58, v59 offset1:1
	ds_write2_b32 v195, v44, v45 offset1:1
	ds_write2_b32 v197, v46, v47 offset1:1
	ds_write2_b32 v199, v48, v49 offset1:1
	ds_write2_b32 v201, v50, v51 offset1:1
	ds_write2_b32 v204, v36, v37 offset1:1
	ds_write2_b32 v205, v38, v39 offset1:1
	ds_write2_b32 v206, v40, v41 offset1:1
	ds_write2_b32 v207, v42, v43 offset1:1
	ds_write2_b32 v208, v28, v29 offset1:1
	ds_write2_b32 v209, v30, v31 offset1:1
	ds_write2_b32 v210, v32, v33 offset1:1
	ds_write2_b32 v211, v34, v35 offset1:1
	ds_write2_b32 v212, v20, v21 offset1:1
	ds_write2_b32 v213, v22, v23 offset1:1
	ds_write2_b32 v214, v24, v25 offset1:1
	ds_write2_b32 v215, v26, v27 offset1:1
	ds_write2_b32 v216, v12, v13 offset1:1
	ds_write2_b32 v217, v14, v15 offset1:1
	ds_write2_b32 v218, v16, v17 offset1:1
	ds_write2_b32 v219, v18, v19 offset1:1
	ds_write2_b32 v220, v4, v5 offset1:1
	ds_write2_b32 v221, v6, v7 offset1:1
	ds_write2_b32 v222, v8, v9 offset1:1
	ds_write2_b32 v223, v10, v11 offset1:1
	s_waitcnt lgkmcnt(0)
; #define GAS __attribute__((address_space(1)))
; #define LAS __attribute__((address_space(3)))
; #define LDS_WAIT() asm volatile("s_waitcnt lgkmcnt(0)" ::: "memory")
; __device__ __forceinline__ unsigned pk2(float lo, float hi) { const f32x2_t v = {lo, hi}; return __builtin_bit_cast(unsigned, __builtin_convertvector(v, bf16x2_t)); }
; __device__ __forceinline__ void cvt_store(const CvtItem& it, const f32x4 (&v)[16], LAS float* scr, int lane) {
;     ...
;     const int c = lane & 7;
; #pragma unroll
;     for (int j = 0; j < 8; ++j) { const int n = (lane >> 3) + 8 * j; const LAS float* s = scr + (8 * c) * 65 + n;
;         v4u o; o.x = pk2(s[0 * 65], s[1 * 65]); o.y = pk2(s[2 * 65], s[3 * 65]); o.z = pk2(s[4 * 65], s[5 * 65]); o.w = pk2(s[6 * 65], s[7 * 65]);
;         __builtin_nontemporal_store(o, (GAS v4u*)(it.dst + (size_t)n * it.ldk + 8 * c)); }
;     LDS_WAIT(); asm volatile("" ::: "memory");
; }
; __device__ __forceinline__ CvtItem moe_item(const Params& p, int l, int it) {
;     bf16* W1 = (bf16*)(p.ws + WS_W1) + (size_t)l * NE * 4096 * 1024; bf16* W2 = (bf16*)(p.ws + WS_W2) + (size_t)l * NE * 1024 * 2048;
;     const int kind = it >> 13, r = it & 8191; CvtItem ci;
;     if (kind < 2) { const int e = r >> 9, kt = (r >> 5) & 15, ntile = r & 31; const int n0 = ntile * 64, k0 = kt * 64;
;         ci.src = (kind ? p.in[IN_WU] : p.in[IN_WG]) + (size_t)l * NE * D * DE + (size_t)e * D * DE + (size_t)k0 * DE + n0; ci.N = DE;
;         ci.dst = W1 + ((size_t)e * 4096 + (size_t)(n0 >> 7) * 256 + kind * 128 + (n0 & 127)) * 1024 + k0; ci.ldk = 1024;
;     } else { const int e = r >> 9, kt = (r >> 4) & 31, ntile = r & 15; const int n0 = ntile * 64, k0 = kt * 64;
;         ci.src = p.in[IN_WD] + (size_t)l * NE * DE * D + (size_t)e * DE * D + (size_t)k0 * D + n0; ci.N = D;
;         ci.dst = W2 + ((size_t)e * 1024 + n0) * 2048 + k0; ci.ldk = 2048; }
	v_add_u32_e32 v171, 0x400, v167
	ds_read2_b32 v[152:153], v167 offset0:65 offset1:73
	ds_read2_b32 v[154:155], v167 offset1:8
	ds_read2_b32 v[158:159], v167 offset0:130 offset1:138
	ds_read2_b32 v[160:161], v167 offset0:195 offset1:203
	ds_read2_b32 v[224:225], v171 offset0:4 offset1:12
	ds_read2_b32 v[226:227], v171 offset0:69 offset1:77
	ds_read2_b32 v[228:229], v171 offset0:134 offset1:142
	ds_read2_b32 v[230:231], v171 offset0:199 offset1:207
	v_mad_u64_u32 v[232:233], s[20:21], s36, v184, 0
	v_mov_b32_e32 v146, v233
	v_lshlrev_b32_e32 v144, 1, v186
	v_mad_u64_u32 v[234:235], s[20:21], s36, v135, v[146:147]
	v_lshl_add_u64 v[202:203], s[16:17], 0, v[144:145]
	v_mov_b32_e32 v233, v234
	s_waitcnt lgkmcnt(6)
	v_cvt_pk_bf16_f32 v148, v154, v152
	s_waitcnt lgkmcnt(4)
	v_cvt_pk_bf16_f32 v149, v158, v160
	s_waitcnt lgkmcnt(2)
	v_cvt_pk_bf16_f32 v150, v224, v226
	s_waitcnt lgkmcnt(0)
	v_cvt_pk_bf16_f32 v151, v228, v230
	v_lshl_add_u64 v[232:233], v[232:233], 1, v[202:203]
	global_store_dwordx4 v[232:233], v[148:151], off nt
	v_mad_u64_u32 v[232:233], s[20:21], s36, v190, 0
	s_nop 0
	v_cvt_pk_bf16_f32 v148, v155, v153
	v_mad_u64_u32 v[152:153], s[20:21], s36, v188, 0
	v_mov_b32_e32 v146, v153
	v_mad_u64_u32 v[154:155], s[20:21], s36, v137, v[146:147]
	v_mov_b32_e32 v153, v154
	v_cvt_pk_bf16_f32 v149, v159, v161
	v_cvt_pk_bf16_f32 v150, v225, v227
	v_cvt_pk_bf16_f32 v151, v229, v231
	v_lshl_add_u64 v[152:153], v[152:153], 1, v[202:203]
	global_store_dwordx4 v[152:153], v[148:151], off nt
	ds_read2_b32 v[152:153], v167 offset0:16 offset1:24
	ds_read2_b32 v[154:155], v167 offset0:81 offset1:89
	ds_read2_b32 v[158:159], v167 offset0:146 offset1:154
	ds_read2_b32 v[160:161], v167 offset0:211 offset1:219
	ds_read2_b32 v[224:225], v171 offset0:20 offset1:28
	ds_read2_b32 v[226:227], v171 offset0:85 offset1:93
	ds_read2_b32 v[228:229], v171 offset0:150 offset1:158
	ds_read2_b32 v[230:231], v171 offset0:215 offset1:223
	v_mov_b32_e32 v146, v233
	v_mad_u64_u32 v[234:235], s[20:21], s36, v139, v[146:147]
	v_mov_b32_e32 v233, v234
	s_waitcnt lgkmcnt(6)
	v_cvt_pk_bf16_f32 v148, v152, v154
	s_waitcnt lgkmcnt(4)
	v_cvt_pk_bf16_f32 v149, v158, v160
	s_waitcnt lgkmcnt(2)
	v_cvt_pk_bf16_f32 v150, v224, v226
	s_waitcnt lgkmcnt(0)
	v_cvt_pk_bf16_f32 v151, v228, v230
	v_lshl_add_u64 v[232:233], v[232:233], 1, v[202:203]
	global_store_dwordx4 v[232:233], v[148:151], off nt
	v_mad_u64_u32 v[232:233], s[20:21], s36, v194, 0
	s_nop 0
	v_cvt_pk_bf16_f32 v148, v153, v155
	v_mad_u64_u32 v[152:153], s[20:21], s36, v192, 0
	v_mov_b32_e32 v146, v153
	v_mad_u64_u32 v[154:155], s[20:21], s36, v141, v[146:147]
	v_mov_b32_e32 v153, v154
	v_cvt_pk_bf16_f32 v149, v159, v161
	v_cvt_pk_bf16_f32 v150, v225, v227
	v_cvt_pk_bf16_f32 v151, v229, v231
	v_lshl_add_u64 v[152:153], v[152:153], 1, v[202:203]
	global_store_dwordx4 v[152:153], v[148:151], off nt
	ds_read2_b32 v[152:153], v167 offset0:32 offset1:40
	ds_read2_b32 v[154:155], v167 offset0:97 offset1:105
	ds_read2_b32 v[158:159], v167 offset0:162 offset1:170
	ds_read2_b32 v[160:161], v167 offset0:227 offset1:235
	ds_read2_b32 v[224:225], v171 offset0:36 offset1:44
	ds_read2_b32 v[226:227], v171 offset0:101 offset1:109
	ds_read2_b32 v[228:229], v171 offset0:166 offset1:174
	ds_read2_b32 v[230:231], v171 offset0:231 offset1:239
	v_mov_b32_e32 v146, v233
	v_mad_u64_u32 v[234:235], s[20:21], s36, v143, v[146:147]
	v_mov_b32_e32 v233, v234
	s_waitcnt lgkmcnt(6)
	v_cvt_pk_bf16_f32 v148, v152, v154
	s_waitcnt lgkmcnt(4)
	v_cvt_pk_bf16_f32 v149, v158, v160
	s_waitcnt lgkmcnt(2)
	v_cvt_pk_bf16_f32 v150, v224, v226
	s_waitcnt lgkmcnt(0)
	v_cvt_pk_bf16_f32 v151, v228, v230
	v_lshl_add_u64 v[232:233], v[232:233], 1, v[202:203]
	global_store_dwordx4 v[232:233], v[148:151], off nt
	v_mad_u64_u32 v[232:233], s[20:21], s36, v198, 0
	s_nop 0
	v_cvt_pk_bf16_f32 v148, v153, v155
	v_mad_u64_u32 v[152:153], s[20:21], s36, v196, 0
	v_mov_b32_e32 v146, v153
	v_mad_u64_u32 v[154:155], s[20:21], s36, v147, v[146:147]
	v_mov_b32_e32 v153, v154
	v_cvt_pk_bf16_f32 v149, v159, v161
	v_cvt_pk_bf16_f32 v150, v225, v227
	v_cvt_pk_bf16_f32 v151, v229, v231
	v_lshl_add_u64 v[152:153], v[152:153], 1, v[202:203]
	global_store_dwordx4 v[152:153], v[148:151], off nt
	ds_read2_b32 v[152:153], v167 offset0:48 offset1:56
	ds_read2_b32 v[154:155], v167 offset0:113 offset1:121
	ds_read2_b32 v[158:159], v167 offset0:178 offset1:186
	ds_read2_b32 v[160:161], v167 offset0:243 offset1:251
	ds_read2_b32 v[224:225], v171 offset0:52 offset1:60
	ds_read2_b32 v[226:227], v171 offset0:117 offset1:125
	ds_read2_b32 v[228:229], v171 offset0:182 offset1:190
	ds_read2_b32 v[230:231], v171 offset0:247 offset1:255
	v_mov_b32_e32 v146, v233
	v_mad_u64_u32 v[234:235], s[20:21], s36, v163, v[146:147]
	v_mov_b32_e32 v233, v234
	s_waitcnt lgkmcnt(6)
	v_cvt_pk_bf16_f32 v148, v152, v154
	s_waitcnt lgkmcnt(4)
	v_cvt_pk_bf16_f32 v149, v158, v160
	s_waitcnt lgkmcnt(2)
	v_cvt_pk_bf16_f32 v150, v224, v226
	s_waitcnt lgkmcnt(0)
	v_cvt_pk_bf16_f32 v151, v228, v230
	v_lshl_add_u64 v[232:233], v[232:233], 1, v[202:203]
	global_store_dwordx4 v[232:233], v[148:151], off nt
	s_nop 1
	v_cvt_pk_bf16_f32 v148, v153, v155
	v_mad_u64_u32 v[152:153], s[20:21], s36, v200, 0
	v_mov_b32_e32 v146, v153
	v_mad_u64_u32 v[154:155], s[20:21], s36, v165, v[146:147]
	v_mov_b32_e32 v153, v154
	v_cvt_pk_bf16_f32 v149, v159, v161
	v_cvt_pk_bf16_f32 v150, v225, v227
	v_cvt_pk_bf16_f32 v151, v229, v231
	v_lshl_add_u64 v[152:153], v[152:153], 1, v[202:203]
	global_store_dwordx4 v[152:153], v[148:151], off nt
	v_readlane_b32 s20, v253, 16
	s_waitcnt lgkmcnt(0)
	s_add_i32 s24, s24, s20
	s_cmp_ge_i32 s24, s33
	s_cselect_b64 s[20:21], -1, 0
	s_and_b64 vcc, exec, s[20:21]
	s_cbranch_vccnz .LBB0_1295
	v_readlane_b32 s16, v254, 15
	s_ashr_i32 s36, s24, 13
	s_bfe_u32 s38, s24, 0x40009
	s_add_i32 s37, s16, s26
	s_cmp_gt_i32 s36, 1
	s_cbranch_scc0 .LBB0_1292
	v_readlane_b32 s17, v254, 9
	s_add_i32 s17, s17, s28
	s_and_b32 s17, s17, 0x7c0
	s_lshl_b32 s34, s38, 23
	s_and_b32 s16, s37, 0x3c0
	v_lshl_add_u64 v[4:5], v[132:133], 0, s[34:35]
	s_lshl_b32 s34, s17, 12
	v_lshl_add_u64 v[4:5], v[4:5], 0, s[34:35]
	s_lshl_b32 s34, s16, 2
	s_lshl_b32 s22, s38, 22
	s_add_u32 s22, s53, s22
	s_addc_u32 s23, s54, 0
	s_lshl_b32 s16, s16, 12
	s_add_u32 s16, s22, s16
	s_addc_u32 s22, s23, 0
	s_lshl_b32 s17, s17, 1
	s_add_u32 s16, s16, s17
	v_lshl_add_u64 v[4:5], v[4:5], 0, s[34:35]
	s_addc_u32 s17, s22, 0
	s_cbranch_execz .LBB0_1293
	s_movk_i32 s36, 0x800
	s_mov_b64 s[22:23], 0x400
	s_branch .LBB0_1294

; #define GAS __attribute__((address_space(1)))
; __device__ __forceinline__ void cvt_load(const CvtItem& it, f32x4 (&v)[16], int lane) {
;     const int kr = lane >> 4, nc = (lane & 15) * 4;
; #pragma unroll
;     for (int i = 0; i < 16; ++i) v[i] = __builtin_nontemporal_load((const GAS f32x4*)(it.src + (size_t)(4 * i + kr) * it.N + nc));
; }
; __device__ __forceinline__ CvtItem moe_item(const Params& p, int l, int it) {
;     bf16* W1 = (bf16*)(p.ws + WS_W1) + (size_t)l * NE * 4096 * 1024; bf16* W2 = (bf16*)(p.ws + WS_W2) + (size_t)l * NE * 1024 * 2048;
;     const int kind = it >> 13, r = it & 8191; CvtItem ci;
;     if (kind < 2) { const int e = r >> 9, kt = (r >> 5) & 15, ntile = r & 31; const int n0 = ntile * 64, k0 = kt * 64;
;         ci.src = (kind ? p.in[IN_WU] : p.in[IN_WG]) + (size_t)l * NE * D * DE + (size_t)e * D * DE + (size_t)k0 * DE + n0; ci.N = DE;
;         ci.dst = W1 + ((size_t)e * 4096 + (size_t)(n0 >> 7) * 256 + kind * 128 + (n0 & 127)) * 1024 + k0; ci.ldk = 1024;
;     } else { const int e = r >> 9, kt = (r >> 4) & 31, ntile = r & 15; const int n0 = ntile * 64, k0 = kt * 64;
;         ci.src = p.in[IN_WD] + (size_t)l * NE * DE * D + (size_t)e * DE * D + (size_t)k0 * D + n0; ci.N = D;
;         ci.dst = W2 + ((size_t)e * 1024 + n0) * 2048 + k0; ci.ldk = 2048; }
.LBB0_1294:
	v_mad_i64_i32 v[6:7], s[38:39], s22, v134, 0
	v_mad_i64_i32 v[10:11], s[38:39], s22, v182, 0
	v_lshl_add_u64 v[6:7], v[6:7], 2, v[4:5]
	v_lshlrev_b32_e32 v8, 2, v138
	v_mov_b32_e32 v9, v145
	v_lshl_add_u64 v[10:11], v[10:11], 2, v[4:5]
	v_lshl_add_u64 v[6:7], v[6:7], 0, v[8:9]
	v_lshl_add_u64 v[10:11], v[10:11], 0, v[8:9]
	global_load_dwordx4 v[60:63], v[6:7], off nt
	global_load_dwordx4 v[64:67], v[10:11], off nt
	v_mad_i64_i32 v[6:7], s[38:39], s22, v180, 0
	v_mad_i64_i32 v[10:11], s[38:39], s22, v178, 0
	v_lshl_add_u64 v[6:7], v[6:7], 2, v[4:5]
	v_lshl_add_u64 v[10:11], v[10:11], 2, v[4:5]
	v_lshl_add_u64 v[6:7], v[6:7], 0, v[8:9]
	v_lshl_add_u64 v[10:11], v[10:11], 0, v[8:9]
	global_load_dwordx4 v[52:55], v[6:7], off nt
	global_load_dwordx4 v[56:59], v[10:11], off nt
	v_mad_i64_i32 v[6:7], s[38:39], s22, v176, 0
	v_mad_i64_i32 v[10:11], s[38:39], s22, v174, 0
	v_lshl_add_u64 v[6:7], v[6:7], 2, v[4:5]
	v_lshl_add_u64 v[10:11], v[10:11], 2, v[4:5]
	v_lshl_add_u64 v[6:7], v[6:7], 0, v[8:9]
	v_lshl_add_u64 v[10:11], v[10:11], 0, v[8:9]
	global_load_dwordx4 v[44:47], v[6:7], off nt
	global_load_dwordx4 v[48:51], v[10:11], off nt
	v_mad_i64_i32 v[6:7], s[38:39], s22, v172, 0
	v_mad_i64_i32 v[10:11], s[38:39], s22, v170, 0
	v_lshl_add_u64 v[6:7], v[6:7], 2, v[4:5]
	v_lshl_add_u64 v[10:11], v[10:11], 2, v[4:5]
	v_lshl_add_u64 v[6:7], v[6:7], 0, v[8:9]
	v_lshl_add_u64 v[10:11], v[10:11], 0, v[8:9]
	global_load_dwordx4 v[36:39], v[6:7], off nt
	global_load_dwordx4 v[40:43], v[10:11], off nt
	v_mad_i64_i32 v[6:7], s[38:39], s22, v168, 0
	v_mad_i64_i32 v[10:11], s[38:39], s22, v166, 0
	v_lshl_add_u64 v[6:7], v[6:7], 2, v[4:5]
	v_lshl_add_u64 v[10:11], v[10:11], 2, v[4:5]
	v_lshl_add_u64 v[6:7], v[6:7], 0, v[8:9]
	v_lshl_add_u64 v[10:11], v[10:11], 0, v[8:9]
	global_load_dwordx4 v[28:31], v[6:7], off nt
	global_load_dwordx4 v[32:35], v[10:11], off nt
	v_mad_i64_i32 v[6:7], s[38:39], s22, v164, 0
	v_mad_i64_i32 v[10:11], s[38:39], s22, v162, 0
	v_lshl_add_u64 v[6:7], v[6:7], 2, v[4:5]
	v_lshl_add_u64 v[10:11], v[10:11], 2, v[4:5]
	v_lshl_add_u64 v[6:7], v[6:7], 0, v[8:9]
	v_lshl_add_u64 v[10:11], v[10:11], 0, v[8:9]
	global_load_dwordx4 v[20:23], v[6:7], off nt
	global_load_dwordx4 v[24:27], v[10:11], off nt
	v_mad_i64_i32 v[6:7], s[38:39], s22, v156, 0
	v_mad_i64_i32 v[10:11], s[38:39], s22, v142, 0
	v_lshl_add_u64 v[6:7], v[6:7], 2, v[4:5]
	v_lshl_add_u64 v[10:11], v[10:11], 2, v[4:5]
	v_lshl_add_u64 v[6:7], v[6:7], 0, v[8:9]
	v_lshl_add_u64 v[10:11], v[10:11], 0, v[8:9]
	global_load_dwordx4 v[12:15], v[6:7], off nt
	global_load_dwordx4 v[16:19], v[10:11], off nt
	v_mad_i64_i32 v[6:7], s[38:39], s22, v140, 0
	v_mad_i64_i32 v[10:11], s[22:23], s22, v136, 0
	v_lshl_add_u64 v[6:7], v[6:7], 2, v[4:5]
	v_lshl_add_u64 v[4:5], v[10:11], 2, v[4:5]
	v_lshl_add_u64 v[6:7], v[6:7], 0, v[8:9]
	v_lshl_add_u64 v[8:9], v[4:5], 0, v[8:9]
	global_load_dwordx4 v[4:7], v[6:7], off nt
	s_nop 0
	global_load_dwordx4 v[8:11], v[8:9], off nt
; #define GAS __attribute__((address_space(1)))
; #define LAS __attribute__((address_space(3)))
; #define LDS_WAIT() asm volatile("s_waitcnt lgkmcnt(0)" ::: "memory")
; __device__ __forceinline__ unsigned pk2(float lo, float hi) { const f32x2_t v = {lo, hi}; return __builtin_bit_cast(unsigned, __builtin_convertvector(v, bf16x2_t)); }
; __device__ __forceinline__ void cvt_store(const CvtItem& it, const f32x4 (&v)[16], LAS float* scr, int lane) {
;     const int kr = lane >> 4, nc = (lane & 15) * 4;
; #pragma unroll
;     for (int i = 0; i < 16; ++i) { LAS float* p = scr + (4 * i + kr) * 65 + nc; p[0] = v[i].x; p[1] = v[i].y; p[2] = v[i].z; p[3] = v[i].w; }
;     LDS_WAIT(); asm volatile("" ::: "memory");
;     const int c = lane & 7;
; #pragma unroll
;     for (int j = 0; j < 8; ++j) { const int n = (lane >> 3) + 8 * j; const LAS float* s = scr + (8 * c) * 65 + n;
;         v4u o; o.x = pk2(s[0 * 65], s[1 * 65]); o.y = pk2(s[2 * 65], s[3 * 65]); o.z = pk2(s[4 * 65], s[5 * 65]); o.w = pk2(s[6 * 65], s[7 * 65]);
;         __builtin_nontemporal_store(o, (GAS v4u*)(it.dst + (size_t)n * it.ldk + 8 * c)); }
;     LDS_WAIT(); asm volatile("" ::: "memory");
; }
; __device__ __forceinline__ void cvt_moe_layer(const Params& p, Frame& F, int l, int w0, int nw, int iend) {
;     ...
;         if (hb) cvt_store(cb, vb, scr, F.lane);
.LBB0_1295:
	s_andn2_b64 vcc, exec, s[18:19]
	s_cbranch_vccnz .LBB0_1280
	ds_write2_b32 v169, v68, v69 offset1:1
	ds_write2_b32 v169, v70, v71 offset0:2 offset1:3
	ds_write2_b32 v173, v72, v73 offset1:1
	ds_write2_b32 v175, v74, v75 offset1:1
	ds_write2_b32 v177, v76, v77 offset1:1
	ds_write2_b32 v189, v78, v79 offset1:1
	ds_write2_b32 v191, v80, v81 offset1:1
	ds_write2_b32 v193, v82, v83 offset1:1
	ds_write2_b32 v195, v84, v85 offset1:1
	ds_write2_b32 v197, v86, v87 offset1:1
	ds_write2_b32 v199, v88, v89 offset1:1
	ds_write2_b32 v201, v90, v91 offset1:1
	ds_write2_b32 v204, v92, v93 offset1:1
	ds_write2_b32 v205, v94, v95 offset1:1
	ds_write2_b32 v206, v96, v97 offset1:1
	ds_write2_b32 v207, v98, v99 offset1:1
	ds_write2_b32 v208, v100, v101 offset1:1
	ds_write2_b32 v209, v102, v103 offset1:1
	ds_write2_b32 v210, v104, v105 offset1:1
	ds_write2_b32 v211, v106, v107 offset1:1
	ds_write2_b32 v212, v108, v109 offset1:1
	ds_write2_b32 v213, v110, v111 offset1:1
	ds_write2_b32 v214, v112, v113 offset1:1
	ds_write2_b32 v215, v114, v115 offset1:1
	ds_write2_b32 v216, v116, v117 offset1:1
	ds_write2_b32 v217, v118, v119 offset1:1
	ds_write2_b32 v218, v120, v121 offset1:1
	ds_write2_b32 v219, v122, v123 offset1:1
	ds_write2_b32 v220, v124, v125 offset1:1
	ds_write2_b32 v221, v126, v127 offset1:1
	ds_write2_b32 v222, v128, v129 offset1:1
	ds_write2_b32 v223, v130, v131 offset1:1
	s_waitcnt lgkmcnt(0)
	ds_read2_b32 v[152:153], v167 offset0:65 offset1:73
	ds_read2_b32 v[154:155], v167 offset1:8
	ds_read2_b32 v[158:159], v167 offset0:130 offset1:138
	ds_read2_b32 v[160:161], v167 offset0:195 offset1:203
	ds_read2_b32 v[202:203], v171 offset0:4 offset1:12
	ds_read2_b32 v[204:205], v171 offset0:69 offset1:77
	ds_read2_b32 v[206:207], v171 offset0:134 offset1:142
	ds_read2_b32 v[208:209], v171 offset0:199 offset1:207
	v_mad_u64_u32 v[212:213], s[18:19], s25, v184, 0
	v_lshl_add_u64 v[210:211], s[14:15], 0, v[144:145]
	v_mov_b32_e32 v144, v213
	v_mad_u64_u32 v[214:215], s[18:19], s25, v135, v[144:145]
	v_mov_b32_e32 v213, v214
	s_waitcnt lgkmcnt(6)
	v_cvt_pk_bf16_f32 v148, v154, v152
	s_waitcnt lgkmcnt(4)
	v_cvt_pk_bf16_f32 v149, v158, v160
	s_waitcnt lgkmcnt(2)
	v_cvt_pk_bf16_f32 v150, v202, v204
	s_waitcnt lgkmcnt(0)
	v_cvt_pk_bf16_f32 v151, v206, v208
	v_lshl_add_u64 v[212:213], v[212:213], 1, v[210:211]
	global_store_dwordx4 v[212:213], v[148:151], off nt
	s_nop 1
	v_cvt_pk_bf16_f32 v148, v155, v153
	v_mad_u64_u32 v[152:153], s[18:19], s25, v188, 0
	v_mov_b32_e32 v144, v153
	v_mad_u64_u32 v[154:155], s[18:19], s25, v137, v[144:145]
	v_mov_b32_e32 v153, v154
	v_cvt_pk_bf16_f32 v149, v159, v161
	v_cvt_pk_bf16_f32 v150, v203, v205
	v_cvt_pk_bf16_f32 v151, v207, v209
	v_lshl_add_u64 v[152:153], v[152:153], 1, v[210:211]
	ds_read2_b32 v[154:155], v167 offset0:16 offset1:24
	ds_read2_b32 v[158:159], v167 offset0:81 offset1:89
	ds_read2_b32 v[160:161], v167 offset0:146 offset1:154
	ds_read2_b32 v[202:203], v167 offset0:211 offset1:219
	ds_read2_b32 v[204:205], v171 offset0:20 offset1:28
	ds_read2_b32 v[206:207], v171 offset0:85 offset1:93
	ds_read2_b32 v[208:209], v171 offset0:150 offset1:158
	ds_read2_b32 v[212:213], v171 offset0:215 offset1:223
	global_store_dwordx4 v[152:153], v[148:151], off nt
	v_mad_u64_u32 v[152:153], s[18:19], s25, v190, 0
	v_mov_b32_e32 v144, v153
	v_mad_u64_u32 v[214:215], s[18:19], s25, v139, v[144:145]
	v_mov_b32_e32 v153, v214
	s_waitcnt lgkmcnt(6)
	v_cvt_pk_bf16_f32 v148, v154, v158
	s_waitcnt lgkmcnt(4)
	v_cvt_pk_bf16_f32 v149, v160, v202
	s_waitcnt lgkmcnt(2)
	v_cvt_pk_bf16_f32 v150, v204, v206
	s_waitcnt lgkmcnt(0)
	v_cvt_pk_bf16_f32 v151, v208, v212
	v_lshl_add_u64 v[152:153], v[152:153], 1, v[210:211]
	global_store_dwordx4 v[152:153], v[148:151], off nt
	v_mad_u64_u32 v[152:153], s[18:19], s25, v192, 0
	v_mov_b32_e32 v144, v153
	v_cvt_pk_bf16_f32 v148, v155, v159
	v_mad_u64_u32 v[154:155], s[18:19], s25, v141, v[144:145]
	v_mov_b32_e32 v153, v154
	v_cvt_pk_bf16_f32 v149, v161, v203
	v_cvt_pk_bf16_f32 v150, v205, v207
	v_cvt_pk_bf16_f32 v151, v209, v213
	v_lshl_add_u64 v[152:153], v[152:153], 1, v[210:211]
	ds_read2_b32 v[154:155], v167 offset0:32 offset1:40
	ds_read2_b32 v[158:159], v167 offset0:97 offset1:105
	ds_read2_b32 v[160:161], v167 offset0:162 offset1:170
	ds_read2_b32 v[202:203], v167 offset0:227 offset1:235
	ds_read2_b32 v[204:205], v171 offset0:36 offset1:44
	ds_read2_b32 v[206:207], v171 offset0:101 offset1:109
	ds_read2_b32 v[208:209], v171 offset0:166 offset1:174
	ds_read2_b32 v[212:213], v171 offset0:231 offset1:239
	global_store_dwordx4 v[152:153], v[148:151], off nt
	v_mad_u64_u32 v[152:153], s[18:19], s25, v194, 0
	v_mov_b32_e32 v144, v153
	v_mad_u64_u32 v[214:215], s[18:19], s25, v143, v[144:145]
	v_mov_b32_e32 v153, v214
	s_waitcnt lgkmcnt(6)
	v_cvt_pk_bf16_f32 v148, v154, v158
	s_waitcnt lgkmcnt(4)
	v_cvt_pk_bf16_f32 v149, v160, v202
	s_waitcnt lgkmcnt(2)
	v_cvt_pk_bf16_f32 v150, v204, v206
	s_waitcnt lgkmcnt(0)
	v_cvt_pk_bf16_f32 v151, v208, v212
	v_lshl_add_u64 v[152:153], v[152:153], 1, v[210:211]
	global_store_dwordx4 v[152:153], v[148:151], off nt
	v_mad_u64_u32 v[152:153], s[18:19], s25, v196, 0
	v_mov_b32_e32 v144, v153
	v_cvt_pk_bf16_f32 v148, v155, v159
	v_mad_u64_u32 v[154:155], s[18:19], s25, v147, v[144:145]
	v_mov_b32_e32 v153, v154
	v_cvt_pk_bf16_f32 v149, v161, v203
	v_cvt_pk_bf16_f32 v150, v205, v207
	v_cvt_pk_bf16_f32 v151, v209, v213
	v_lshl_add_u64 v[152:153], v[152:153], 1, v[210:211]
	ds_read2_b32 v[154:155], v167 offset0:48 offset1:56
	ds_read2_b32 v[158:159], v167 offset0:113 offset1:121
	ds_read2_b32 v[160:161], v167 offset0:178 offset1:186
	ds_read2_b32 v[202:203], v167 offset0:243 offset1:251
	ds_read2_b32 v[204:205], v171 offset0:52 offset1:60
	ds_read2_b32 v[206:207], v171 offset0:117 offset1:125
	ds_read2_b32 v[208:209], v171 offset0:182 offset1:190
	ds_read2_b32 v[212:213], v171 offset0:247 offset1:255
	global_store_dwordx4 v[152:153], v[148:151], off nt
	v_mad_u64_u32 v[152:153], s[18:19], s25, v198, 0
	v_mov_b32_e32 v144, v153
	v_mad_u64_u32 v[214:215], s[18:19], s25, v163, v[144:145]
	v_mov_b32_e32 v153, v214
	s_waitcnt lgkmcnt(6)
	v_cvt_pk_bf16_f32 v148, v154, v158
	s_waitcnt lgkmcnt(4)
	v_cvt_pk_bf16_f32 v149, v160, v202
	s_waitcnt lgkmcnt(2)
	v_cvt_pk_bf16_f32 v150, v204, v206
	s_waitcnt lgkmcnt(0)
	v_cvt_pk_bf16_f32 v151, v208, v212
	v_lshl_add_u64 v[152:153], v[152:153], 1, v[210:211]
	global_store_dwordx4 v[152:153], v[148:151], off nt
	v_mad_u64_u32 v[152:153], s[18:19], s25, v200, 0
	v_mov_b32_e32 v144, v153
	v_cvt_pk_bf16_f32 v148, v155, v159
	v_mad_u64_u32 v[154:155], s[18:19], s25, v165, v[144:145]
	v_mov_b32_e32 v153, v154
	v_cvt_pk_bf16_f32 v149, v161, v203
	v_cvt_pk_bf16_f32 v150, v205, v207
	v_cvt_pk_bf16_f32 v151, v209, v213
	v_lshl_add_u64 v[152:153], v[152:153], 1, v[210:211]
	global_store_dwordx4 v[152:153], v[148:151], off nt
	s_waitcnt lgkmcnt(0)
	s_branch .LBB0_1280

; __device__ __forceinline__ unsigned cvt_pk_bf16(float lo, float hi) { unsigned r; asm volatile("v_cvt_pk_bf16_f32 %0, %1, %2" : "=v"(r) : "v"(lo), "v"(hi)); return r; }
; #define PG8_GAS __attribute__((address_space(1)))
;     __device__ __forceinline__ void operator()(const f32x4 (&acc)[2][2][4][2], const Unit& u, int wr, int wc, int fr, int fq) const {
;         const int row0 = u.pm * BM + wr * 64 + fr, col0 = coff + u.pn * BM + wc * 32 + 8 * fq;
; #pragma unroll
;         for (int ai = 0; ai < 2; ++ai)
; #pragma unroll
;             for (int m = 0; m < 4; ++m) { const int row = row0 + ai * HALF + m * 16; bf16_t* rowp = O + (size_t)row * ldc + col0; const float s = rs ? *(const PG8_GAS float*)(rs + row) : scale;
; #pragma unroll
;                 for (int bj = 0; bj < 2; ++bj) { const f32x4 v0 = acc[ai][bj][m][0] * s, v1 = acc[ai][bj][m][1] * s;
;                     u32x4 w; w.x = cvt_pk_bf16(v0[0], v0[1]); w.y = cvt_pk_bf16(v0[2], v0[3]); w.z = cvt_pk_bf16(v1[0], v1[1]); w.w = cvt_pk_bf16(v1[2], v1[3]);
;                     *(PG8_GAS u32x4*)(rowp + bj * HALF) = w; } }
.LBB0_1369:
	s_lshl_b32 s9, s43, 8
	v_mbcnt_lo_u32_b32 v138, -1, 0
	v_mbcnt_hi_u32_b32 v138, -1, v138
	s_add_i32 s9, s9, s36
	v_and_or_b32 v142, v138, 15, s9
	s_lshl_b32 s9, s42, 8
	v_ashrrev_i32_e32 v138, 1, v138
	v_and_b32_e32 v138, -8, v138
	s_or_b32 s9, s9, s37
	v_add_u32_e32 v138, s9, v138
	v_ashrrev_i32_e32 v143, 31, v142
	v_ashrrev_i32_e32 v139, 31, v138
	v_lshlrev_b64 v[140:141], 11, v[142:143]
	v_lshl_add_u64 v[140:141], s[2:3], 0, v[140:141]
	v_lshlrev_b64 v[162:163], 1, v[138:139]
	v_lshl_add_u64 v[138:139], v[140:141], 0, v[162:163]
	v_lshl_add_u64 v[140:141], v[142:143], 2, s[4:5]
	global_load_dword v180, v[140:141], off
	global_load_dword v182, v[140:141], off offset:64
	global_load_dword v184, v[140:141], off offset:128
	global_load_dword v186, v[140:141], off offset:192
	global_load_dword v188, v[140:141], off offset:512
	global_load_dword v190, v[140:141], off offset:576
	global_load_dword v192, v[140:141], off offset:640
	global_load_dword v194, v[140:141], off offset:704
	s_mov_b32 s9, 0x40000
	s_mov_b64 s[16:17], 0x40000
	s_waitcnt vmcnt(0)
	v_pk_mul_f32 v[126:127], v[126:127], v[180:181] op_sel_hi:[1,0]
	v_pk_mul_f32 v[124:125], v[124:125], v[180:181] op_sel_hi:[1,0]
	v_pk_mul_f32 v[148:149], v[122:123], v[180:181] op_sel_hi:[1,0]
	v_pk_mul_f32 v[122:123], v[120:121], v[180:181] op_sel_hi:[1,0]
	v_cvt_pk_bf16_f32 v120, v124, v125
	v_cvt_pk_bf16_f32 v121, v126, v127
	v_pk_mul_f32 v[116:117], v[116:117], v[180:181] op_sel_hi:[1,0]
	v_cvt_pk_bf16_f32 v122, v122, v123
	v_cvt_pk_bf16_f32 v123, v148, v149
	global_store_dwordx4 v[138:139], v[120:123], off
	v_pk_mul_f32 v[118:119], v[118:119], v[180:181] op_sel_hi:[1,0]
	s_nop 0
	v_pk_mul_f32 v[120:121], v[114:115], v[180:181] op_sel_hi:[1,0]
	v_pk_mul_f32 v[114:115], v[112:113], v[180:181] op_sel_hi:[1,0]
	v_cvt_pk_bf16_f32 v112, v116, v117
	v_cvt_pk_bf16_f32 v113, v118, v119
	s_nop 0
	v_cvt_pk_bf16_f32 v114, v114, v115
	v_cvt_pk_bf16_f32 v115, v120, v121
	global_store_dwordx4 v[138:139], v[112:115], off offset:256
	s_nop 1
	v_or_b32_e32 v112, 16, v142
	v_ashrrev_i32_e32 v113, 31, v112
	v_lshlrev_b64 v[114:115], 11, v[112:113]
	v_lshl_add_u64 v[114:115], s[2:3], 0, v[114:115]
	v_lshl_add_u64 v[114:115], v[114:115], 0, v[162:163]
	v_pk_mul_f32 v[110:111], v[110:111], v[182:183] op_sel_hi:[1,0]
	v_pk_mul_f32 v[108:109], v[108:109], v[182:183] op_sel_hi:[1,0]
	v_pk_mul_f32 v[116:117], v[106:107], v[182:183] op_sel_hi:[1,0]
	v_pk_mul_f32 v[106:107], v[104:105], v[182:183] op_sel_hi:[1,0]
	v_cvt_pk_bf16_f32 v104, v108, v109
	v_cvt_pk_bf16_f32 v105, v110, v111
	v_pk_mul_f32 v[100:101], v[100:101], v[182:183] op_sel_hi:[1,0]
	v_cvt_pk_bf16_f32 v106, v106, v107
	v_cvt_pk_bf16_f32 v107, v116, v117
	global_store_dwordx4 v[114:115], v[104:107], off
	v_pk_mul_f32 v[102:103], v[102:103], v[182:183] op_sel_hi:[1,0]
	s_nop 0
	v_pk_mul_f32 v[104:105], v[98:99], v[182:183] op_sel_hi:[1,0]
	v_pk_mul_f32 v[98:99], v[96:97], v[182:183] op_sel_hi:[1,0]
	v_cvt_pk_bf16_f32 v96, v100, v101
	v_cvt_pk_bf16_f32 v97, v102, v103
	s_nop 0
	v_cvt_pk_bf16_f32 v98, v98, v99
	v_cvt_pk_bf16_f32 v99, v104, v105
	global_store_dwordx4 v[114:115], v[96:99], off offset:256
	s_nop 1
	v_or_b32_e32 v96, 32, v142
	v_ashrrev_i32_e32 v97, 31, v96
	v_lshlrev_b64 v[98:99], 11, v[96:97]
	v_lshl_add_u64 v[98:99], s[2:3], 0, v[98:99]
	v_lshl_add_u64 v[98:99], v[98:99], 0, v[162:163]
	v_pk_mul_f32 v[94:95], v[94:95], v[184:185] op_sel_hi:[1,0]
	v_pk_mul_f32 v[92:93], v[92:93], v[184:185] op_sel_hi:[1,0]
	v_pk_mul_f32 v[100:101], v[90:91], v[184:185] op_sel_hi:[1,0]
	v_pk_mul_f32 v[90:91], v[88:89], v[184:185] op_sel_hi:[1,0]
	v_cvt_pk_bf16_f32 v88, v92, v93
	v_cvt_pk_bf16_f32 v89, v94, v95
	v_pk_mul_f32 v[84:85], v[84:85], v[184:185] op_sel_hi:[1,0]
	v_cvt_pk_bf16_f32 v90, v90, v91
	v_cvt_pk_bf16_f32 v91, v100, v101
	global_store_dwordx4 v[98:99], v[88:91], off
	v_pk_mul_f32 v[86:87], v[86:87], v[184:185] op_sel_hi:[1,0]
	s_nop 0
	v_pk_mul_f32 v[88:89], v[82:83], v[184:185] op_sel_hi:[1,0]
	v_pk_mul_f32 v[82:83], v[80:81], v[184:185] op_sel_hi:[1,0]
	v_cvt_pk_bf16_f32 v80, v84, v85
	v_cvt_pk_bf16_f32 v81, v86, v87
	s_nop 0
	v_cvt_pk_bf16_f32 v82, v82, v83
	v_cvt_pk_bf16_f32 v83, v88, v89
	global_store_dwordx4 v[98:99], v[80:83], off offset:256
	s_nop 1
	v_or_b32_e32 v80, 48, v142
	v_ashrrev_i32_e32 v81, 31, v80
	v_lshlrev_b64 v[82:83], 11, v[80:81]
	v_lshl_add_u64 v[82:83], s[2:3], 0, v[82:83]
	v_lshl_add_u64 v[82:83], v[82:83], 0, v[162:163]
	v_pk_mul_f32 v[78:79], v[78:79], v[186:187] op_sel_hi:[1,0]
	v_pk_mul_f32 v[76:77], v[76:77], v[186:187] op_sel_hi:[1,0]
	v_pk_mul_f32 v[84:85], v[74:75], v[186:187] op_sel_hi:[1,0]
	v_pk_mul_f32 v[74:75], v[72:73], v[186:187] op_sel_hi:[1,0]
	v_cvt_pk_bf16_f32 v72, v76, v77
	v_cvt_pk_bf16_f32 v73, v78, v79
	v_pk_mul_f32 v[70:71], v[70:71], v[186:187] op_sel_hi:[1,0]
; __device__ __forceinline__ unsigned cvt_pk_bf16(float lo, float hi) { unsigned r; asm volatile("v_cvt_pk_bf16_f32 %0, %1, %2" : "=v"(r) : "v"(lo), "v"(hi)); return r; }
; #define PG8_GAS __attribute__((address_space(1)))
;     __device__ __forceinline__ void operator()(const f32x4 (&acc)[2][2][4][2], const Unit& u, int wr, int wc, int fr, int fq) const {
;     ...
;             for (int m = 0; m < 4; ++m) { const int row = row0 + ai * HALF + m * 16; bf16_t* rowp = O + (size_t)row * ldc + col0; const float s = rs ? *(const PG8_GAS float*)(rs + row) : scale;
; #pragma unroll
;                 for (int bj = 0; bj < 2; ++bj) { const f32x4 v0 = acc[ai][bj][m][0] * s, v1 = acc[ai][bj][m][1] * s;
;                     u32x4 w; w.x = cvt_pk_bf16(v0[0], v0[1]); w.y = cvt_pk_bf16(v0[2], v0[3]); w.z = cvt_pk_bf16(v1[0], v1[1]); w.w = cvt_pk_bf16(v1[2], v1[3]);
;                     *(PG8_GAS u32x4*)(rowp + bj * HALF) = w; } }
	v_cvt_pk_bf16_f32 v74, v74, v75
	v_cvt_pk_bf16_f32 v75, v84, v85
	global_store_dwordx4 v[82:83], v[72:75], off
	v_pk_mul_f32 v[68:69], v[68:69], v[186:187] op_sel_hi:[1,0]
	s_nop 0
	v_pk_mul_f32 v[72:73], v[66:67], v[186:187] op_sel_hi:[1,0]
	v_pk_mul_f32 v[66:67], v[64:65], v[186:187] op_sel_hi:[1,0]
	v_cvt_pk_bf16_f32 v64, v68, v69
	v_cvt_pk_bf16_f32 v65, v70, v71
	s_nop 0
	v_cvt_pk_bf16_f32 v66, v66, v67
	v_cvt_pk_bf16_f32 v67, v72, v73
	global_store_dwordx4 v[82:83], v[64:67], off offset:256
	v_pk_mul_f32 v[60:61], v[60:61], v[188:189] op_sel_hi:[1,0]
	v_pk_mul_f32 v[68:69], v[58:59], v[188:189] op_sel_hi:[1,0]
	v_pk_mul_f32 v[58:59], v[56:57], v[188:189] op_sel_hi:[1,0]
	v_cvt_pk_bf16_f32 v56, v60, v61
	v_add_co_u32_e32 v60, vcc, s9, v138
	v_pk_mul_f32 v[62:63], v[62:63], v[188:189] op_sel_hi:[1,0]
	s_nop 0
	v_addc_co_u32_e32 v61, vcc, 0, v139, vcc
	v_cvt_pk_bf16_f32 v57, v62, v63
	v_lshl_add_u64 v[64:65], v[138:139], 0, s[16:17]
	v_cvt_pk_bf16_f32 v58, v58, v59
	v_cvt_pk_bf16_f32 v59, v68, v69
	global_store_dwordx4 v[60:61], v[56:59], off
	v_pk_mul_f32 v[54:55], v[54:55], v[188:189] op_sel_hi:[1,0]
	v_pk_mul_f32 v[52:53], v[52:53], v[188:189] op_sel_hi:[1,0]
	v_pk_mul_f32 v[56:57], v[50:51], v[188:189] op_sel_hi:[1,0]
	v_pk_mul_f32 v[50:51], v[48:49], v[188:189] op_sel_hi:[1,0]
	v_cvt_pk_bf16_f32 v48, v52, v53
	v_cvt_pk_bf16_f32 v49, v54, v55
	s_mov_b32 s9, 0x48000
	v_cvt_pk_bf16_f32 v50, v50, v51
	v_cvt_pk_bf16_f32 v51, v56, v57
	global_store_dwordx4 v[64:65], v[48:51], off offset:256
	s_mov_b64 s[16:17], 0x48000
	v_lshl_add_u64 v[48:49], v[138:139], 0, s[16:17]
	s_mov_b64 s[16:17], 0x50000
	v_pk_mul_f32 v[44:45], v[44:45], v[190:191] op_sel_hi:[1,0]
	v_pk_mul_f32 v[52:53], v[42:43], v[190:191] op_sel_hi:[1,0]
	v_pk_mul_f32 v[42:43], v[40:41], v[190:191] op_sel_hi:[1,0]
	v_cvt_pk_bf16_f32 v40, v44, v45
	v_add_co_u32_e32 v44, vcc, s9, v138
	v_pk_mul_f32 v[46:47], v[46:47], v[190:191] op_sel_hi:[1,0]
	s_nop 0
	v_addc_co_u32_e32 v45, vcc, 0, v139, vcc
	v_cvt_pk_bf16_f32 v41, v46, v47
	v_cvt_pk_bf16_f32 v42, v42, v43
	v_cvt_pk_bf16_f32 v43, v52, v53
	global_store_dwordx4 v[44:45], v[40:43], off
	v_pk_mul_f32 v[38:39], v[38:39], v[190:191] op_sel_hi:[1,0]
	v_pk_mul_f32 v[36:37], v[36:37], v[190:191] op_sel_hi:[1,0]
	v_pk_mul_f32 v[40:41], v[34:35], v[190:191] op_sel_hi:[1,0]
	v_pk_mul_f32 v[34:35], v[32:33], v[190:191] op_sel_hi:[1,0]
	v_cvt_pk_bf16_f32 v32, v36, v37
	v_cvt_pk_bf16_f32 v33, v38, v39
	s_mov_b32 s9, 0x50000
	v_cvt_pk_bf16_f32 v34, v34, v35
	v_cvt_pk_bf16_f32 v35, v40, v41
	global_store_dwordx4 v[48:49], v[32:35], off offset:256
	v_pk_mul_f32 v[28:29], v[28:29], v[192:193] op_sel_hi:[1,0]
	v_pk_mul_f32 v[36:37], v[26:27], v[192:193] op_sel_hi:[1,0]
	v_pk_mul_f32 v[26:27], v[24:25], v[192:193] op_sel_hi:[1,0]
	v_cvt_pk_bf16_f32 v24, v28, v29
	v_add_co_u32_e32 v28, vcc, s9, v138
	v_pk_mul_f32 v[30:31], v[30:31], v[192:193] op_sel_hi:[1,0]
	s_nop 0
	v_addc_co_u32_e32 v29, vcc, 0, v139, vcc
	v_cvt_pk_bf16_f32 v25, v30, v31
	v_lshl_add_u64 v[32:33], v[138:139], 0, s[16:17]
	v_cvt_pk_bf16_f32 v26, v26, v27
	v_cvt_pk_bf16_f32 v27, v36, v37
	global_store_dwordx4 v[28:29], v[24:27], off
	v_pk_mul_f32 v[22:23], v[22:23], v[192:193] op_sel_hi:[1,0]
	v_pk_mul_f32 v[20:21], v[20:21], v[192:193] op_sel_hi:[1,0]
	v_pk_mul_f32 v[24:25], v[18:19], v[192:193] op_sel_hi:[1,0]
	v_pk_mul_f32 v[18:19], v[16:17], v[192:193] op_sel_hi:[1,0]
	v_cvt_pk_bf16_f32 v16, v20, v21
	v_cvt_pk_bf16_f32 v17, v22, v23
	s_mov_b32 s9, 0x58000
	v_cvt_pk_bf16_f32 v18, v18, v19
	v_cvt_pk_bf16_f32 v19, v24, v25
	global_store_dwordx4 v[32:33], v[16:19], off offset:256
	s_mov_b64 s[16:17], 0x58000
	v_lshl_add_u64 v[18:19], v[138:139], 0, s[16:17]
	s_mov_b64 s[16:17], -1
	v_pk_mul_f32 v[12:13], v[12:13], v[194:195] op_sel_hi:[1,0]
	v_pk_mul_f32 v[20:21], v[10:11], v[194:195] op_sel_hi:[1,0]
	v_pk_mul_f32 v[10:11], v[8:9], v[194:195] op_sel_hi:[1,0]
	v_cvt_pk_bf16_f32 v8, v12, v13
	v_add_co_u32_e32 v12, vcc, s9, v138
	v_pk_mul_f32 v[14:15], v[14:15], v[194:195] op_sel_hi:[1,0]
	s_nop 0
	v_addc_co_u32_e32 v13, vcc, 0, v139, vcc
	v_cvt_pk_bf16_f32 v9, v14, v15
	v_cvt_pk_bf16_f32 v10, v10, v11
	v_cvt_pk_bf16_f32 v11, v20, v21
	global_store_dwordx4 v[12:13], v[8:11], off
	s_andn2_b64 vcc, exec, s[14:15]
	v_pk_mul_f32 v[6:7], v[6:7], v[194:195] op_sel_hi:[1,0]
	v_pk_mul_f32 v[8:9], v[2:3], v[194:195] op_sel_hi:[1,0]
	v_pk_mul_f32 v[2:3], v[0:1], v[194:195] op_sel_hi:[1,0]
	v_pk_mul_f32 v[4:5], v[4:5], v[194:195] op_sel_hi:[1,0]
	s_nop 0
	v_cvt_pk_bf16_f32 v0, v4, v5
	v_cvt_pk_bf16_f32 v1, v6, v7
	v_cvt_pk_bf16_f32 v2, v2, v3
	v_cvt_pk_bf16_f32 v3, v8, v9
	global_store_dwordx4 v[18:19], v[0:3], off offset:256
	s_cbranch_vccnz .LBB0_1361
	s_andn2_b64 vcc, exec, s[0:1]
	s_cbranch_vccnz .LBB0_1360
	s_barrier
	s_branch .LBB0_1360
